# s_sleep 1 before the vmcnt wait in the load segment of all GEMM main loops
# baseline (speedup 1.0000x reference)
; #define PG8_STAGE(bufoff, gbase, voff) do { _Pragma("unroll") for (int _i = 0; _i < 2; ++_i) \
;         __builtin_amdgcn_global_load_lds((const unsigned*)((const char*)(gbase) + (voff)[_i]), (PG8_LAS unsigned*)(lds + (bufoff) + ldsw + _i * 8192), 16, 0, 0); } while (0)
; #define PG8_LDA(dst, b, h) do { _Pragma("unroll") for (int m = 0; m < 4; ++m) _Pragma("unroll") for (int k = 0; k < 2; ++k) dst[m][k] = *(const PG8_LAS bf16x8*)(lds + PG8_SA(b, h) + aoff + m * 2048 + k * 1024); } while (0)
; #define PG8_LDB(dst, b, h) do { _Pragma("unroll") for (int n = 0; n < 2; ++n) _Pragma("unroll") for (int k = 0; k < 2; ++k) dst[n][k] = *(const PG8_LAS bf16x8*)(lds + PG8_SB(b, h) + boff + n * 2048 + k * 1024); } while (0)
; #define PG8_MMA(ai, bj, At, Bt) do { __builtin_amdgcn_s_setprio(1); _Pragma("unroll") for (int m = 0; m < 4; ++m) _Pragma("unroll") for (int n = 0; n < 2; ++n) _Pragma("unroll") for (int k = 0; k < 2; ++k) \
;         acc[ai][bj][m][n] = __builtin_amdgcn_mfma_f32_16x16x32_bf16(Bt[n][k], At[m][k], acc[ai][bj][m][n], 0, 0, 0); __builtin_amdgcn_s_setprio(0); } while (0)
; #define PG8_WAIT_V(n) asm volatile("s_waitcnt vmcnt(" #n ")" ::: "memory")
; #define PG8_BAR __builtin_amdgcn_s_barrier()
; template <class Epi, class Sched, bool ALIGN_EPI = false, bool SP2 = false>
; __device__ __forceinline__ void gemm_phase(PG8_LAS unsigned char* lds, const Gemm g, const Sched& S, const Epi& E) {
;     ...
;         for (int t = 0; t < nt; t += 2) {
;             const bool last = (t == nt - 2);
;             const char* a1 = cA + (size_t)(t + 1) * kstep;
;             const char* a2 = last ? nA : cA + (size_t)(t + 2) * kstep; const char* b2 = last ? nB : cB + (size_t)(t + 2) * kstep;
;             const char* a3 = a2 + kstep; const char* b3 = b2 + kstep;
;             if (last && has_next) S.a_ready(nxt);
;             if constexpr (SP2) {
;             PG8_LDB(B0, 0, 0); PG8_LDB(B1, 0, 1); PG8_SCHED; PG8_LDA(At, 0, 0); PG8_STAGE(PG8_SA(1, 1), a1 + hstep, voffA);
;             PG8_WAIT_V(8); PG8_WAIT_L(0); PG8_BAR; PG8_MMA(0, 0, At, B0); PG8_MMA(0, 1, At, B1); PG8_BAR; PG8_SCHED;
;             PG8_LDA(At, 0, 1); PG8_STAGE(PG8_SB(0, 0), b2, voffB); PG8_STAGE(PG8_SB(0, 1), b2 + hstep, voffB); PG8_STAGE(PG8_SA(0, 0), a2, voffA);
;             PG8_WAIT_V(8); PG8_WAIT_L(0); PG8_BAR; PG8_MMA(1, 0, At, B0); PG8_MMA(1, 1, At, B1); PG8_BAR; PG8_SCHED;
.LBB0_244:
	ds_read_b128 v[150:153], v147
	ds_read_b128 v[154:157], v147 offset:1024
	ds_read_b128 v[158:161], v147 offset:2048
	ds_read_b128 v[162:165], v147 offset:3072
	ds_read_b128 v[166:169], v148
	ds_read_b128 v[170:173], v148 offset:1024
	ds_read_b128 v[174:177], v148 offset:2048
	ds_read_b128 v[178:181], v148 offset:3072
	s_add_u32 s22, s20, 0xfffc0080
	s_addc_u32 s23, s21, -1
	s_cmp_eq_u32 s51, 12
	s_cselect_b32 s25, s13, s23
	s_cselect_b32 s24, s43, s22
	s_cselect_b32 s23, s11, s50
	s_cselect_b32 s22, s48, s49
	v_lshl_add_u64 v[216:217], s[20:21], 0, v[136:137]
	s_add_i32 m0, s19, 0xc000
	ds_read_b128 v[182:185], v149
	ds_read_b128 v[186:189], v149 offset:1024
	ds_read_b128 v[190:193], v149 offset:2048
	ds_read_b128 v[194:197], v149 offset:3072
	ds_read_b128 v[200:203], v149 offset:4096
	ds_read_b128 v[204:207], v149 offset:5120
	ds_read_b128 v[208:211], v149 offset:6144
	ds_read_b128 v[212:215], v149 offset:7168
	global_load_lds_dwordx4 v[216:217], off
	v_lshl_add_u64 v[216:217], s[20:21], 0, v[138:139]
	s_add_i32 m0, s19, 0xe000
	s_nop 0
	global_load_lds_dwordx4 v[216:217], off
	s_sleep 1
	s_waitcnt vmcnt(8)
	s_waitcnt lgkmcnt(0)
	s_barrier
	s_setprio 1
	s_waitcnt lgkmcnt(0)
	v_mfma_f32_16x16x32_bf16 v[124:127], v[150:153], v[182:185], v[124:127]
	v_mfma_f32_16x16x32_bf16 v[116:119], v[158:161], v[182:185], v[116:119]
	v_mfma_f32_16x16x32_bf16 v[108:111], v[150:153], v[190:193], v[108:111]
	v_mfma_f32_16x16x32_bf16 v[100:103], v[158:161], v[190:193], v[100:103]
	v_mfma_f32_16x16x32_bf16 v[92:95], v[150:153], v[200:203], v[92:95]
	v_mfma_f32_16x16x32_bf16 v[84:87], v[158:161], v[200:203], v[84:87]
	v_mfma_f32_16x16x32_bf16 v[76:79], v[150:153], v[208:211], v[76:79]
	v_mfma_f32_16x16x32_bf16 v[68:71], v[158:161], v[208:211], v[68:71]
	v_mfma_f32_16x16x32_bf16 v[124:127], v[154:157], v[186:189], v[124:127]
	v_mfma_f32_16x16x32_bf16 v[116:119], v[162:165], v[186:189], v[116:119]
	v_mfma_f32_16x16x32_bf16 v[108:111], v[154:157], v[194:197], v[108:111]
	v_mfma_f32_16x16x32_bf16 v[100:103], v[162:165], v[194:197], v[100:103]
	v_mfma_f32_16x16x32_bf16 v[92:95], v[154:157], v[204:207], v[92:95]
	v_mfma_f32_16x16x32_bf16 v[84:87], v[162:165], v[204:207], v[84:87]
	v_mfma_f32_16x16x32_bf16 v[76:79], v[154:157], v[212:215], v[76:79]
	v_mfma_f32_16x16x32_bf16 v[68:71], v[162:165], v[212:215], v[68:71]
	s_setprio 0
	s_setprio 1
	v_mfma_f32_16x16x32_bf16 v[120:123], v[166:169], v[182:185], v[120:123]
	v_mfma_f32_16x16x32_bf16 v[112:115], v[174:177], v[182:185], v[112:115]
	v_mfma_f32_16x16x32_bf16 v[104:107], v[166:169], v[190:193], v[104:107]
	v_mfma_f32_16x16x32_bf16 v[96:99], v[174:177], v[190:193], v[96:99]
	v_mfma_f32_16x16x32_bf16 v[88:91], v[166:169], v[200:203], v[88:91]
	v_mfma_f32_16x16x32_bf16 v[80:83], v[174:177], v[200:203], v[80:83]
	v_mfma_f32_16x16x32_bf16 v[72:75], v[166:169], v[208:211], v[72:75]
	v_mfma_f32_16x16x32_bf16 v[64:67], v[174:177], v[208:211], v[64:67]
	v_mfma_f32_16x16x32_bf16 v[120:123], v[170:173], v[186:189], v[120:123]
	v_mfma_f32_16x16x32_bf16 v[112:115], v[178:181], v[186:189], v[112:115]
	v_mfma_f32_16x16x32_bf16 v[104:107], v[170:173], v[194:197], v[104:107]
	v_mfma_f32_16x16x32_bf16 v[96:99], v[178:181], v[194:197], v[96:99]
	v_mfma_f32_16x16x32_bf16 v[88:91], v[170:173], v[204:207], v[88:91]
	v_mfma_f32_16x16x32_bf16 v[80:83], v[178:181], v[204:207], v[80:83]
	v_mfma_f32_16x16x32_bf16 v[72:75], v[170:173], v[212:215], v[72:75]
	v_mfma_f32_16x16x32_bf16 v[64:67], v[178:181], v[212:215], v[64:67]
	s_setprio 0
	s_barrier
	s_add_i32 s52, s39, s26
	v_lshl_add_u64 v[216:217], s[22:23], 0, v[132:133]
	s_mov_b32 m0, s52
	ds_read_b128 v[182:185], v149 offset:16384
	ds_read_b128 v[186:189], v149 offset:17408
	ds_read_b128 v[190:193], v149 offset:18432
	ds_read_b128 v[194:197], v149 offset:19456
	ds_read_b128 v[200:203], v149 offset:20480
	ds_read_b128 v[204:207], v149 offset:21504
	ds_read_b128 v[208:211], v149 offset:22528
	ds_read_b128 v[212:215], v149 offset:23552
	global_load_lds_dwordx4 v[216:217], off
	s_add_i32 m0, s52, 0x2000
	s_add_u32 s52, s22, 0x40000
	v_lshl_add_u64 v[218:219], s[22:23], 0, v[128:129]
	s_addc_u32 s53, s23, 0
	s_add_i32 s54, s40, s26
	global_load_lds_dwordx4 v[218:219], off
	v_lshl_add_u64 v[220:221], s[52:53], 0, v[132:133]
	s_mov_b32 m0, s54
	v_lshl_add_u64 v[222:223], s[24:25], 0, v[130:131]
	global_load_lds_dwordx4 v[220:221], off
	v_lshl_add_u64 v[220:221], s[52:53], 0, v[128:129]
	s_add_i32 m0, s54, 0x2000
	s_nop 0
	global_load_lds_dwordx4 v[220:221], off
	v_lshl_add_u64 v[220:221], s[24:25], 0, v[134:135]
	s_mov_b32 m0, s19
	s_nop 0
	global_load_lds_dwordx4 v[220:221], off
	s_mov_b32 m0, s29
	s_nop 0
	global_load_lds_dwordx4 v[222:223], off
	s_sleep 1
	s_waitcnt vmcnt(8)
	s_waitcnt lgkmcnt(0)
	s_barrier
; #define PG8_STAGE(bufoff, gbase, voff) do { _Pragma("unroll") for (int _i = 0; _i < 2; ++_i) \
;         __builtin_amdgcn_global_load_lds((const unsigned*)((const char*)(gbase) + (voff)[_i]), (PG8_LAS unsigned*)(lds + (bufoff) + ldsw + _i * 8192), 16, 0, 0); } while (0)
; #define PG8_LDA(dst, b, h) do { _Pragma("unroll") for (int m = 0; m < 4; ++m) _Pragma("unroll") for (int k = 0; k < 2; ++k) dst[m][k] = *(const PG8_LAS bf16x8*)(lds + PG8_SA(b, h) + aoff + m * 2048 + k * 1024); } while (0)
; #define PG8_LDB(dst, b, h) do { _Pragma("unroll") for (int n = 0; n < 2; ++n) _Pragma("unroll") for (int k = 0; k < 2; ++k) dst[n][k] = *(const PG8_LAS bf16x8*)(lds + PG8_SB(b, h) + boff + n * 2048 + k * 1024); } while (0)
; #define PG8_MMA(ai, bj, At, Bt) do { __builtin_amdgcn_s_setprio(1); _Pragma("unroll") for (int m = 0; m < 4; ++m) _Pragma("unroll") for (int n = 0; n < 2; ++n) _Pragma("unroll") for (int k = 0; k < 2; ++k) \
;         acc[ai][bj][m][n] = __builtin_amdgcn_mfma_f32_16x16x32_bf16(Bt[n][k], At[m][k], acc[ai][bj][m][n], 0, 0, 0); __builtin_amdgcn_s_setprio(0); } while (0)
; #define PG8_WAIT_V(n) asm volatile("s_waitcnt vmcnt(" #n ")" ::: "memory")
; #define PG8_WAIT_L(n) asm volatile("s_waitcnt lgkmcnt(" #n ")" ::: "memory")
; #define PG8_BAR __builtin_amdgcn_s_barrier()
; #define PG8_SCHED __builtin_amdgcn_sched_barrier(0)
; template <class Epi, class Sched, bool ALIGN_EPI = false, bool SP2 = false>
; __device__ __forceinline__ void gemm_phase(PG8_LAS unsigned char* lds, const Gemm g, const Sched& S, const Epi& E) {
;     ...
;             PG8_WAIT_V(8); PG8_WAIT_L(0); PG8_BAR; PG8_MMA(1, 0, At, B0); PG8_MMA(1, 1, At, B1); PG8_BAR; PG8_SCHED;
;             PG8_LDB(B0, 1, 0); PG8_LDB(B1, 1, 1); PG8_SCHED; PG8_LDA(At, 1, 0); PG8_STAGE(PG8_SA(0, 1), a2 + hstep, voffA);
;             PG8_WAIT_V(8); PG8_WAIT_L(0); PG8_BAR; PG8_MMA(0, 0, At, B0); PG8_MMA(0, 1, At, B1); PG8_BAR; PG8_SCHED;
	s_setprio 1
	s_waitcnt lgkmcnt(0)
	v_mfma_f32_16x16x32_bf16 v[60:63], v[150:153], v[182:185], v[60:63]
	v_mfma_f32_16x16x32_bf16 v[52:55], v[158:161], v[182:185], v[52:55]
	v_mfma_f32_16x16x32_bf16 v[44:47], v[150:153], v[190:193], v[44:47]
	v_mfma_f32_16x16x32_bf16 v[36:39], v[158:161], v[190:193], v[36:39]
	v_mfma_f32_16x16x32_bf16 v[28:31], v[150:153], v[200:203], v[28:31]
	v_mfma_f32_16x16x32_bf16 v[20:23], v[158:161], v[200:203], v[20:23]
	v_mfma_f32_16x16x32_bf16 v[12:15], v[150:153], v[208:211], v[12:15]
	v_mfma_f32_16x16x32_bf16 v[4:7], v[158:161], v[208:211], v[4:7]
	v_mfma_f32_16x16x32_bf16 v[60:63], v[154:157], v[186:189], v[60:63]
	v_mfma_f32_16x16x32_bf16 v[52:55], v[162:165], v[186:189], v[52:55]
	v_mfma_f32_16x16x32_bf16 v[44:47], v[154:157], v[194:197], v[44:47]
	v_mfma_f32_16x16x32_bf16 v[36:39], v[162:165], v[194:197], v[36:39]
	v_mfma_f32_16x16x32_bf16 v[28:31], v[154:157], v[204:207], v[28:31]
	v_mfma_f32_16x16x32_bf16 v[20:23], v[162:165], v[204:207], v[20:23]
	v_mfma_f32_16x16x32_bf16 v[12:15], v[154:157], v[212:215], v[12:15]
	v_mfma_f32_16x16x32_bf16 v[4:7], v[162:165], v[212:215], v[4:7]
	s_setprio 0
	s_setprio 1
	v_mfma_f32_16x16x32_bf16 v[56:59], v[166:169], v[182:185], v[56:59]
	v_mfma_f32_16x16x32_bf16 v[48:51], v[174:177], v[182:185], v[48:51]
	v_mfma_f32_16x16x32_bf16 v[40:43], v[166:169], v[190:193], v[40:43]
	v_mfma_f32_16x16x32_bf16 v[32:35], v[174:177], v[190:193], v[32:35]
	v_mfma_f32_16x16x32_bf16 v[24:27], v[166:169], v[200:203], v[24:27]
	v_mfma_f32_16x16x32_bf16 v[16:19], v[174:177], v[200:203], v[16:19]
	v_mfma_f32_16x16x32_bf16 v[8:11], v[166:169], v[208:211], v[8:11]
	v_mfma_f32_16x16x32_bf16 v[0:3], v[174:177], v[208:211], v[0:3]
	v_mfma_f32_16x16x32_bf16 v[56:59], v[170:173], v[186:189], v[56:59]
	v_mfma_f32_16x16x32_bf16 v[48:51], v[178:181], v[186:189], v[48:51]
	v_mfma_f32_16x16x32_bf16 v[40:43], v[170:173], v[194:197], v[40:43]
	v_mfma_f32_16x16x32_bf16 v[32:35], v[178:181], v[194:197], v[32:35]
	v_mfma_f32_16x16x32_bf16 v[24:27], v[170:173], v[204:207], v[24:27]
	v_mfma_f32_16x16x32_bf16 v[16:19], v[178:181], v[204:207], v[16:19]
	v_mfma_f32_16x16x32_bf16 v[8:11], v[170:173], v[212:215], v[8:11]
	v_mfma_f32_16x16x32_bf16 v[0:3], v[178:181], v[212:215], v[0:3]
	s_setprio 0
	s_barrier
	s_add_i32 s52, 0, 0x18000
	s_add_i32 s53, 0, 0x1c000
	v_add_u32_e32 v162, s52, v145
	v_add_u32_e32 v178, s53, v145
	ds_read_b128 v[150:153], v162
	ds_read_b128 v[154:157], v162 offset:1024
	ds_read_b128 v[158:161], v162 offset:2048
	ds_read_b128 v[162:165], v162 offset:3072
	ds_read_b128 v[166:169], v178
	ds_read_b128 v[170:173], v178 offset:1024
	ds_read_b128 v[174:177], v178 offset:2048
	ds_read_b128 v[178:181], v178 offset:3072
	s_add_u32 s24, s24, 0x40000
	s_addc_u32 s25, s25, 0
	s_mov_b32 m0, s30
	v_lshl_add_u64 v[224:225], s[24:25], 0, v[134:135]
	ds_read_b128 v[182:185], v149 offset:32768
	ds_read_b128 v[186:189], v149 offset:33792
	ds_read_b128 v[190:193], v149 offset:34816
	ds_read_b128 v[194:197], v149 offset:35840
	ds_read_b128 v[200:203], v149 offset:36864
	ds_read_b128 v[204:207], v149 offset:37888
	ds_read_b128 v[208:211], v149 offset:38912
	ds_read_b128 v[212:215], v149 offset:39936
	global_load_lds_dwordx4 v[224:225], off
	v_lshl_add_u64 v[224:225], s[24:25], 0, v[130:131]
	s_mov_b32 m0, s31
	s_nop 0
	global_load_lds_dwordx4 v[224:225], off
	s_sleep 1
	s_waitcnt vmcnt(8)
	s_waitcnt lgkmcnt(0)
	s_barrier
	s_setprio 1
	s_waitcnt lgkmcnt(0)
	v_mfma_f32_16x16x32_bf16 v[124:127], v[150:153], v[182:185], v[124:127]
	v_mfma_f32_16x16x32_bf16 v[116:119], v[158:161], v[182:185], v[116:119]
	v_mfma_f32_16x16x32_bf16 v[108:111], v[150:153], v[190:193], v[108:111]
	v_mfma_f32_16x16x32_bf16 v[100:103], v[158:161], v[190:193], v[100:103]
	v_mfma_f32_16x16x32_bf16 v[92:95], v[150:153], v[200:203], v[92:95]
	v_mfma_f32_16x16x32_bf16 v[84:87], v[158:161], v[200:203], v[84:87]
	v_mfma_f32_16x16x32_bf16 v[76:79], v[150:153], v[208:211], v[76:79]
	v_mfma_f32_16x16x32_bf16 v[68:71], v[158:161], v[208:211], v[68:71]
	v_mfma_f32_16x16x32_bf16 v[124:127], v[154:157], v[186:189], v[124:127]
	v_mfma_f32_16x16x32_bf16 v[116:119], v[162:165], v[186:189], v[116:119]
	v_mfma_f32_16x16x32_bf16 v[108:111], v[154:157], v[194:197], v[108:111]
	v_mfma_f32_16x16x32_bf16 v[100:103], v[162:165], v[194:197], v[100:103]
	v_mfma_f32_16x16x32_bf16 v[92:95], v[154:157], v[204:207], v[92:95]
	v_mfma_f32_16x16x32_bf16 v[84:87], v[162:165], v[204:207], v[84:87]
	v_mfma_f32_16x16x32_bf16 v[76:79], v[154:157], v[212:215], v[76:79]
	v_mfma_f32_16x16x32_bf16 v[68:71], v[162:165], v[212:215], v[68:71]
	s_setprio 0
	s_setprio 1
	v_mfma_f32_16x16x32_bf16 v[120:123], v[166:169], v[182:185], v[120:123]
	v_mfma_f32_16x16x32_bf16 v[112:115], v[174:177], v[182:185], v[112:115]
	v_mfma_f32_16x16x32_bf16 v[104:107], v[166:169], v[190:193], v[104:107]
	v_mfma_f32_16x16x32_bf16 v[96:99], v[174:177], v[190:193], v[96:99]
	v_mfma_f32_16x16x32_bf16 v[88:91], v[166:169], v[200:203], v[88:91]
	v_mfma_f32_16x16x32_bf16 v[80:83], v[174:177], v[200:203], v[80:83]
	v_mfma_f32_16x16x32_bf16 v[72:75], v[166:169], v[208:211], v[72:75]
	v_mfma_f32_16x16x32_bf16 v[64:67], v[174:177], v[208:211], v[64:67]
	v_mfma_f32_16x16x32_bf16 v[120:123], v[170:173], v[186:189], v[120:123]
	v_mfma_f32_16x16x32_bf16 v[112:115], v[178:181], v[186:189], v[112:115]
	v_mfma_f32_16x16x32_bf16 v[104:107], v[170:173], v[194:197], v[104:107]
	v_mfma_f32_16x16x32_bf16 v[96:99], v[178:181], v[194:197], v[96:99]
	v_mfma_f32_16x16x32_bf16 v[88:91], v[170:173], v[204:207], v[88:91]
	v_mfma_f32_16x16x32_bf16 v[80:83], v[178:181], v[204:207], v[80:83]
	v_mfma_f32_16x16x32_bf16 v[72:75], v[170:173], v[212:215], v[72:75]
	v_mfma_f32_16x16x32_bf16 v[64:67], v[178:181], v[212:215], v[64:67]
	s_setprio 0
	s_barrier
; #define PG8_STAGE(bufoff, gbase, voff) do { _Pragma("unroll") for (int _i = 0; _i < 2; ++_i) \
;         __builtin_amdgcn_global_load_lds((const unsigned*)((const char*)(gbase) + (voff)[_i]), (PG8_LAS unsigned*)(lds + (bufoff) + ldsw + _i * 8192), 16, 0, 0); } while (0)
; #define PG8_LDA(dst, b, h) do { _Pragma("unroll") for (int m = 0; m < 4; ++m) _Pragma("unroll") for (int k = 0; k < 2; ++k) dst[m][k] = *(const PG8_LAS bf16x8*)(lds + PG8_SA(b, h) + aoff + m * 2048 + k * 1024); } while (0)
; #define PG8_MMA(ai, bj, At, Bt) do { __builtin_amdgcn_s_setprio(1); _Pragma("unroll") for (int m = 0; m < 4; ++m) _Pragma("unroll") for (int n = 0; n < 2; ++n) _Pragma("unroll") for (int k = 0; k < 2; ++k) \
;         acc[ai][bj][m][n] = __builtin_amdgcn_mfma_f32_16x16x32_bf16(Bt[n][k], At[m][k], acc[ai][bj][m][n], 0, 0, 0); __builtin_amdgcn_s_setprio(0); } while (0)
; #define PG8_WAIT_V(n) asm volatile("s_waitcnt vmcnt(" #n ")" ::: "memory")
; #define PG8_WAIT_L(n) asm volatile("s_waitcnt lgkmcnt(" #n ")" ::: "memory")
; #define PG8_BAR __builtin_amdgcn_s_barrier()
; #define PG8_SCHED __builtin_amdgcn_sched_barrier(0)
; template <class Epi, class Sched, bool ALIGN_EPI = false, bool SP2 = false>
; __device__ __forceinline__ void gemm_phase(PG8_LAS unsigned char* lds, const Gemm g, const Sched& S, const Epi& E) {
;     ...
;         for (int t = 0; t < nt; t += 2) {
;     ...
;             PG8_LDA(At, 1, 1); PG8_STAGE(PG8_SB(1, 0), b3, voffB); PG8_STAGE(PG8_SB(1, 1), b3 + hstep, voffB); PG8_STAGE(PG8_SA(1, 0), a3, voffA);
;             PG8_WAIT_V(8); PG8_WAIT_L(0); PG8_BAR; PG8_MMA(1, 0, At, B0); PG8_MMA(1, 1, At, B1); PG8_BAR; PG8_SCHED;
;     ...
;         if constexpr (ALIGN_EPI) { if (wr == 0) PG8_BAR; }
	s_add_i32 s24, s52, s26
	v_lshl_add_u64 v[216:217], v[216:217], 0, s[6:7]
	s_mov_b32 m0, s24
	ds_read_b128 v[182:185], v149 offset:49152
	ds_read_b128 v[186:189], v149 offset:50176
	ds_read_b128 v[190:193], v149 offset:51200
	ds_read_b128 v[194:197], v149 offset:52224
	ds_read_b128 v[200:203], v149 offset:53248
	ds_read_b128 v[204:207], v149 offset:54272
	ds_read_b128 v[208:211], v149 offset:55296
	ds_read_b128 v[212:215], v149 offset:56320
	global_load_lds_dwordx4 v[216:217], off
	s_add_i32 m0, s24, 0x2000
	s_add_u32 s22, s22, 0x40080
	v_lshl_add_u64 v[216:217], v[218:219], 0, s[6:7]
	s_addc_u32 s23, s23, 0
	s_add_i32 s24, s53, s26
	global_load_lds_dwordx4 v[216:217], off
	v_lshl_add_u64 v[216:217], s[22:23], 0, v[132:133]
	s_mov_b32 m0, s24
	s_nop 0
	global_load_lds_dwordx4 v[216:217], off
	v_lshl_add_u64 v[216:217], s[22:23], 0, v[128:129]
	s_add_i32 m0, s24, 0x2000
	s_nop 0
	global_load_lds_dwordx4 v[216:217], off
	v_lshl_add_u64 v[216:217], v[220:221], 0, s[6:7]
	s_mov_b32 m0, s35
	s_nop 0
	global_load_lds_dwordx4 v[216:217], off
	v_lshl_add_u64 v[216:217], v[222:223], 0, s[6:7]
	s_mov_b32 m0, s36
	s_nop 0
	global_load_lds_dwordx4 v[216:217], off
	s_sleep 1
	s_waitcnt vmcnt(8)
	s_waitcnt lgkmcnt(0)
	s_barrier
	s_setprio 1
	s_waitcnt lgkmcnt(0)
	v_mfma_f32_16x16x32_bf16 v[60:63], v[150:153], v[182:185], v[60:63]
	v_mfma_f32_16x16x32_bf16 v[52:55], v[158:161], v[182:185], v[52:55]
	v_mfma_f32_16x16x32_bf16 v[44:47], v[150:153], v[190:193], v[44:47]
	v_mfma_f32_16x16x32_bf16 v[36:39], v[158:161], v[190:193], v[36:39]
	v_mfma_f32_16x16x32_bf16 v[28:31], v[150:153], v[200:203], v[28:31]
	v_mfma_f32_16x16x32_bf16 v[20:23], v[158:161], v[200:203], v[20:23]
	v_mfma_f32_16x16x32_bf16 v[12:15], v[150:153], v[208:211], v[12:15]
	v_mfma_f32_16x16x32_bf16 v[4:7], v[158:161], v[208:211], v[4:7]
	v_mfma_f32_16x16x32_bf16 v[60:63], v[154:157], v[186:189], v[60:63]
	v_mfma_f32_16x16x32_bf16 v[52:55], v[162:165], v[186:189], v[52:55]
	v_mfma_f32_16x16x32_bf16 v[44:47], v[154:157], v[194:197], v[44:47]
	v_mfma_f32_16x16x32_bf16 v[36:39], v[162:165], v[194:197], v[36:39]
	v_mfma_f32_16x16x32_bf16 v[28:31], v[154:157], v[204:207], v[28:31]
	v_mfma_f32_16x16x32_bf16 v[20:23], v[162:165], v[204:207], v[20:23]
	v_mfma_f32_16x16x32_bf16 v[12:15], v[154:157], v[212:215], v[12:15]
	v_mfma_f32_16x16x32_bf16 v[4:7], v[162:165], v[212:215], v[4:7]
	s_setprio 0
	s_setprio 1
	v_mfma_f32_16x16x32_bf16 v[56:59], v[166:169], v[182:185], v[56:59]
	v_mfma_f32_16x16x32_bf16 v[48:51], v[174:177], v[182:185], v[48:51]
	v_mfma_f32_16x16x32_bf16 v[40:43], v[166:169], v[190:193], v[40:43]
	v_mfma_f32_16x16x32_bf16 v[32:35], v[174:177], v[190:193], v[32:35]
	v_mfma_f32_16x16x32_bf16 v[24:27], v[166:169], v[200:203], v[24:27]
	v_mfma_f32_16x16x32_bf16 v[16:19], v[174:177], v[200:203], v[16:19]
	v_mfma_f32_16x16x32_bf16 v[8:11], v[166:169], v[208:211], v[8:11]
	v_mfma_f32_16x16x32_bf16 v[0:3], v[174:177], v[208:211], v[0:3]
	v_mfma_f32_16x16x32_bf16 v[56:59], v[170:173], v[186:189], v[56:59]
	v_mfma_f32_16x16x32_bf16 v[48:51], v[178:181], v[186:189], v[48:51]
	v_mfma_f32_16x16x32_bf16 v[40:43], v[170:173], v[194:197], v[40:43]
	v_mfma_f32_16x16x32_bf16 v[32:35], v[178:181], v[194:197], v[32:35]
	v_mfma_f32_16x16x32_bf16 v[24:27], v[170:173], v[204:207], v[24:27]
	v_mfma_f32_16x16x32_bf16 v[16:19], v[178:181], v[204:207], v[16:19]
	v_mfma_f32_16x16x32_bf16 v[8:11], v[170:173], v[212:215], v[8:11]
	v_mfma_f32_16x16x32_bf16 v[0:3], v[178:181], v[212:215], v[0:3]
	s_setprio 0
	s_barrier
	s_add_i32 s51, s51, 2
	s_add_u32 s20, s20, 0x100
	s_addc_u32 s21, s21, 0
	s_add_u32 s49, s49, 0x100
	s_addc_u32 s50, s50, 0
	s_cmp_gt_u32 s51, 13
	s_cbranch_scc0 .LBB0_244
	s_and_b64 vcc, exec, s[8:9]
	s_cbranch_vccz .LBB0_247
	s_barrier

; #define PG8_STAGE(bufoff, gbase, voff) do { _Pragma("unroll") for (int _i = 0; _i < 2; ++_i) \
;         __builtin_amdgcn_global_load_lds((const unsigned*)((const char*)(gbase) + (voff)[_i]), (PG8_LAS unsigned*)(lds + (bufoff) + ldsw + _i * 8192), 16, 0, 0); } while (0)
; #define PG8_LDA(dst, b, h) do { _Pragma("unroll") for (int m = 0; m < 4; ++m) _Pragma("unroll") for (int k = 0; k < 2; ++k) dst[m][k] = *(const PG8_LAS bf16x8*)(lds + PG8_SA(b, h) + aoff + m * 2048 + k * 1024); } while (0)
; #define PG8_LDB(dst, b, h) do { _Pragma("unroll") for (int n = 0; n < 2; ++n) _Pragma("unroll") for (int k = 0; k < 2; ++k) dst[n][k] = *(const PG8_LAS bf16x8*)(lds + PG8_SB(b, h) + boff + n * 2048 + k * 1024); } while (0)
; #define PG8_MMA(ai, bj, At, Bt) do { __builtin_amdgcn_s_setprio(1); _Pragma("unroll") for (int m = 0; m < 4; ++m) _Pragma("unroll") for (int n = 0; n < 2; ++n) _Pragma("unroll") for (int k = 0; k < 2; ++k) \
;         acc[ai][bj][m][n] = __builtin_amdgcn_mfma_f32_16x16x32_bf16(Bt[n][k], At[m][k], acc[ai][bj][m][n], 0, 0, 0); __builtin_amdgcn_s_setprio(0); } while (0)
; #define PG8_WAIT_V(n) asm volatile("s_waitcnt vmcnt(" #n ")" ::: "memory")
; #define PG8_BAR __builtin_amdgcn_s_barrier()
; template <class Epi, class Sched, bool ALIGN_EPI = false, bool SP2 = false>
; __device__ __forceinline__ void gemm_phase(PG8_LAS unsigned char* lds, const Gemm g, const Sched& S, const Epi& E) {
;     ...
;         for (int t = 0; t < nt; t += 2) {
;             const bool last = (t == nt - 2);
;             const char* a1 = cA + (size_t)(t + 1) * kstep;
;             const char* a2 = last ? nA : cA + (size_t)(t + 2) * kstep; const char* b2 = last ? nB : cB + (size_t)(t + 2) * kstep;
;             const char* a3 = a2 + kstep; const char* b3 = b2 + kstep;
;             if (last && has_next) S.a_ready(nxt);
;             if constexpr (SP2) {
;             PG8_LDB(B0, 0, 0); PG8_LDB(B1, 0, 1); PG8_SCHED; PG8_LDA(At, 0, 0); PG8_STAGE(PG8_SA(1, 1), a1 + hstep, voffA);
;             PG8_WAIT_V(8); PG8_WAIT_L(0); PG8_BAR; PG8_MMA(0, 0, At, B0); PG8_MMA(0, 1, At, B1); PG8_BAR; PG8_SCHED;
;             PG8_LDA(At, 0, 1); PG8_STAGE(PG8_SB(0, 0), b2, voffB); PG8_STAGE(PG8_SB(0, 1), b2 + hstep, voffB); PG8_STAGE(PG8_SA(0, 0), a2, voffA);
;             PG8_WAIT_V(8); PG8_WAIT_L(0); PG8_BAR; PG8_MMA(1, 0, At, B0); PG8_MMA(1, 1, At, B1); PG8_BAR; PG8_SCHED;
.LBB0_321:
	ds_read_b128 v[128:131], v171
	ds_read_b128 v[132:135], v171 offset:1024
	ds_read_b128 v[136:139], v171 offset:2048
	ds_read_b128 v[140:143], v171 offset:3072
	ds_read_b128 v[160:163], v172
	ds_read_b128 v[164:167], v172 offset:1024
	ds_read_b128 v[176:179], v172 offset:2048
	ds_read_b128 v[180:183], v172 offset:3072
	s_add_u32 s22, s20, 0xfff50080
	s_addc_u32 s23, s21, -1
	s_cmp_eq_u32 s58, 40
	s_cselect_b32 s25, s5, s23
	s_cselect_b32 s24, s4, s22
	s_cselect_b32 s23, s19, s57
	s_cselect_b32 s22, s18, s56
	v_lshl_add_u64 v[196:197], s[20:21], 0, v[152:153]
	s_add_i32 m0, s29, 0xc000
	ds_read_b128 v[184:187], v173
	ds_read_b128 v[188:191], v173 offset:1024
	ds_read_b128 v[192:195], v173 offset:2048
	ds_read_b128 v[200:203], v173 offset:3072
	ds_read_b128 v[204:207], v173 offset:4096
	ds_read_b128 v[208:211], v173 offset:5120
	ds_read_b128 v[212:215], v173 offset:6144
	ds_read_b128 v[216:219], v173 offset:7168
	global_load_lds_dwordx4 v[196:197], off
	v_lshl_add_u64 v[196:197], s[20:21], 0, v[154:155]
	s_add_i32 m0, s29, 0xe000
	s_nop 0
	global_load_lds_dwordx4 v[196:197], off
	s_sleep 1
	s_waitcnt vmcnt(8)
	s_waitcnt lgkmcnt(0)
	s_barrier
	s_setprio 1
	s_waitcnt lgkmcnt(0)
	v_mfma_f32_16x16x32_bf16 v[124:127], v[128:131], v[184:187], v[124:127]
	v_mfma_f32_16x16x32_bf16 v[120:123], v[136:139], v[184:187], v[120:123]
	v_mfma_f32_16x16x32_bf16 v[108:111], v[128:131], v[192:195], v[108:111]
	v_mfma_f32_16x16x32_bf16 v[104:107], v[136:139], v[192:195], v[104:107]
	v_mfma_f32_16x16x32_bf16 v[92:95], v[128:131], v[204:207], v[92:95]
	v_mfma_f32_16x16x32_bf16 v[88:91], v[136:139], v[204:207], v[88:91]
	v_mfma_f32_16x16x32_bf16 v[76:79], v[128:131], v[212:215], v[76:79]
	v_mfma_f32_16x16x32_bf16 v[72:75], v[136:139], v[212:215], v[72:75]
	v_mfma_f32_16x16x32_bf16 v[124:127], v[132:135], v[188:191], v[124:127]
	v_mfma_f32_16x16x32_bf16 v[120:123], v[140:143], v[188:191], v[120:123]
	v_mfma_f32_16x16x32_bf16 v[108:111], v[132:135], v[200:203], v[108:111]
	v_mfma_f32_16x16x32_bf16 v[104:107], v[140:143], v[200:203], v[104:107]
	v_mfma_f32_16x16x32_bf16 v[92:95], v[132:135], v[208:211], v[92:95]
	v_mfma_f32_16x16x32_bf16 v[88:91], v[140:143], v[208:211], v[88:91]
	v_mfma_f32_16x16x32_bf16 v[76:79], v[132:135], v[216:219], v[76:79]
	v_mfma_f32_16x16x32_bf16 v[72:75], v[140:143], v[216:219], v[72:75]
	s_setprio 0
	s_setprio 1
	v_mfma_f32_16x16x32_bf16 v[116:119], v[160:163], v[184:187], v[116:119]
	v_mfma_f32_16x16x32_bf16 v[112:115], v[176:179], v[184:187], v[112:115]
	v_mfma_f32_16x16x32_bf16 v[100:103], v[160:163], v[192:195], v[100:103]
	v_mfma_f32_16x16x32_bf16 v[96:99], v[176:179], v[192:195], v[96:99]
	v_mfma_f32_16x16x32_bf16 v[84:87], v[160:163], v[204:207], v[84:87]
	v_mfma_f32_16x16x32_bf16 v[80:83], v[176:179], v[204:207], v[80:83]
	v_mfma_f32_16x16x32_bf16 v[68:71], v[160:163], v[212:215], v[68:71]
	v_mfma_f32_16x16x32_bf16 v[64:67], v[176:179], v[212:215], v[64:67]
	v_mfma_f32_16x16x32_bf16 v[116:119], v[164:167], v[188:191], v[116:119]
	v_mfma_f32_16x16x32_bf16 v[112:115], v[180:183], v[188:191], v[112:115]
	v_mfma_f32_16x16x32_bf16 v[100:103], v[164:167], v[200:203], v[100:103]
	v_mfma_f32_16x16x32_bf16 v[96:99], v[180:183], v[200:203], v[96:99]
	v_mfma_f32_16x16x32_bf16 v[84:87], v[164:167], v[208:211], v[84:87]
	v_mfma_f32_16x16x32_bf16 v[80:83], v[180:183], v[208:211], v[80:83]
	v_mfma_f32_16x16x32_bf16 v[68:71], v[164:167], v[216:219], v[68:71]
	v_mfma_f32_16x16x32_bf16 v[64:67], v[180:183], v[216:219], v[64:67]
	s_setprio 0
	s_barrier
	s_add_i32 s59, s50, s28
	v_lshl_add_u64 v[196:197], s[22:23], 0, v[146:147]
	s_mov_b32 m0, s59
	ds_read_b128 v[184:187], v173 offset:16384
	ds_read_b128 v[188:191], v173 offset:17408
	ds_read_b128 v[192:195], v173 offset:18432
	ds_read_b128 v[200:203], v173 offset:19456
	ds_read_b128 v[204:207], v173 offset:20480
	ds_read_b128 v[208:211], v173 offset:21504
	ds_read_b128 v[212:215], v173 offset:22528
	ds_read_b128 v[216:219], v173 offset:23552
	global_load_lds_dwordx4 v[196:197], off
	s_add_i32 m0, s59, 0x2000
	s_add_u32 s60, s22, 0xb0000
	v_lshl_add_u64 v[220:221], s[22:23], 0, v[150:151]
	s_addc_u32 s61, s23, 0
	s_add_i32 s59, s51, s28
	global_load_lds_dwordx4 v[220:221], off
	v_lshl_add_u64 v[222:223], s[60:61], 0, v[146:147]
	s_mov_b32 m0, s59
	v_lshl_add_u64 v[224:225], s[24:25], 0, v[148:149]
	global_load_lds_dwordx4 v[222:223], off
	v_lshl_add_u64 v[222:223], s[60:61], 0, v[150:151]
	s_add_i32 m0, s59, 0x2000
	s_nop 0
	global_load_lds_dwordx4 v[222:223], off
	v_lshl_add_u64 v[222:223], s[24:25], 0, v[144:145]
	s_mov_b32 m0, s29
	s_nop 0
	global_load_lds_dwordx4 v[222:223], off
	s_mov_b32 m0, s30
	s_nop 0
	global_load_lds_dwordx4 v[224:225], off
	s_sleep 1
	s_waitcnt vmcnt(8)
	s_waitcnt lgkmcnt(0)
	s_barrier
; #define PG8_STAGE(bufoff, gbase, voff) do { _Pragma("unroll") for (int _i = 0; _i < 2; ++_i) \
;         __builtin_amdgcn_global_load_lds((const unsigned*)((const char*)(gbase) + (voff)[_i]), (PG8_LAS unsigned*)(lds + (bufoff) + ldsw + _i * 8192), 16, 0, 0); } while (0)
; #define PG8_LDA(dst, b, h) do { _Pragma("unroll") for (int m = 0; m < 4; ++m) _Pragma("unroll") for (int k = 0; k < 2; ++k) dst[m][k] = *(const PG8_LAS bf16x8*)(lds + PG8_SA(b, h) + aoff + m * 2048 + k * 1024); } while (0)
; #define PG8_LDB(dst, b, h) do { _Pragma("unroll") for (int n = 0; n < 2; ++n) _Pragma("unroll") for (int k = 0; k < 2; ++k) dst[n][k] = *(const PG8_LAS bf16x8*)(lds + PG8_SB(b, h) + boff + n * 2048 + k * 1024); } while (0)
; #define PG8_MMA(ai, bj, At, Bt) do { __builtin_amdgcn_s_setprio(1); _Pragma("unroll") for (int m = 0; m < 4; ++m) _Pragma("unroll") for (int n = 0; n < 2; ++n) _Pragma("unroll") for (int k = 0; k < 2; ++k) \
;         acc[ai][bj][m][n] = __builtin_amdgcn_mfma_f32_16x16x32_bf16(Bt[n][k], At[m][k], acc[ai][bj][m][n], 0, 0, 0); __builtin_amdgcn_s_setprio(0); } while (0)
; #define PG8_WAIT_V(n) asm volatile("s_waitcnt vmcnt(" #n ")" ::: "memory")
; #define PG8_WAIT_L(n) asm volatile("s_waitcnt lgkmcnt(" #n ")" ::: "memory")
; #define PG8_BAR __builtin_amdgcn_s_barrier()
; #define PG8_SCHED __builtin_amdgcn_sched_barrier(0)
; template <class Epi, class Sched, bool ALIGN_EPI = false, bool SP2 = false>
; __device__ __forceinline__ void gemm_phase(PG8_LAS unsigned char* lds, const Gemm g, const Sched& S, const Epi& E) {
;     ...
;             PG8_WAIT_V(8); PG8_WAIT_L(0); PG8_BAR; PG8_MMA(1, 0, At, B0); PG8_MMA(1, 1, At, B1); PG8_BAR; PG8_SCHED;
;             PG8_LDB(B0, 1, 0); PG8_LDB(B1, 1, 1); PG8_SCHED; PG8_LDA(At, 1, 0); PG8_STAGE(PG8_SA(0, 1), a2 + hstep, voffA);
;             PG8_WAIT_V(8); PG8_WAIT_L(0); PG8_BAR; PG8_MMA(0, 0, At, B0); PG8_MMA(0, 1, At, B1); PG8_BAR; PG8_SCHED;
	s_setprio 1
	s_waitcnt lgkmcnt(0)
	v_mfma_f32_16x16x32_bf16 v[60:63], v[128:131], v[184:187], v[60:63]
	v_mfma_f32_16x16x32_bf16 v[56:59], v[136:139], v[184:187], v[56:59]
	v_mfma_f32_16x16x32_bf16 v[44:47], v[128:131], v[192:195], v[44:47]
	v_mfma_f32_16x16x32_bf16 v[40:43], v[136:139], v[192:195], v[40:43]
	v_mfma_f32_16x16x32_bf16 v[28:31], v[128:131], v[204:207], v[28:31]
	v_mfma_f32_16x16x32_bf16 v[24:27], v[136:139], v[204:207], v[24:27]
	v_mfma_f32_16x16x32_bf16 v[12:15], v[128:131], v[212:215], v[12:15]
	v_mfma_f32_16x16x32_bf16 v[8:11], v[136:139], v[212:215], v[8:11]
	v_mfma_f32_16x16x32_bf16 v[60:63], v[132:135], v[188:191], v[60:63]
	v_mfma_f32_16x16x32_bf16 v[56:59], v[140:143], v[188:191], v[56:59]
	v_mfma_f32_16x16x32_bf16 v[44:47], v[132:135], v[200:203], v[44:47]
	v_mfma_f32_16x16x32_bf16 v[40:43], v[140:143], v[200:203], v[40:43]
	v_mfma_f32_16x16x32_bf16 v[28:31], v[132:135], v[208:211], v[28:31]
	v_mfma_f32_16x16x32_bf16 v[24:27], v[140:143], v[208:211], v[24:27]
	v_mfma_f32_16x16x32_bf16 v[12:15], v[132:135], v[216:219], v[12:15]
	v_mfma_f32_16x16x32_bf16 v[8:11], v[140:143], v[216:219], v[8:11]
	s_setprio 0
	s_setprio 1
	v_mfma_f32_16x16x32_bf16 v[52:55], v[160:163], v[184:187], v[52:55]
	v_mfma_f32_16x16x32_bf16 v[48:51], v[176:179], v[184:187], v[48:51]
	v_mfma_f32_16x16x32_bf16 v[36:39], v[160:163], v[192:195], v[36:39]
	v_mfma_f32_16x16x32_bf16 v[32:35], v[176:179], v[192:195], v[32:35]
	v_mfma_f32_16x16x32_bf16 v[20:23], v[160:163], v[204:207], v[20:23]
	v_mfma_f32_16x16x32_bf16 v[16:19], v[176:179], v[204:207], v[16:19]
	v_mfma_f32_16x16x32_bf16 v[4:7], v[160:163], v[212:215], v[4:7]
	v_mfma_f32_16x16x32_bf16 v[0:3], v[176:179], v[212:215], v[0:3]
	v_mfma_f32_16x16x32_bf16 v[52:55], v[164:167], v[188:191], v[52:55]
	v_mfma_f32_16x16x32_bf16 v[48:51], v[180:183], v[188:191], v[48:51]
	v_mfma_f32_16x16x32_bf16 v[36:39], v[164:167], v[200:203], v[36:39]
	v_mfma_f32_16x16x32_bf16 v[32:35], v[180:183], v[200:203], v[32:35]
	v_mfma_f32_16x16x32_bf16 v[20:23], v[164:167], v[208:211], v[20:23]
	v_mfma_f32_16x16x32_bf16 v[16:19], v[180:183], v[208:211], v[16:19]
	v_mfma_f32_16x16x32_bf16 v[4:7], v[164:167], v[216:219], v[4:7]
	v_mfma_f32_16x16x32_bf16 v[0:3], v[180:183], v[216:219], v[0:3]
	s_setprio 0
	s_barrier
	s_add_i32 s59, 0, 0x18000
	s_add_i32 s60, 0, 0x1c000
	v_add_u32_e32 v140, s59, v169
	v_add_u32_e32 v175, s60, v169
	ds_read_b128 v[128:131], v140
	ds_read_b128 v[132:135], v140 offset:1024
	ds_read_b128 v[136:139], v140 offset:2048
	ds_read_b128 v[140:143], v140 offset:3072
	ds_read_b128 v[160:163], v175
	ds_read_b128 v[164:167], v175 offset:1024
	ds_read_b128 v[176:179], v175 offset:2048
	ds_read_b128 v[180:183], v175 offset:3072
	s_add_u32 s24, s24, 0xb0000
	s_addc_u32 s25, s25, 0
	s_mov_b32 m0, s31
	v_lshl_add_u64 v[226:227], s[24:25], 0, v[144:145]
	ds_read_b128 v[184:187], v173 offset:32768
	ds_read_b128 v[188:191], v173 offset:33792
	ds_read_b128 v[192:195], v173 offset:34816
	ds_read_b128 v[200:203], v173 offset:35840
	ds_read_b128 v[204:207], v173 offset:36864
	ds_read_b128 v[208:211], v173 offset:37888
	ds_read_b128 v[212:215], v173 offset:38912
	ds_read_b128 v[216:219], v173 offset:39936
	global_load_lds_dwordx4 v[226:227], off
	v_lshl_add_u64 v[226:227], s[24:25], 0, v[148:149]
	s_mov_b32 m0, s34
	s_nop 0
	global_load_lds_dwordx4 v[226:227], off
	s_sleep 1
	s_waitcnt vmcnt(8)
	s_waitcnt lgkmcnt(0)
	s_barrier
	s_setprio 1
	s_waitcnt lgkmcnt(0)
	v_mfma_f32_16x16x32_bf16 v[124:127], v[128:131], v[184:187], v[124:127]
	v_mfma_f32_16x16x32_bf16 v[120:123], v[136:139], v[184:187], v[120:123]
	v_mfma_f32_16x16x32_bf16 v[108:111], v[128:131], v[192:195], v[108:111]
	v_mfma_f32_16x16x32_bf16 v[104:107], v[136:139], v[192:195], v[104:107]
	v_mfma_f32_16x16x32_bf16 v[92:95], v[128:131], v[204:207], v[92:95]
	v_mfma_f32_16x16x32_bf16 v[88:91], v[136:139], v[204:207], v[88:91]
	v_mfma_f32_16x16x32_bf16 v[76:79], v[128:131], v[212:215], v[76:79]
	v_mfma_f32_16x16x32_bf16 v[72:75], v[136:139], v[212:215], v[72:75]
	v_mfma_f32_16x16x32_bf16 v[124:127], v[132:135], v[188:191], v[124:127]
	v_mfma_f32_16x16x32_bf16 v[120:123], v[140:143], v[188:191], v[120:123]
	v_mfma_f32_16x16x32_bf16 v[108:111], v[132:135], v[200:203], v[108:111]
	v_mfma_f32_16x16x32_bf16 v[104:107], v[140:143], v[200:203], v[104:107]
	v_mfma_f32_16x16x32_bf16 v[92:95], v[132:135], v[208:211], v[92:95]
	v_mfma_f32_16x16x32_bf16 v[88:91], v[140:143], v[208:211], v[88:91]
	v_mfma_f32_16x16x32_bf16 v[76:79], v[132:135], v[216:219], v[76:79]
	v_mfma_f32_16x16x32_bf16 v[72:75], v[140:143], v[216:219], v[72:75]
	s_setprio 0
	s_setprio 1
	v_mfma_f32_16x16x32_bf16 v[116:119], v[160:163], v[184:187], v[116:119]
	v_mfma_f32_16x16x32_bf16 v[112:115], v[176:179], v[184:187], v[112:115]
	v_mfma_f32_16x16x32_bf16 v[100:103], v[160:163], v[192:195], v[100:103]
	v_mfma_f32_16x16x32_bf16 v[96:99], v[176:179], v[192:195], v[96:99]
	v_mfma_f32_16x16x32_bf16 v[84:87], v[160:163], v[204:207], v[84:87]
	v_mfma_f32_16x16x32_bf16 v[80:83], v[176:179], v[204:207], v[80:83]
	v_mfma_f32_16x16x32_bf16 v[68:71], v[160:163], v[212:215], v[68:71]
	v_mfma_f32_16x16x32_bf16 v[64:67], v[176:179], v[212:215], v[64:67]
	v_mfma_f32_16x16x32_bf16 v[116:119], v[164:167], v[188:191], v[116:119]
	v_mfma_f32_16x16x32_bf16 v[112:115], v[180:183], v[188:191], v[112:115]
	v_mfma_f32_16x16x32_bf16 v[100:103], v[164:167], v[200:203], v[100:103]
	v_mfma_f32_16x16x32_bf16 v[96:99], v[180:183], v[200:203], v[96:99]
	v_mfma_f32_16x16x32_bf16 v[84:87], v[164:167], v[208:211], v[84:87]
	v_mfma_f32_16x16x32_bf16 v[80:83], v[180:183], v[208:211], v[80:83]
	v_mfma_f32_16x16x32_bf16 v[68:71], v[164:167], v[216:219], v[68:71]
	v_mfma_f32_16x16x32_bf16 v[64:67], v[180:183], v[216:219], v[64:67]
	s_setprio 0
	s_barrier
; #define PG8_STAGE(bufoff, gbase, voff) do { _Pragma("unroll") for (int _i = 0; _i < 2; ++_i) \
;         __builtin_amdgcn_global_load_lds((const unsigned*)((const char*)(gbase) + (voff)[_i]), (PG8_LAS unsigned*)(lds + (bufoff) + ldsw + _i * 8192), 16, 0, 0); } while (0)
; #define PG8_LDA(dst, b, h) do { _Pragma("unroll") for (int m = 0; m < 4; ++m) _Pragma("unroll") for (int k = 0; k < 2; ++k) dst[m][k] = *(const PG8_LAS bf16x8*)(lds + PG8_SA(b, h) + aoff + m * 2048 + k * 1024); } while (0)
; #define PG8_MMA(ai, bj, At, Bt) do { __builtin_amdgcn_s_setprio(1); _Pragma("unroll") for (int m = 0; m < 4; ++m) _Pragma("unroll") for (int n = 0; n < 2; ++n) _Pragma("unroll") for (int k = 0; k < 2; ++k) \
;         acc[ai][bj][m][n] = __builtin_amdgcn_mfma_f32_16x16x32_bf16(Bt[n][k], At[m][k], acc[ai][bj][m][n], 0, 0, 0); __builtin_amdgcn_s_setprio(0); } while (0)
; #define PG8_WAIT_V(n) asm volatile("s_waitcnt vmcnt(" #n ")" ::: "memory")
; #define PG8_WAIT_L(n) asm volatile("s_waitcnt lgkmcnt(" #n ")" ::: "memory")
; #define PG8_BAR __builtin_amdgcn_s_barrier()
; #define PG8_SCHED __builtin_amdgcn_sched_barrier(0)
; template <class Epi, class Sched, bool ALIGN_EPI = false, bool SP2 = false>
; __device__ __forceinline__ void gemm_phase(PG8_LAS unsigned char* lds, const Gemm g, const Sched& S, const Epi& E) {
;     ...
;         for (int t = 0; t < nt; t += 2) {
;     ...
;             PG8_LDA(At, 1, 1); PG8_STAGE(PG8_SB(1, 0), b3, voffB); PG8_STAGE(PG8_SB(1, 1), b3 + hstep, voffB); PG8_STAGE(PG8_SA(1, 0), a3, voffA);
;             PG8_WAIT_V(8); PG8_WAIT_L(0); PG8_BAR; PG8_MMA(1, 0, At, B0); PG8_MMA(1, 1, At, B1); PG8_BAR; PG8_SCHED;
;     ...
;         if constexpr (ALIGN_EPI) { if (wr == 0) PG8_BAR; }
	s_add_i32 s24, s59, s28
	v_lshl_add_u64 v[196:197], v[196:197], 0, s[10:11]
	s_mov_b32 m0, s24
	ds_read_b128 v[184:187], v173 offset:49152
	ds_read_b128 v[188:191], v173 offset:50176
	ds_read_b128 v[192:195], v173 offset:51200
	ds_read_b128 v[200:203], v173 offset:52224
	ds_read_b128 v[204:207], v173 offset:53248
	ds_read_b128 v[208:211], v173 offset:54272
	ds_read_b128 v[212:215], v173 offset:55296
	ds_read_b128 v[216:219], v173 offset:56320
	global_load_lds_dwordx4 v[196:197], off
	s_add_i32 m0, s24, 0x2000
	s_add_u32 s22, s22, 0xb0080
	v_lshl_add_u64 v[196:197], v[220:221], 0, s[10:11]
	s_addc_u32 s23, s23, 0
	s_add_i32 s24, s60, s28
	global_load_lds_dwordx4 v[196:197], off
	v_lshl_add_u64 v[196:197], s[22:23], 0, v[146:147]
	s_mov_b32 m0, s24
	s_nop 0
	global_load_lds_dwordx4 v[196:197], off
	v_lshl_add_u64 v[196:197], s[22:23], 0, v[150:151]
	s_add_i32 m0, s24, 0x2000
	s_nop 0
	global_load_lds_dwordx4 v[196:197], off
	v_lshl_add_u64 v[196:197], v[222:223], 0, s[10:11]
	s_mov_b32 m0, s38
	s_nop 0
	global_load_lds_dwordx4 v[196:197], off
	v_lshl_add_u64 v[196:197], v[224:225], 0, s[10:11]
	s_mov_b32 m0, s39
	s_nop 0
	global_load_lds_dwordx4 v[196:197], off
	s_sleep 1
	s_waitcnt vmcnt(8)
	s_waitcnt lgkmcnt(0)
	s_barrier
	s_setprio 1
	s_waitcnt lgkmcnt(0)
	v_mfma_f32_16x16x32_bf16 v[60:63], v[128:131], v[184:187], v[60:63]
	v_mfma_f32_16x16x32_bf16 v[56:59], v[136:139], v[184:187], v[56:59]
	v_mfma_f32_16x16x32_bf16 v[44:47], v[128:131], v[192:195], v[44:47]
	v_mfma_f32_16x16x32_bf16 v[40:43], v[136:139], v[192:195], v[40:43]
	v_mfma_f32_16x16x32_bf16 v[28:31], v[128:131], v[204:207], v[28:31]
	v_mfma_f32_16x16x32_bf16 v[24:27], v[136:139], v[204:207], v[24:27]
	v_mfma_f32_16x16x32_bf16 v[12:15], v[128:131], v[212:215], v[12:15]
	v_mfma_f32_16x16x32_bf16 v[8:11], v[136:139], v[212:215], v[8:11]
	v_mfma_f32_16x16x32_bf16 v[60:63], v[132:135], v[188:191], v[60:63]
	v_mfma_f32_16x16x32_bf16 v[56:59], v[140:143], v[188:191], v[56:59]
	v_mfma_f32_16x16x32_bf16 v[44:47], v[132:135], v[200:203], v[44:47]
	v_mfma_f32_16x16x32_bf16 v[40:43], v[140:143], v[200:203], v[40:43]
	v_mfma_f32_16x16x32_bf16 v[28:31], v[132:135], v[208:211], v[28:31]
	v_mfma_f32_16x16x32_bf16 v[24:27], v[140:143], v[208:211], v[24:27]
	v_mfma_f32_16x16x32_bf16 v[12:15], v[132:135], v[216:219], v[12:15]
	v_mfma_f32_16x16x32_bf16 v[8:11], v[140:143], v[216:219], v[8:11]
	s_setprio 0
	s_setprio 1
	v_mfma_f32_16x16x32_bf16 v[52:55], v[160:163], v[184:187], v[52:55]
	v_mfma_f32_16x16x32_bf16 v[48:51], v[176:179], v[184:187], v[48:51]
	v_mfma_f32_16x16x32_bf16 v[36:39], v[160:163], v[192:195], v[36:39]
	v_mfma_f32_16x16x32_bf16 v[32:35], v[176:179], v[192:195], v[32:35]
	v_mfma_f32_16x16x32_bf16 v[20:23], v[160:163], v[204:207], v[20:23]
	v_mfma_f32_16x16x32_bf16 v[16:19], v[176:179], v[204:207], v[16:19]
	v_mfma_f32_16x16x32_bf16 v[4:7], v[160:163], v[212:215], v[4:7]
	v_mfma_f32_16x16x32_bf16 v[0:3], v[176:179], v[212:215], v[0:3]
	v_mfma_f32_16x16x32_bf16 v[52:55], v[164:167], v[188:191], v[52:55]
	v_mfma_f32_16x16x32_bf16 v[48:51], v[180:183], v[188:191], v[48:51]
	v_mfma_f32_16x16x32_bf16 v[36:39], v[164:167], v[200:203], v[36:39]
	v_mfma_f32_16x16x32_bf16 v[32:35], v[180:183], v[200:203], v[32:35]
	v_mfma_f32_16x16x32_bf16 v[20:23], v[164:167], v[208:211], v[20:23]
	v_mfma_f32_16x16x32_bf16 v[16:19], v[180:183], v[208:211], v[16:19]
	v_mfma_f32_16x16x32_bf16 v[4:7], v[164:167], v[216:219], v[4:7]
	v_mfma_f32_16x16x32_bf16 v[0:3], v[180:183], v[216:219], v[0:3]
	s_setprio 0
	s_barrier
	s_add_i32 s58, s58, 2
	s_add_u32 s20, s20, 0x100
	s_addc_u32 s21, s21, 0
	s_add_u32 s56, s56, 0x100
	s_addc_u32 s57, s57, 0
	s_cmp_gt_u32 s58, 41
	s_cbranch_scc0 .LBB0_321
	s_and_b64 vcc, exec, s[16:17]
	s_cbranch_vccz .LBB0_324
	s_barrier

; #define PG8_STAGE(bufoff, gbase, voff) do { _Pragma("unroll") for (int _i = 0; _i < 2; ++_i) \
;         __builtin_amdgcn_global_load_lds((const unsigned*)((const char*)(gbase) + (voff)[_i]), (PG8_LAS unsigned*)(lds + (bufoff) + ldsw + _i * 8192), 16, 0, 0); } while (0)
; #define PG8_LDA(dst, b, h) do { _Pragma("unroll") for (int m = 0; m < 4; ++m) _Pragma("unroll") for (int k = 0; k < 2; ++k) dst[m][k] = *(const PG8_LAS bf16x8*)(lds + PG8_SA(b, h) + aoff + m * 2048 + k * 1024); } while (0)
; #define PG8_LDB(dst, b, h) do { _Pragma("unroll") for (int n = 0; n < 2; ++n) _Pragma("unroll") for (int k = 0; k < 2; ++k) dst[n][k] = *(const PG8_LAS bf16x8*)(lds + PG8_SB(b, h) + boff + n * 2048 + k * 1024); } while (0)
; #define PG8_MMA(ai, bj, At, Bt) do { __builtin_amdgcn_s_setprio(1); _Pragma("unroll") for (int m = 0; m < 4; ++m) _Pragma("unroll") for (int n = 0; n < 2; ++n) _Pragma("unroll") for (int k = 0; k < 2; ++k) \
;         acc[ai][bj][m][n] = __builtin_amdgcn_mfma_f32_16x16x32_bf16(Bt[n][k], At[m][k], acc[ai][bj][m][n], 0, 0, 0); __builtin_amdgcn_s_setprio(0); } while (0)
; #define PG8_WAIT_V(n) asm volatile("s_waitcnt vmcnt(" #n ")" ::: "memory")
; #define PG8_BAR __builtin_amdgcn_s_barrier()
; template <class Epi, class Sched, bool ALIGN_EPI = false, bool SP2 = false>
; __device__ __forceinline__ void gemm_phase(PG8_LAS unsigned char* lds, const Gemm g, const Sched& S, const Epi& E) {
;     ...
;         for (int t = 0; t < nt; t += 2) {
;             const bool last = (t == nt - 2);
;             const char* a1 = cA + (size_t)(t + 1) * kstep;
;             const char* a2 = last ? nA : cA + (size_t)(t + 2) * kstep; const char* b2 = last ? nB : cB + (size_t)(t + 2) * kstep;
;             const char* a3 = a2 + kstep; const char* b3 = b2 + kstep;
;             if (last && has_next) S.a_ready(nxt);
;             if constexpr (SP2) {
;             PG8_LDB(B0, 0, 0); PG8_LDB(B1, 0, 1); PG8_SCHED; PG8_LDA(At, 0, 0); PG8_STAGE(PG8_SA(1, 1), a1 + hstep, voffA);
;             PG8_WAIT_V(8); PG8_WAIT_L(0); PG8_BAR; PG8_MMA(0, 0, At, B0); PG8_MMA(0, 1, At, B1); PG8_BAR; PG8_SCHED;
;             PG8_LDA(At, 0, 1); PG8_STAGE(PG8_SB(0, 0), b2, voffB); PG8_STAGE(PG8_SB(0, 1), b2 + hstep, voffB); PG8_STAGE(PG8_SA(0, 0), a2, voffA);
;             PG8_WAIT_V(8); PG8_WAIT_L(0); PG8_BAR; PG8_MMA(1, 0, At, B0); PG8_MMA(1, 1, At, B1); PG8_BAR; PG8_SCHED;
.LBB0_410:
	ds_read_b128 v[146:149], v175
	ds_read_b128 v[150:153], v175 offset:1024
	ds_read_b128 v[154:157], v175 offset:2048
	ds_read_b128 v[158:161], v175 offset:3072
	ds_read_b128 v[188:191], v176
	ds_read_b128 v[192:195], v176 offset:1024
	ds_read_b128 v[200:203], v176 offset:2048
	ds_read_b128 v[204:207], v176 offset:3072
	s_add_u32 s8, s6, 0xfffc0080
	s_addc_u32 s9, s7, -1
	s_cmp_eq_u32 s18, 12
	s_cselect_b32 s11, s5, s9
	s_cselect_b32 s10, s13, s8
	s_cselect_b32 s9, s14, s17
	s_cselect_b32 s8, s15, s16
	v_lshl_add_u64 v[162:163], s[6:7], 0, v[138:139]
	s_add_i32 m0, s57, 0xc000
	ds_read_b128 v[208:211], v177
	ds_read_b128 v[212:215], v177 offset:1024
	ds_read_b128 v[216:219], v177 offset:2048
	ds_read_b128 v[220:223], v177 offset:3072
	ds_read_b128 v[224:227], v177 offset:4096
	ds_read_b128 v[228:231], v177 offset:5120
	ds_read_b128 v[232:235], v177 offset:6144
	ds_read_b128 v[236:239], v177 offset:7168
	global_load_lds_dwordx4 v[162:163], off
	v_lshl_add_u64 v[162:163], s[6:7], 0, v[140:141]
	s_add_i32 m0, s57, 0xe000
	s_nop 0
	global_load_lds_dwordx4 v[162:163], off
	s_sleep 1
	s_waitcnt vmcnt(8)
	s_waitcnt lgkmcnt(0)
	s_barrier
	s_setprio 1
	s_waitcnt lgkmcnt(0)
	v_mfma_f32_16x16x32_bf16 v[124:127], v[146:149], v[208:211], v[124:127]
	v_mfma_f32_16x16x32_bf16 v[120:123], v[154:157], v[208:211], v[120:123]
	v_mfma_f32_16x16x32_bf16 v[108:111], v[146:149], v[216:219], v[108:111]
	v_mfma_f32_16x16x32_bf16 v[104:107], v[154:157], v[216:219], v[104:107]
	v_mfma_f32_16x16x32_bf16 v[92:95], v[146:149], v[224:227], v[92:95]
	v_mfma_f32_16x16x32_bf16 v[88:91], v[154:157], v[224:227], v[88:91]
	v_mfma_f32_16x16x32_bf16 v[76:79], v[146:149], v[232:235], v[76:79]
	v_mfma_f32_16x16x32_bf16 v[72:75], v[154:157], v[232:235], v[72:75]
	v_mfma_f32_16x16x32_bf16 v[124:127], v[150:153], v[212:215], v[124:127]
	v_mfma_f32_16x16x32_bf16 v[120:123], v[158:161], v[212:215], v[120:123]
	v_mfma_f32_16x16x32_bf16 v[108:111], v[150:153], v[220:223], v[108:111]
	v_mfma_f32_16x16x32_bf16 v[104:107], v[158:161], v[220:223], v[104:107]
	v_mfma_f32_16x16x32_bf16 v[92:95], v[150:153], v[228:231], v[92:95]
	v_mfma_f32_16x16x32_bf16 v[88:91], v[158:161], v[228:231], v[88:91]
	v_mfma_f32_16x16x32_bf16 v[76:79], v[150:153], v[236:239], v[76:79]
	v_mfma_f32_16x16x32_bf16 v[72:75], v[158:161], v[236:239], v[72:75]
	s_setprio 0
	s_setprio 1
	v_mfma_f32_16x16x32_bf16 v[116:119], v[188:191], v[208:211], v[116:119]
	v_mfma_f32_16x16x32_bf16 v[112:115], v[200:203], v[208:211], v[112:115]
	v_mfma_f32_16x16x32_bf16 v[100:103], v[188:191], v[216:219], v[100:103]
	v_mfma_f32_16x16x32_bf16 v[96:99], v[200:203], v[216:219], v[96:99]
	v_mfma_f32_16x16x32_bf16 v[84:87], v[188:191], v[224:227], v[84:87]
	v_mfma_f32_16x16x32_bf16 v[80:83], v[200:203], v[224:227], v[80:83]
	v_mfma_f32_16x16x32_bf16 v[68:71], v[188:191], v[232:235], v[68:71]
	v_mfma_f32_16x16x32_bf16 v[64:67], v[200:203], v[232:235], v[64:67]
	v_mfma_f32_16x16x32_bf16 v[116:119], v[192:195], v[212:215], v[116:119]
	v_mfma_f32_16x16x32_bf16 v[112:115], v[204:207], v[212:215], v[112:115]
	v_mfma_f32_16x16x32_bf16 v[100:103], v[192:195], v[220:223], v[100:103]
	v_mfma_f32_16x16x32_bf16 v[96:99], v[204:207], v[220:223], v[96:99]
	v_mfma_f32_16x16x32_bf16 v[84:87], v[192:195], v[228:231], v[84:87]
	v_mfma_f32_16x16x32_bf16 v[80:83], v[204:207], v[228:231], v[80:83]
	v_mfma_f32_16x16x32_bf16 v[68:71], v[192:195], v[236:239], v[68:71]
	v_mfma_f32_16x16x32_bf16 v[64:67], v[204:207], v[236:239], v[64:67]
	s_setprio 0
	s_barrier
	s_add_i32 s19, s69, s56
	v_lshl_add_u64 v[162:163], s[8:9], 0, v[130:131]
	s_mov_b32 m0, s19
	ds_read_b128 v[208:211], v177 offset:16384
	ds_read_b128 v[212:215], v177 offset:17408
	ds_read_b128 v[216:219], v177 offset:18432
	ds_read_b128 v[220:223], v177 offset:19456
	ds_read_b128 v[224:227], v177 offset:20480
	ds_read_b128 v[228:231], v177 offset:21504
	ds_read_b128 v[232:235], v177 offset:22528
	ds_read_b128 v[236:239], v177 offset:23552
	global_load_lds_dwordx4 v[162:163], off
	s_add_i32 m0, s19, 0x2000
	s_add_u32 s20, s8, 0x40000
	v_lshl_add_u64 v[196:197], s[8:9], 0, v[134:135]
	s_addc_u32 s21, s9, 0
	s_add_i32 s19, s70, s56
	global_load_lds_dwordx4 v[196:197], off
	v_lshl_add_u64 v[240:241], s[20:21], 0, v[130:131]
	s_mov_b32 m0, s19
	v_lshl_add_u64 v[242:243], s[10:11], 0, v[132:133]
	global_load_lds_dwordx4 v[240:241], off
	v_lshl_add_u64 v[240:241], s[20:21], 0, v[134:135]
	s_add_i32 m0, s19, 0x2000
	s_nop 0
	global_load_lds_dwordx4 v[240:241], off
	v_lshl_add_u64 v[240:241], s[10:11], 0, v[128:129]
	s_mov_b32 m0, s57
	s_nop 0
	global_load_lds_dwordx4 v[240:241], off
	s_mov_b32 m0, s58
	s_nop 0
	global_load_lds_dwordx4 v[242:243], off
	s_sleep 1
	s_waitcnt vmcnt(8)
	s_waitcnt lgkmcnt(0)
	s_barrier
; #define PG8_STAGE(bufoff, gbase, voff) do { _Pragma("unroll") for (int _i = 0; _i < 2; ++_i) \
;         __builtin_amdgcn_global_load_lds((const unsigned*)((const char*)(gbase) + (voff)[_i]), (PG8_LAS unsigned*)(lds + (bufoff) + ldsw + _i * 8192), 16, 0, 0); } while (0)
; #define PG8_LDA(dst, b, h) do { _Pragma("unroll") for (int m = 0; m < 4; ++m) _Pragma("unroll") for (int k = 0; k < 2; ++k) dst[m][k] = *(const PG8_LAS bf16x8*)(lds + PG8_SA(b, h) + aoff + m * 2048 + k * 1024); } while (0)
; #define PG8_LDB(dst, b, h) do { _Pragma("unroll") for (int n = 0; n < 2; ++n) _Pragma("unroll") for (int k = 0; k < 2; ++k) dst[n][k] = *(const PG8_LAS bf16x8*)(lds + PG8_SB(b, h) + boff + n * 2048 + k * 1024); } while (0)
; #define PG8_MMA(ai, bj, At, Bt) do { __builtin_amdgcn_s_setprio(1); _Pragma("unroll") for (int m = 0; m < 4; ++m) _Pragma("unroll") for (int n = 0; n < 2; ++n) _Pragma("unroll") for (int k = 0; k < 2; ++k) \
;         acc[ai][bj][m][n] = __builtin_amdgcn_mfma_f32_16x16x32_bf16(Bt[n][k], At[m][k], acc[ai][bj][m][n], 0, 0, 0); __builtin_amdgcn_s_setprio(0); } while (0)
; #define PG8_WAIT_V(n) asm volatile("s_waitcnt vmcnt(" #n ")" ::: "memory")
; #define PG8_WAIT_L(n) asm volatile("s_waitcnt lgkmcnt(" #n ")" ::: "memory")
; #define PG8_BAR __builtin_amdgcn_s_barrier()
; #define PG8_SCHED __builtin_amdgcn_sched_barrier(0)
; template <class Epi, class Sched, bool ALIGN_EPI = false, bool SP2 = false>
; __device__ __forceinline__ void gemm_phase(PG8_LAS unsigned char* lds, const Gemm g, const Sched& S, const Epi& E) {
;     ...
;             PG8_WAIT_V(8); PG8_WAIT_L(0); PG8_BAR; PG8_MMA(1, 0, At, B0); PG8_MMA(1, 1, At, B1); PG8_BAR; PG8_SCHED;
;             PG8_LDB(B0, 1, 0); PG8_LDB(B1, 1, 1); PG8_SCHED; PG8_LDA(At, 1, 0); PG8_STAGE(PG8_SA(0, 1), a2 + hstep, voffA);
;             PG8_WAIT_V(8); PG8_WAIT_L(0); PG8_BAR; PG8_MMA(0, 0, At, B0); PG8_MMA(0, 1, At, B1); PG8_BAR; PG8_SCHED;
	s_setprio 1
	s_waitcnt lgkmcnt(0)
	v_mfma_f32_16x16x32_bf16 v[60:63], v[146:149], v[208:211], v[60:63]
	v_mfma_f32_16x16x32_bf16 v[56:59], v[154:157], v[208:211], v[56:59]
	v_mfma_f32_16x16x32_bf16 v[44:47], v[146:149], v[216:219], v[44:47]
	v_mfma_f32_16x16x32_bf16 v[40:43], v[154:157], v[216:219], v[40:43]
	v_mfma_f32_16x16x32_bf16 v[28:31], v[146:149], v[224:227], v[28:31]
	v_mfma_f32_16x16x32_bf16 v[24:27], v[154:157], v[224:227], v[24:27]
	v_mfma_f32_16x16x32_bf16 v[12:15], v[146:149], v[232:235], v[12:15]
	v_mfma_f32_16x16x32_bf16 v[8:11], v[154:157], v[232:235], v[8:11]
	v_mfma_f32_16x16x32_bf16 v[60:63], v[150:153], v[212:215], v[60:63]
	v_mfma_f32_16x16x32_bf16 v[56:59], v[158:161], v[212:215], v[56:59]
	v_mfma_f32_16x16x32_bf16 v[44:47], v[150:153], v[220:223], v[44:47]
	v_mfma_f32_16x16x32_bf16 v[40:43], v[158:161], v[220:223], v[40:43]
	v_mfma_f32_16x16x32_bf16 v[28:31], v[150:153], v[228:231], v[28:31]
	v_mfma_f32_16x16x32_bf16 v[24:27], v[158:161], v[228:231], v[24:27]
	v_mfma_f32_16x16x32_bf16 v[12:15], v[150:153], v[236:239], v[12:15]
	v_mfma_f32_16x16x32_bf16 v[8:11], v[158:161], v[236:239], v[8:11]
	s_setprio 0
	s_setprio 1
	v_mfma_f32_16x16x32_bf16 v[52:55], v[188:191], v[208:211], v[52:55]
	v_mfma_f32_16x16x32_bf16 v[48:51], v[200:203], v[208:211], v[48:51]
	v_mfma_f32_16x16x32_bf16 v[36:39], v[188:191], v[216:219], v[36:39]
	v_mfma_f32_16x16x32_bf16 v[32:35], v[200:203], v[216:219], v[32:35]
	v_mfma_f32_16x16x32_bf16 v[20:23], v[188:191], v[224:227], v[20:23]
	v_mfma_f32_16x16x32_bf16 v[16:19], v[200:203], v[224:227], v[16:19]
	v_mfma_f32_16x16x32_bf16 v[4:7], v[188:191], v[232:235], v[4:7]
	v_mfma_f32_16x16x32_bf16 v[0:3], v[200:203], v[232:235], v[0:3]
	v_mfma_f32_16x16x32_bf16 v[52:55], v[192:195], v[212:215], v[52:55]
	v_mfma_f32_16x16x32_bf16 v[48:51], v[204:207], v[212:215], v[48:51]
	v_mfma_f32_16x16x32_bf16 v[36:39], v[192:195], v[220:223], v[36:39]
	v_mfma_f32_16x16x32_bf16 v[32:35], v[204:207], v[220:223], v[32:35]
	v_mfma_f32_16x16x32_bf16 v[20:23], v[192:195], v[228:231], v[20:23]
	v_mfma_f32_16x16x32_bf16 v[16:19], v[204:207], v[228:231], v[16:19]
	v_mfma_f32_16x16x32_bf16 v[4:7], v[192:195], v[236:239], v[4:7]
	v_mfma_f32_16x16x32_bf16 v[0:3], v[204:207], v[236:239], v[0:3]
	s_setprio 0
	s_barrier
	s_add_i32 s19, 0, 0x18000
	s_add_i32 s20, 0, 0x1c000
	v_add_u32_e32 v158, s19, v165
	v_add_u32_e32 v199, s20, v165
	ds_read_b128 v[146:149], v158
	ds_read_b128 v[150:153], v158 offset:1024
	ds_read_b128 v[154:157], v158 offset:2048
	ds_read_b128 v[158:161], v158 offset:3072
	ds_read_b128 v[188:191], v199
	ds_read_b128 v[192:195], v199 offset:1024
	ds_read_b128 v[200:203], v199 offset:2048
	ds_read_b128 v[204:207], v199 offset:3072
	s_add_u32 s10, s10, 0x40000
	s_addc_u32 s11, s11, 0
	s_mov_b32 m0, s59
	v_lshl_add_u64 v[244:245], s[10:11], 0, v[128:129]
	ds_read_b128 v[208:211], v177 offset:32768
	ds_read_b128 v[212:215], v177 offset:33792
	ds_read_b128 v[216:219], v177 offset:34816
	ds_read_b128 v[220:223], v177 offset:35840
	ds_read_b128 v[224:227], v177 offset:36864
	ds_read_b128 v[228:231], v177 offset:37888
	ds_read_b128 v[232:235], v177 offset:38912
	ds_read_b128 v[236:239], v177 offset:39936
	global_load_lds_dwordx4 v[244:245], off
	v_lshl_add_u64 v[244:245], s[10:11], 0, v[132:133]
	s_mov_b32 m0, s60
	s_nop 0
	global_load_lds_dwordx4 v[244:245], off
	s_sleep 1
	s_waitcnt vmcnt(8)
	s_waitcnt lgkmcnt(0)
	s_barrier
	s_setprio 1
	s_waitcnt lgkmcnt(0)
	v_mfma_f32_16x16x32_bf16 v[124:127], v[146:149], v[208:211], v[124:127]
	v_mfma_f32_16x16x32_bf16 v[120:123], v[154:157], v[208:211], v[120:123]
	v_mfma_f32_16x16x32_bf16 v[108:111], v[146:149], v[216:219], v[108:111]
	v_mfma_f32_16x16x32_bf16 v[104:107], v[154:157], v[216:219], v[104:107]
	v_mfma_f32_16x16x32_bf16 v[92:95], v[146:149], v[224:227], v[92:95]
	v_mfma_f32_16x16x32_bf16 v[88:91], v[154:157], v[224:227], v[88:91]
	v_mfma_f32_16x16x32_bf16 v[76:79], v[146:149], v[232:235], v[76:79]
	v_mfma_f32_16x16x32_bf16 v[72:75], v[154:157], v[232:235], v[72:75]
	v_mfma_f32_16x16x32_bf16 v[124:127], v[150:153], v[212:215], v[124:127]
	v_mfma_f32_16x16x32_bf16 v[120:123], v[158:161], v[212:215], v[120:123]
	v_mfma_f32_16x16x32_bf16 v[108:111], v[150:153], v[220:223], v[108:111]
	v_mfma_f32_16x16x32_bf16 v[104:107], v[158:161], v[220:223], v[104:107]
	v_mfma_f32_16x16x32_bf16 v[92:95], v[150:153], v[228:231], v[92:95]
	v_mfma_f32_16x16x32_bf16 v[88:91], v[158:161], v[228:231], v[88:91]
	v_mfma_f32_16x16x32_bf16 v[76:79], v[150:153], v[236:239], v[76:79]
	v_mfma_f32_16x16x32_bf16 v[72:75], v[158:161], v[236:239], v[72:75]
	s_setprio 0
	s_setprio 1
	v_mfma_f32_16x16x32_bf16 v[116:119], v[188:191], v[208:211], v[116:119]
	v_mfma_f32_16x16x32_bf16 v[112:115], v[200:203], v[208:211], v[112:115]
	v_mfma_f32_16x16x32_bf16 v[100:103], v[188:191], v[216:219], v[100:103]
	v_mfma_f32_16x16x32_bf16 v[96:99], v[200:203], v[216:219], v[96:99]
	v_mfma_f32_16x16x32_bf16 v[84:87], v[188:191], v[224:227], v[84:87]
	v_mfma_f32_16x16x32_bf16 v[80:83], v[200:203], v[224:227], v[80:83]
	v_mfma_f32_16x16x32_bf16 v[68:71], v[188:191], v[232:235], v[68:71]
	v_mfma_f32_16x16x32_bf16 v[64:67], v[200:203], v[232:235], v[64:67]
	v_mfma_f32_16x16x32_bf16 v[116:119], v[192:195], v[212:215], v[116:119]
	v_mfma_f32_16x16x32_bf16 v[112:115], v[204:207], v[212:215], v[112:115]
	v_mfma_f32_16x16x32_bf16 v[100:103], v[192:195], v[220:223], v[100:103]
	v_mfma_f32_16x16x32_bf16 v[96:99], v[204:207], v[220:223], v[96:99]
	v_mfma_f32_16x16x32_bf16 v[84:87], v[192:195], v[228:231], v[84:87]
	v_mfma_f32_16x16x32_bf16 v[80:83], v[204:207], v[228:231], v[80:83]
	v_mfma_f32_16x16x32_bf16 v[68:71], v[192:195], v[236:239], v[68:71]
	v_mfma_f32_16x16x32_bf16 v[64:67], v[204:207], v[236:239], v[64:67]
	s_setprio 0
	s_barrier
; #define PG8_STAGE(bufoff, gbase, voff) do { _Pragma("unroll") for (int _i = 0; _i < 2; ++_i) \
;         __builtin_amdgcn_global_load_lds((const unsigned*)((const char*)(gbase) + (voff)[_i]), (PG8_LAS unsigned*)(lds + (bufoff) + ldsw + _i * 8192), 16, 0, 0); } while (0)
; #define PG8_LDA(dst, b, h) do { _Pragma("unroll") for (int m = 0; m < 4; ++m) _Pragma("unroll") for (int k = 0; k < 2; ++k) dst[m][k] = *(const PG8_LAS bf16x8*)(lds + PG8_SA(b, h) + aoff + m * 2048 + k * 1024); } while (0)
; #define PG8_MMA(ai, bj, At, Bt) do { __builtin_amdgcn_s_setprio(1); _Pragma("unroll") for (int m = 0; m < 4; ++m) _Pragma("unroll") for (int n = 0; n < 2; ++n) _Pragma("unroll") for (int k = 0; k < 2; ++k) \
;         acc[ai][bj][m][n] = __builtin_amdgcn_mfma_f32_16x16x32_bf16(Bt[n][k], At[m][k], acc[ai][bj][m][n], 0, 0, 0); __builtin_amdgcn_s_setprio(0); } while (0)
; #define PG8_WAIT_V(n) asm volatile("s_waitcnt vmcnt(" #n ")" ::: "memory")
; #define PG8_WAIT_L(n) asm volatile("s_waitcnt lgkmcnt(" #n ")" ::: "memory")
; #define PG8_BAR __builtin_amdgcn_s_barrier()
; #define PG8_SCHED __builtin_amdgcn_sched_barrier(0)
; template <class Epi, class Sched, bool ALIGN_EPI = false, bool SP2 = false>
; __device__ __forceinline__ void gemm_phase(PG8_LAS unsigned char* lds, const Gemm g, const Sched& S, const Epi& E) {
;     ...
;         for (int t = 0; t < nt; t += 2) {
;     ...
;             PG8_LDA(At, 1, 1); PG8_STAGE(PG8_SB(1, 0), b3, voffB); PG8_STAGE(PG8_SB(1, 1), b3 + hstep, voffB); PG8_STAGE(PG8_SA(1, 0), a3, voffA);
;             PG8_WAIT_V(8); PG8_WAIT_L(0); PG8_BAR; PG8_MMA(1, 0, At, B0); PG8_MMA(1, 1, At, B1); PG8_BAR; PG8_SCHED;
;     ...
;         if constexpr (ALIGN_EPI) { if (wr == 0) PG8_BAR; }
	s_add_i32 s10, s19, s56
	v_lshl_add_u64 v[162:163], v[162:163], 0, s[26:27]
	s_mov_b32 m0, s10
	ds_read_b128 v[208:211], v177 offset:49152
	ds_read_b128 v[212:215], v177 offset:50176
	ds_read_b128 v[216:219], v177 offset:51200
	ds_read_b128 v[220:223], v177 offset:52224
	ds_read_b128 v[224:227], v177 offset:53248
	ds_read_b128 v[228:231], v177 offset:54272
	ds_read_b128 v[232:235], v177 offset:55296
	ds_read_b128 v[236:239], v177 offset:56320
	global_load_lds_dwordx4 v[162:163], off
	s_add_i32 m0, s10, 0x2000
	s_add_u32 s8, s8, 0x40080
	v_lshl_add_u64 v[162:163], v[196:197], 0, s[26:27]
	s_addc_u32 s9, s9, 0
	s_add_i32 s10, s20, s56
	global_load_lds_dwordx4 v[162:163], off
	v_lshl_add_u64 v[162:163], s[8:9], 0, v[130:131]
	s_mov_b32 m0, s10
	s_nop 0
	global_load_lds_dwordx4 v[162:163], off
	v_lshl_add_u64 v[162:163], s[8:9], 0, v[134:135]
	s_add_i32 m0, s10, 0x2000
	s_nop 0
	global_load_lds_dwordx4 v[162:163], off
	v_lshl_add_u64 v[162:163], v[240:241], 0, s[26:27]
	s_mov_b32 m0, s62
	s_nop 0
	global_load_lds_dwordx4 v[162:163], off
	v_lshl_add_u64 v[162:163], v[242:243], 0, s[26:27]
	s_mov_b32 m0, s63
	s_nop 0
	global_load_lds_dwordx4 v[162:163], off
	s_sleep 1
	s_waitcnt vmcnt(8)
	s_waitcnt lgkmcnt(0)
	s_barrier
	s_setprio 1
	s_waitcnt lgkmcnt(0)
	v_mfma_f32_16x16x32_bf16 v[60:63], v[146:149], v[208:211], v[60:63]
	v_mfma_f32_16x16x32_bf16 v[56:59], v[154:157], v[208:211], v[56:59]
	v_mfma_f32_16x16x32_bf16 v[44:47], v[146:149], v[216:219], v[44:47]
	v_mfma_f32_16x16x32_bf16 v[40:43], v[154:157], v[216:219], v[40:43]
	v_mfma_f32_16x16x32_bf16 v[28:31], v[146:149], v[224:227], v[28:31]
	v_mfma_f32_16x16x32_bf16 v[24:27], v[154:157], v[224:227], v[24:27]
	v_mfma_f32_16x16x32_bf16 v[12:15], v[146:149], v[232:235], v[12:15]
	v_mfma_f32_16x16x32_bf16 v[8:11], v[154:157], v[232:235], v[8:11]
	v_mfma_f32_16x16x32_bf16 v[60:63], v[150:153], v[212:215], v[60:63]
	v_mfma_f32_16x16x32_bf16 v[56:59], v[158:161], v[212:215], v[56:59]
	v_mfma_f32_16x16x32_bf16 v[44:47], v[150:153], v[220:223], v[44:47]
	v_mfma_f32_16x16x32_bf16 v[40:43], v[158:161], v[220:223], v[40:43]
	v_mfma_f32_16x16x32_bf16 v[28:31], v[150:153], v[228:231], v[28:31]
	v_mfma_f32_16x16x32_bf16 v[24:27], v[158:161], v[228:231], v[24:27]
	v_mfma_f32_16x16x32_bf16 v[12:15], v[150:153], v[236:239], v[12:15]
	v_mfma_f32_16x16x32_bf16 v[8:11], v[158:161], v[236:239], v[8:11]
	s_setprio 0
	s_setprio 1
	v_mfma_f32_16x16x32_bf16 v[52:55], v[188:191], v[208:211], v[52:55]
	v_mfma_f32_16x16x32_bf16 v[48:51], v[200:203], v[208:211], v[48:51]
	v_mfma_f32_16x16x32_bf16 v[36:39], v[188:191], v[216:219], v[36:39]
	v_mfma_f32_16x16x32_bf16 v[32:35], v[200:203], v[216:219], v[32:35]
	v_mfma_f32_16x16x32_bf16 v[20:23], v[188:191], v[224:227], v[20:23]
	v_mfma_f32_16x16x32_bf16 v[16:19], v[200:203], v[224:227], v[16:19]
	v_mfma_f32_16x16x32_bf16 v[4:7], v[188:191], v[232:235], v[4:7]
	v_mfma_f32_16x16x32_bf16 v[0:3], v[200:203], v[232:235], v[0:3]
	v_mfma_f32_16x16x32_bf16 v[52:55], v[192:195], v[212:215], v[52:55]
	v_mfma_f32_16x16x32_bf16 v[48:51], v[204:207], v[212:215], v[48:51]
	v_mfma_f32_16x16x32_bf16 v[36:39], v[192:195], v[220:223], v[36:39]
	v_mfma_f32_16x16x32_bf16 v[32:35], v[204:207], v[220:223], v[32:35]
	v_mfma_f32_16x16x32_bf16 v[20:23], v[192:195], v[228:231], v[20:23]
	v_mfma_f32_16x16x32_bf16 v[16:19], v[204:207], v[228:231], v[16:19]
	v_mfma_f32_16x16x32_bf16 v[4:7], v[192:195], v[236:239], v[4:7]
	v_mfma_f32_16x16x32_bf16 v[0:3], v[204:207], v[236:239], v[0:3]
	s_setprio 0
	s_barrier
	s_add_i32 s18, s18, 2
	s_add_u32 s6, s6, 0x100
	s_addc_u32 s7, s7, 0
	s_add_u32 s16, s16, 0x100
	s_addc_u32 s17, s17, 0
	s_cmp_gt_u32 s18, 13
	s_cbranch_scc0 .LBB0_410
	s_and_b64 vcc, exec, s[28:29]
	s_cbranch_vccz .LBB0_413
	s_barrier

; #define PG8_STAGE(bufoff, gbase, voff) do { _Pragma("unroll") for (int _i = 0; _i < 2; ++_i) \
;         __builtin_amdgcn_global_load_lds((const unsigned*)((const char*)(gbase) + (voff)[_i]), (PG8_LAS unsigned*)(lds + (bufoff) + ldsw + _i * 8192), 16, 0, 0); } while (0)
; #define PG8_LDA(dst, b, h) do { _Pragma("unroll") for (int m = 0; m < 4; ++m) _Pragma("unroll") for (int k = 0; k < 2; ++k) dst[m][k] = *(const PG8_LAS bf16x8*)(lds + PG8_SA(b, h) + aoff + m * 2048 + k * 1024); } while (0)
; #define PG8_LDB(dst, b, h) do { _Pragma("unroll") for (int n = 0; n < 2; ++n) _Pragma("unroll") for (int k = 0; k < 2; ++k) dst[n][k] = *(const PG8_LAS bf16x8*)(lds + PG8_SB(b, h) + boff + n * 2048 + k * 1024); } while (0)
; #define PG8_MMA(ai, bj, At, Bt) do { __builtin_amdgcn_s_setprio(1); _Pragma("unroll") for (int m = 0; m < 4; ++m) _Pragma("unroll") for (int n = 0; n < 2; ++n) _Pragma("unroll") for (int k = 0; k < 2; ++k) \
;         acc[ai][bj][m][n] = __builtin_amdgcn_mfma_f32_16x16x32_bf16(Bt[n][k], At[m][k], acc[ai][bj][m][n], 0, 0, 0); __builtin_amdgcn_s_setprio(0); } while (0)
; #define PG8_WAIT_V(n) asm volatile("s_waitcnt vmcnt(" #n ")" ::: "memory")
; #define PG8_BAR __builtin_amdgcn_s_barrier()
; template <class Epi, class Sched, bool ALIGN_EPI = false, bool SP2 = false>
; __device__ __forceinline__ void gemm_phase(PG8_LAS unsigned char* lds, const Gemm g, const Sched& S, const Epi& E) {
;     ...
;         for (int t = 0; t < nt; t += 2) {
;             const bool last = (t == nt - 2);
;             const char* a1 = cA + (size_t)(t + 1) * kstep;
;             const char* a2 = last ? nA : cA + (size_t)(t + 2) * kstep; const char* b2 = last ? nB : cB + (size_t)(t + 2) * kstep;
;             const char* a3 = a2 + kstep; const char* b3 = b2 + kstep;
;             if (last && has_next) S.a_ready(nxt);
;             if constexpr (SP2) {
;             PG8_LDB(B0, 0, 0); PG8_LDB(B1, 0, 1); PG8_SCHED; PG8_LDA(At, 0, 0); PG8_STAGE(PG8_SA(1, 1), a1 + hstep, voffA);
;             PG8_WAIT_V(8); PG8_WAIT_L(0); PG8_BAR; PG8_MMA(0, 0, At, B0); PG8_MMA(0, 1, At, B1); PG8_BAR; PG8_SCHED;
;             PG8_LDA(At, 0, 1); PG8_STAGE(PG8_SB(0, 0), b2, voffB); PG8_STAGE(PG8_SB(0, 1), b2 + hstep, voffB); PG8_STAGE(PG8_SA(0, 0), a2, voffA);
;             PG8_WAIT_V(8); PG8_WAIT_L(0); PG8_BAR; PG8_MMA(1, 0, At, B0); PG8_MMA(1, 1, At, B1); PG8_BAR; PG8_SCHED;
.LBB0_769:
	ds_read_b128 v[128:131], v165
	ds_read_b128 v[132:135], v165 offset:1024
	ds_read_b128 v[152:155], v165 offset:2048
	ds_read_b128 v[156:159], v165 offset:3072
	ds_read_b128 v[170:173], v166
	ds_read_b128 v[174:177], v166 offset:1024
	ds_read_b128 v[178:181], v166 offset:2048
	ds_read_b128 v[182:185], v166 offset:3072
	s_add_u32 s26, s24, 0xfffc0080
	s_addc_u32 s27, s25, -1
	s_cmp_eq_u32 s60, 12
	s_cselect_b32 s29, s17, s27
	s_cselect_b32 s28, s23, s26
	s_cselect_b32 s27, s15, s59
	s_cselect_b32 s26, s57, s58
	v_lshl_add_u64 v[160:161], s[24:25], 0, v[144:145]
	s_add_i32 m0, s37, 0xc000
	ds_read_b128 v[186:189], v167
	ds_read_b128 v[190:193], v167 offset:1024
	ds_read_b128 v[194:197], v167 offset:2048
	ds_read_b128 v[200:203], v167 offset:3072
	ds_read_b128 v[204:207], v167 offset:4096
	ds_read_b128 v[208:211], v167 offset:5120
	ds_read_b128 v[212:215], v167 offset:6144
	ds_read_b128 v[216:219], v167 offset:7168
	global_load_lds_dwordx4 v[160:161], off
	v_lshl_add_u64 v[160:161], s[24:25], 0, v[146:147]
	s_add_i32 m0, s37, 0xe000
	s_nop 0
	global_load_lds_dwordx4 v[160:161], off
	s_sleep 1
	s_waitcnt vmcnt(8)
	s_waitcnt lgkmcnt(0)
	s_barrier
	s_setprio 1
	s_waitcnt lgkmcnt(0)
	v_mfma_f32_16x16x32_bf16 v[124:127], v[128:131], v[186:189], v[124:127]
	v_mfma_f32_16x16x32_bf16 v[120:123], v[152:155], v[186:189], v[120:123]
	v_mfma_f32_16x16x32_bf16 v[108:111], v[128:131], v[194:197], v[108:111]
	v_mfma_f32_16x16x32_bf16 v[104:107], v[152:155], v[194:197], v[104:107]
	v_mfma_f32_16x16x32_bf16 v[92:95], v[128:131], v[204:207], v[92:95]
	v_mfma_f32_16x16x32_bf16 v[88:91], v[152:155], v[204:207], v[88:91]
	v_mfma_f32_16x16x32_bf16 v[76:79], v[128:131], v[212:215], v[76:79]
	v_mfma_f32_16x16x32_bf16 v[72:75], v[152:155], v[212:215], v[72:75]
	v_mfma_f32_16x16x32_bf16 v[124:127], v[132:135], v[190:193], v[124:127]
	v_mfma_f32_16x16x32_bf16 v[120:123], v[156:159], v[190:193], v[120:123]
	v_mfma_f32_16x16x32_bf16 v[108:111], v[132:135], v[200:203], v[108:111]
	v_mfma_f32_16x16x32_bf16 v[104:107], v[156:159], v[200:203], v[104:107]
	v_mfma_f32_16x16x32_bf16 v[92:95], v[132:135], v[208:211], v[92:95]
	v_mfma_f32_16x16x32_bf16 v[88:91], v[156:159], v[208:211], v[88:91]
	v_mfma_f32_16x16x32_bf16 v[76:79], v[132:135], v[216:219], v[76:79]
	v_mfma_f32_16x16x32_bf16 v[72:75], v[156:159], v[216:219], v[72:75]
	s_setprio 0
	s_setprio 1
	v_mfma_f32_16x16x32_bf16 v[116:119], v[170:173], v[186:189], v[116:119]
	v_mfma_f32_16x16x32_bf16 v[112:115], v[178:181], v[186:189], v[112:115]
	v_mfma_f32_16x16x32_bf16 v[100:103], v[170:173], v[194:197], v[100:103]
	v_mfma_f32_16x16x32_bf16 v[96:99], v[178:181], v[194:197], v[96:99]
	v_mfma_f32_16x16x32_bf16 v[84:87], v[170:173], v[204:207], v[84:87]
	v_mfma_f32_16x16x32_bf16 v[80:83], v[178:181], v[204:207], v[80:83]
	v_mfma_f32_16x16x32_bf16 v[68:71], v[170:173], v[212:215], v[68:71]
	v_mfma_f32_16x16x32_bf16 v[64:67], v[178:181], v[212:215], v[64:67]
	v_mfma_f32_16x16x32_bf16 v[116:119], v[174:177], v[190:193], v[116:119]
	v_mfma_f32_16x16x32_bf16 v[112:115], v[182:185], v[190:193], v[112:115]
	v_mfma_f32_16x16x32_bf16 v[100:103], v[174:177], v[200:203], v[100:103]
	v_mfma_f32_16x16x32_bf16 v[96:99], v[182:185], v[200:203], v[96:99]
	v_mfma_f32_16x16x32_bf16 v[84:87], v[174:177], v[208:211], v[84:87]
	v_mfma_f32_16x16x32_bf16 v[80:83], v[182:185], v[208:211], v[80:83]
	v_mfma_f32_16x16x32_bf16 v[68:71], v[174:177], v[216:219], v[68:71]
	v_mfma_f32_16x16x32_bf16 v[64:67], v[182:185], v[216:219], v[64:67]
	s_setprio 0
	s_barrier
	s_add_i32 s61, s54, s34
	v_lshl_add_u64 v[160:161], s[26:27], 0, v[138:139]
	s_mov_b32 m0, s61
	ds_read_b128 v[186:189], v167 offset:16384
	ds_read_b128 v[190:193], v167 offset:17408
	ds_read_b128 v[194:197], v167 offset:18432
	ds_read_b128 v[200:203], v167 offset:19456
	ds_read_b128 v[204:207], v167 offset:20480
	ds_read_b128 v[208:211], v167 offset:21504
	ds_read_b128 v[212:215], v167 offset:22528
	ds_read_b128 v[216:219], v167 offset:23552
	global_load_lds_dwordx4 v[160:161], off
	s_add_i32 m0, s61, 0x2000
	s_add_u32 s62, s26, 0x40000
	v_lshl_add_u64 v[220:221], s[26:27], 0, v[142:143]
	s_addc_u32 s63, s27, 0
	s_add_i32 s61, s55, s34
	global_load_lds_dwordx4 v[220:221], off
	v_lshl_add_u64 v[222:223], s[62:63], 0, v[138:139]
	s_mov_b32 m0, s61
	v_lshl_add_u64 v[224:225], s[28:29], 0, v[140:141]
	global_load_lds_dwordx4 v[222:223], off
	v_lshl_add_u64 v[222:223], s[62:63], 0, v[142:143]
	s_add_i32 m0, s61, 0x2000
	s_nop 0
	global_load_lds_dwordx4 v[222:223], off
	v_lshl_add_u64 v[222:223], s[28:29], 0, v[136:137]
	s_mov_b32 m0, s37
	s_nop 0
	global_load_lds_dwordx4 v[222:223], off
	s_mov_b32 m0, s38
	s_nop 0
	global_load_lds_dwordx4 v[224:225], off
	s_sleep 1
	s_waitcnt vmcnt(8)
	s_waitcnt lgkmcnt(0)
	s_barrier
; #define PG8_STAGE(bufoff, gbase, voff) do { _Pragma("unroll") for (int _i = 0; _i < 2; ++_i) \
;         __builtin_amdgcn_global_load_lds((const unsigned*)((const char*)(gbase) + (voff)[_i]), (PG8_LAS unsigned*)(lds + (bufoff) + ldsw + _i * 8192), 16, 0, 0); } while (0)
; #define PG8_LDA(dst, b, h) do { _Pragma("unroll") for (int m = 0; m < 4; ++m) _Pragma("unroll") for (int k = 0; k < 2; ++k) dst[m][k] = *(const PG8_LAS bf16x8*)(lds + PG8_SA(b, h) + aoff + m * 2048 + k * 1024); } while (0)
; #define PG8_LDB(dst, b, h) do { _Pragma("unroll") for (int n = 0; n < 2; ++n) _Pragma("unroll") for (int k = 0; k < 2; ++k) dst[n][k] = *(const PG8_LAS bf16x8*)(lds + PG8_SB(b, h) + boff + n * 2048 + k * 1024); } while (0)
; #define PG8_MMA(ai, bj, At, Bt) do { __builtin_amdgcn_s_setprio(1); _Pragma("unroll") for (int m = 0; m < 4; ++m) _Pragma("unroll") for (int n = 0; n < 2; ++n) _Pragma("unroll") for (int k = 0; k < 2; ++k) \
;         acc[ai][bj][m][n] = __builtin_amdgcn_mfma_f32_16x16x32_bf16(Bt[n][k], At[m][k], acc[ai][bj][m][n], 0, 0, 0); __builtin_amdgcn_s_setprio(0); } while (0)
; #define PG8_WAIT_V(n) asm volatile("s_waitcnt vmcnt(" #n ")" ::: "memory")
; #define PG8_WAIT_L(n) asm volatile("s_waitcnt lgkmcnt(" #n ")" ::: "memory")
; #define PG8_BAR __builtin_amdgcn_s_barrier()
; #define PG8_SCHED __builtin_amdgcn_sched_barrier(0)
; template <class Epi, class Sched, bool ALIGN_EPI = false, bool SP2 = false>
; __device__ __forceinline__ void gemm_phase(PG8_LAS unsigned char* lds, const Gemm g, const Sched& S, const Epi& E) {
;     ...
;             PG8_WAIT_V(8); PG8_WAIT_L(0); PG8_BAR; PG8_MMA(1, 0, At, B0); PG8_MMA(1, 1, At, B1); PG8_BAR; PG8_SCHED;
;             PG8_LDB(B0, 1, 0); PG8_LDB(B1, 1, 1); PG8_SCHED; PG8_LDA(At, 1, 0); PG8_STAGE(PG8_SA(0, 1), a2 + hstep, voffA);
;             PG8_WAIT_V(8); PG8_WAIT_L(0); PG8_BAR; PG8_MMA(0, 0, At, B0); PG8_MMA(0, 1, At, B1); PG8_BAR; PG8_SCHED;
	s_setprio 1
	s_waitcnt lgkmcnt(0)
	v_mfma_f32_16x16x32_bf16 v[60:63], v[128:131], v[186:189], v[60:63]
	v_mfma_f32_16x16x32_bf16 v[56:59], v[152:155], v[186:189], v[56:59]
	v_mfma_f32_16x16x32_bf16 v[44:47], v[128:131], v[194:197], v[44:47]
	v_mfma_f32_16x16x32_bf16 v[40:43], v[152:155], v[194:197], v[40:43]
	v_mfma_f32_16x16x32_bf16 v[28:31], v[128:131], v[204:207], v[28:31]
	v_mfma_f32_16x16x32_bf16 v[24:27], v[152:155], v[204:207], v[24:27]
	v_mfma_f32_16x16x32_bf16 v[12:15], v[128:131], v[212:215], v[12:15]
	v_mfma_f32_16x16x32_bf16 v[8:11], v[152:155], v[212:215], v[8:11]
	v_mfma_f32_16x16x32_bf16 v[60:63], v[132:135], v[190:193], v[60:63]
	v_mfma_f32_16x16x32_bf16 v[56:59], v[156:159], v[190:193], v[56:59]
	v_mfma_f32_16x16x32_bf16 v[44:47], v[132:135], v[200:203], v[44:47]
	v_mfma_f32_16x16x32_bf16 v[40:43], v[156:159], v[200:203], v[40:43]
	v_mfma_f32_16x16x32_bf16 v[28:31], v[132:135], v[208:211], v[28:31]
	v_mfma_f32_16x16x32_bf16 v[24:27], v[156:159], v[208:211], v[24:27]
	v_mfma_f32_16x16x32_bf16 v[12:15], v[132:135], v[216:219], v[12:15]
	v_mfma_f32_16x16x32_bf16 v[8:11], v[156:159], v[216:219], v[8:11]
	s_setprio 0
	s_setprio 1
	v_mfma_f32_16x16x32_bf16 v[52:55], v[170:173], v[186:189], v[52:55]
	v_mfma_f32_16x16x32_bf16 v[48:51], v[178:181], v[186:189], v[48:51]
	v_mfma_f32_16x16x32_bf16 v[36:39], v[170:173], v[194:197], v[36:39]
	v_mfma_f32_16x16x32_bf16 v[32:35], v[178:181], v[194:197], v[32:35]
	v_mfma_f32_16x16x32_bf16 v[20:23], v[170:173], v[204:207], v[20:23]
	v_mfma_f32_16x16x32_bf16 v[16:19], v[178:181], v[204:207], v[16:19]
	v_mfma_f32_16x16x32_bf16 v[4:7], v[170:173], v[212:215], v[4:7]
	v_mfma_f32_16x16x32_bf16 v[0:3], v[178:181], v[212:215], v[0:3]
	v_mfma_f32_16x16x32_bf16 v[52:55], v[174:177], v[190:193], v[52:55]
	v_mfma_f32_16x16x32_bf16 v[48:51], v[182:185], v[190:193], v[48:51]
	v_mfma_f32_16x16x32_bf16 v[36:39], v[174:177], v[200:203], v[36:39]
	v_mfma_f32_16x16x32_bf16 v[32:35], v[182:185], v[200:203], v[32:35]
	v_mfma_f32_16x16x32_bf16 v[20:23], v[174:177], v[208:211], v[20:23]
	v_mfma_f32_16x16x32_bf16 v[16:19], v[182:185], v[208:211], v[16:19]
	v_mfma_f32_16x16x32_bf16 v[4:7], v[174:177], v[216:219], v[4:7]
	v_mfma_f32_16x16x32_bf16 v[0:3], v[182:185], v[216:219], v[0:3]
	s_setprio 0
	s_barrier
	s_add_i32 s61, 0, 0x18000
	s_add_i32 s62, 0, 0x1c000
	v_add_u32_e32 v156, s61, v163
	v_add_u32_e32 v169, s62, v163
	ds_read_b128 v[128:131], v156
	ds_read_b128 v[132:135], v156 offset:1024
	ds_read_b128 v[152:155], v156 offset:2048
	ds_read_b128 v[156:159], v156 offset:3072
	ds_read_b128 v[170:173], v169
	ds_read_b128 v[174:177], v169 offset:1024
	ds_read_b128 v[178:181], v169 offset:2048
	ds_read_b128 v[182:185], v169 offset:3072
	s_add_u32 s28, s28, 0x40000
	s_addc_u32 s29, s29, 0
	s_mov_b32 m0, s39
	v_lshl_add_u64 v[226:227], s[28:29], 0, v[136:137]
	ds_read_b128 v[186:189], v167 offset:32768
	ds_read_b128 v[190:193], v167 offset:33792
	ds_read_b128 v[194:197], v167 offset:34816
	ds_read_b128 v[200:203], v167 offset:35840
	ds_read_b128 v[204:207], v167 offset:36864
	ds_read_b128 v[208:211], v167 offset:37888
	ds_read_b128 v[212:215], v167 offset:38912
	ds_read_b128 v[216:219], v167 offset:39936
	global_load_lds_dwordx4 v[226:227], off
	v_lshl_add_u64 v[226:227], s[28:29], 0, v[140:141]
	s_mov_b32 m0, s40
	s_nop 0
	global_load_lds_dwordx4 v[226:227], off
	s_sleep 1
	s_waitcnt vmcnt(8)
	s_waitcnt lgkmcnt(0)
	s_barrier
	s_setprio 1
	s_waitcnt lgkmcnt(0)
	v_mfma_f32_16x16x32_bf16 v[124:127], v[128:131], v[186:189], v[124:127]
	v_mfma_f32_16x16x32_bf16 v[120:123], v[152:155], v[186:189], v[120:123]
	v_mfma_f32_16x16x32_bf16 v[108:111], v[128:131], v[194:197], v[108:111]
	v_mfma_f32_16x16x32_bf16 v[104:107], v[152:155], v[194:197], v[104:107]
	v_mfma_f32_16x16x32_bf16 v[92:95], v[128:131], v[204:207], v[92:95]
	v_mfma_f32_16x16x32_bf16 v[88:91], v[152:155], v[204:207], v[88:91]
	v_mfma_f32_16x16x32_bf16 v[76:79], v[128:131], v[212:215], v[76:79]
	v_mfma_f32_16x16x32_bf16 v[72:75], v[152:155], v[212:215], v[72:75]
	v_mfma_f32_16x16x32_bf16 v[124:127], v[132:135], v[190:193], v[124:127]
	v_mfma_f32_16x16x32_bf16 v[120:123], v[156:159], v[190:193], v[120:123]
	v_mfma_f32_16x16x32_bf16 v[108:111], v[132:135], v[200:203], v[108:111]
	v_mfma_f32_16x16x32_bf16 v[104:107], v[156:159], v[200:203], v[104:107]
	v_mfma_f32_16x16x32_bf16 v[92:95], v[132:135], v[208:211], v[92:95]
	v_mfma_f32_16x16x32_bf16 v[88:91], v[156:159], v[208:211], v[88:91]
	v_mfma_f32_16x16x32_bf16 v[76:79], v[132:135], v[216:219], v[76:79]
	v_mfma_f32_16x16x32_bf16 v[72:75], v[156:159], v[216:219], v[72:75]
	s_setprio 0
	s_setprio 1
	v_mfma_f32_16x16x32_bf16 v[116:119], v[170:173], v[186:189], v[116:119]
	v_mfma_f32_16x16x32_bf16 v[112:115], v[178:181], v[186:189], v[112:115]
	v_mfma_f32_16x16x32_bf16 v[100:103], v[170:173], v[194:197], v[100:103]
	v_mfma_f32_16x16x32_bf16 v[96:99], v[178:181], v[194:197], v[96:99]
	v_mfma_f32_16x16x32_bf16 v[84:87], v[170:173], v[204:207], v[84:87]
	v_mfma_f32_16x16x32_bf16 v[80:83], v[178:181], v[204:207], v[80:83]
	v_mfma_f32_16x16x32_bf16 v[68:71], v[170:173], v[212:215], v[68:71]
	v_mfma_f32_16x16x32_bf16 v[64:67], v[178:181], v[212:215], v[64:67]
	v_mfma_f32_16x16x32_bf16 v[116:119], v[174:177], v[190:193], v[116:119]
	v_mfma_f32_16x16x32_bf16 v[112:115], v[182:185], v[190:193], v[112:115]
	v_mfma_f32_16x16x32_bf16 v[100:103], v[174:177], v[200:203], v[100:103]
	v_mfma_f32_16x16x32_bf16 v[96:99], v[182:185], v[200:203], v[96:99]
	v_mfma_f32_16x16x32_bf16 v[84:87], v[174:177], v[208:211], v[84:87]
	v_mfma_f32_16x16x32_bf16 v[80:83], v[182:185], v[208:211], v[80:83]
	v_mfma_f32_16x16x32_bf16 v[68:71], v[174:177], v[216:219], v[68:71]
	v_mfma_f32_16x16x32_bf16 v[64:67], v[182:185], v[216:219], v[64:67]
	s_setprio 0
	s_barrier
; #define PG8_STAGE(bufoff, gbase, voff) do { _Pragma("unroll") for (int _i = 0; _i < 2; ++_i) \
;         __builtin_amdgcn_global_load_lds((const unsigned*)((const char*)(gbase) + (voff)[_i]), (PG8_LAS unsigned*)(lds + (bufoff) + ldsw + _i * 8192), 16, 0, 0); } while (0)
; #define PG8_LDA(dst, b, h) do { _Pragma("unroll") for (int m = 0; m < 4; ++m) _Pragma("unroll") for (int k = 0; k < 2; ++k) dst[m][k] = *(const PG8_LAS bf16x8*)(lds + PG8_SA(b, h) + aoff + m * 2048 + k * 1024); } while (0)
; #define PG8_MMA(ai, bj, At, Bt) do { __builtin_amdgcn_s_setprio(1); _Pragma("unroll") for (int m = 0; m < 4; ++m) _Pragma("unroll") for (int n = 0; n < 2; ++n) _Pragma("unroll") for (int k = 0; k < 2; ++k) \
;         acc[ai][bj][m][n] = __builtin_amdgcn_mfma_f32_16x16x32_bf16(Bt[n][k], At[m][k], acc[ai][bj][m][n], 0, 0, 0); __builtin_amdgcn_s_setprio(0); } while (0)
; #define PG8_WAIT_V(n) asm volatile("s_waitcnt vmcnt(" #n ")" ::: "memory")
; #define PG8_WAIT_L(n) asm volatile("s_waitcnt lgkmcnt(" #n ")" ::: "memory")
; #define PG8_BAR __builtin_amdgcn_s_barrier()
; #define PG8_SCHED __builtin_amdgcn_sched_barrier(0)
; template <class Epi, class Sched, bool ALIGN_EPI = false, bool SP2 = false>
; __device__ __forceinline__ void gemm_phase(PG8_LAS unsigned char* lds, const Gemm g, const Sched& S, const Epi& E) {
;     ...
;         for (int t = 0; t < nt; t += 2) {
;     ...
;             PG8_LDA(At, 1, 1); PG8_STAGE(PG8_SB(1, 0), b3, voffB); PG8_STAGE(PG8_SB(1, 1), b3 + hstep, voffB); PG8_STAGE(PG8_SA(1, 0), a3, voffA);
;             PG8_WAIT_V(8); PG8_WAIT_L(0); PG8_BAR; PG8_MMA(1, 0, At, B0); PG8_MMA(1, 1, At, B1); PG8_BAR; PG8_SCHED;
;     ...
;         if constexpr (ALIGN_EPI) { if (wr == 0) PG8_BAR; }
	s_add_i32 s28, s61, s34
	v_lshl_add_u64 v[160:161], v[160:161], 0, s[10:11]
	s_mov_b32 m0, s28
	ds_read_b128 v[186:189], v167 offset:49152
	ds_read_b128 v[190:193], v167 offset:50176
	ds_read_b128 v[194:197], v167 offset:51200
	ds_read_b128 v[200:203], v167 offset:52224
	ds_read_b128 v[204:207], v167 offset:53248
	ds_read_b128 v[208:211], v167 offset:54272
	ds_read_b128 v[212:215], v167 offset:55296
	ds_read_b128 v[216:219], v167 offset:56320
	global_load_lds_dwordx4 v[160:161], off
	s_add_i32 m0, s28, 0x2000
	s_add_u32 s26, s26, 0x40080
	v_lshl_add_u64 v[160:161], v[220:221], 0, s[10:11]
	s_addc_u32 s27, s27, 0
	s_add_i32 s28, s62, s34
	global_load_lds_dwordx4 v[160:161], off
	v_lshl_add_u64 v[160:161], s[26:27], 0, v[138:139]
	s_mov_b32 m0, s28
	s_nop 0
	global_load_lds_dwordx4 v[160:161], off
	v_lshl_add_u64 v[160:161], s[26:27], 0, v[142:143]
	s_add_i32 m0, s28, 0x2000
	s_nop 0
	global_load_lds_dwordx4 v[160:161], off
	v_lshl_add_u64 v[160:161], v[222:223], 0, s[10:11]
	s_mov_b32 m0, s42
	s_nop 0
	global_load_lds_dwordx4 v[160:161], off
	v_lshl_add_u64 v[160:161], v[224:225], 0, s[10:11]
	s_mov_b32 m0, s43
	s_nop 0
	global_load_lds_dwordx4 v[160:161], off
	s_sleep 1
	s_waitcnt vmcnt(8)
	s_waitcnt lgkmcnt(0)
	s_barrier
	s_setprio 1
	s_waitcnt lgkmcnt(0)
	v_mfma_f32_16x16x32_bf16 v[60:63], v[128:131], v[186:189], v[60:63]
	v_mfma_f32_16x16x32_bf16 v[56:59], v[152:155], v[186:189], v[56:59]
	v_mfma_f32_16x16x32_bf16 v[44:47], v[128:131], v[194:197], v[44:47]
	v_mfma_f32_16x16x32_bf16 v[40:43], v[152:155], v[194:197], v[40:43]
	v_mfma_f32_16x16x32_bf16 v[28:31], v[128:131], v[204:207], v[28:31]
	v_mfma_f32_16x16x32_bf16 v[24:27], v[152:155], v[204:207], v[24:27]
	v_mfma_f32_16x16x32_bf16 v[12:15], v[128:131], v[212:215], v[12:15]
	v_mfma_f32_16x16x32_bf16 v[8:11], v[152:155], v[212:215], v[8:11]
	v_mfma_f32_16x16x32_bf16 v[60:63], v[132:135], v[190:193], v[60:63]
	v_mfma_f32_16x16x32_bf16 v[56:59], v[156:159], v[190:193], v[56:59]
	v_mfma_f32_16x16x32_bf16 v[44:47], v[132:135], v[200:203], v[44:47]
	v_mfma_f32_16x16x32_bf16 v[40:43], v[156:159], v[200:203], v[40:43]
	v_mfma_f32_16x16x32_bf16 v[28:31], v[132:135], v[208:211], v[28:31]
	v_mfma_f32_16x16x32_bf16 v[24:27], v[156:159], v[208:211], v[24:27]
	v_mfma_f32_16x16x32_bf16 v[12:15], v[132:135], v[216:219], v[12:15]
	v_mfma_f32_16x16x32_bf16 v[8:11], v[156:159], v[216:219], v[8:11]
	s_setprio 0
	s_setprio 1
	v_mfma_f32_16x16x32_bf16 v[52:55], v[170:173], v[186:189], v[52:55]
	v_mfma_f32_16x16x32_bf16 v[48:51], v[178:181], v[186:189], v[48:51]
	v_mfma_f32_16x16x32_bf16 v[36:39], v[170:173], v[194:197], v[36:39]
	v_mfma_f32_16x16x32_bf16 v[32:35], v[178:181], v[194:197], v[32:35]
	v_mfma_f32_16x16x32_bf16 v[20:23], v[170:173], v[204:207], v[20:23]
	v_mfma_f32_16x16x32_bf16 v[16:19], v[178:181], v[204:207], v[16:19]
	v_mfma_f32_16x16x32_bf16 v[4:7], v[170:173], v[212:215], v[4:7]
	v_mfma_f32_16x16x32_bf16 v[0:3], v[178:181], v[212:215], v[0:3]
	v_mfma_f32_16x16x32_bf16 v[52:55], v[174:177], v[190:193], v[52:55]
	v_mfma_f32_16x16x32_bf16 v[48:51], v[182:185], v[190:193], v[48:51]
	v_mfma_f32_16x16x32_bf16 v[36:39], v[174:177], v[200:203], v[36:39]
	v_mfma_f32_16x16x32_bf16 v[32:35], v[182:185], v[200:203], v[32:35]
	v_mfma_f32_16x16x32_bf16 v[20:23], v[174:177], v[208:211], v[20:23]
	v_mfma_f32_16x16x32_bf16 v[16:19], v[182:185], v[208:211], v[16:19]
	v_mfma_f32_16x16x32_bf16 v[4:7], v[174:177], v[216:219], v[4:7]
	v_mfma_f32_16x16x32_bf16 v[0:3], v[182:185], v[216:219], v[0:3]
	s_setprio 0
	s_barrier
	s_add_i32 s60, s60, 2
	s_add_u32 s24, s24, 0x100
	s_addc_u32 s25, s25, 0
	s_add_u32 s58, s58, 0x100
	s_addc_u32 s59, s59, 0
	s_cmp_gt_u32 s60, 13
	s_cbranch_scc0 .LBB0_769
	s_and_b64 vcc, exec, s[12:13]
	s_cbranch_vccz .LBB0_772
	s_barrier

; #define PG8_STAGE(bufoff, gbase, voff) do { _Pragma("unroll") for (int _i = 0; _i < 2; ++_i) \
;         __builtin_amdgcn_global_load_lds((const unsigned*)((const char*)(gbase) + (voff)[_i]), (PG8_LAS unsigned*)(lds + (bufoff) + ldsw + _i * 8192), 16, 0, 0); } while (0)
; #define PG8_LDA(dst, b, h) do { _Pragma("unroll") for (int m = 0; m < 4; ++m) _Pragma("unroll") for (int k = 0; k < 2; ++k) dst[m][k] = *(const PG8_LAS bf16x8*)(lds + PG8_SA(b, h) + aoff + m * 2048 + k * 1024); } while (0)
; #define PG8_LDB(dst, b, h) do { _Pragma("unroll") for (int n = 0; n < 2; ++n) _Pragma("unroll") for (int k = 0; k < 2; ++k) dst[n][k] = *(const PG8_LAS bf16x8*)(lds + PG8_SB(b, h) + boff + n * 2048 + k * 1024); } while (0)
; #define PG8_MMA(ai, bj, At, Bt) do { __builtin_amdgcn_s_setprio(1); _Pragma("unroll") for (int m = 0; m < 4; ++m) _Pragma("unroll") for (int n = 0; n < 2; ++n) _Pragma("unroll") for (int k = 0; k < 2; ++k) \
;         acc[ai][bj][m][n] = __builtin_amdgcn_mfma_f32_16x16x32_bf16(Bt[n][k], At[m][k], acc[ai][bj][m][n], 0, 0, 0); __builtin_amdgcn_s_setprio(0); } while (0)
; #define PG8_WAIT_V(n) asm volatile("s_waitcnt vmcnt(" #n ")" ::: "memory")
; #define PG8_BAR __builtin_amdgcn_s_barrier()
; template <class Epi, class Sched, bool ALIGN_EPI = false, bool SP2 = false>
; __device__ __forceinline__ void gemm_phase(PG8_LAS unsigned char* lds, const Gemm g, const Sched& S, const Epi& E) {
;     ...
;         for (int t = 0; t < nt; t += 2) {
;             const bool last = (t == nt - 2);
;             const char* a1 = cA + (size_t)(t + 1) * kstep;
;             const char* a2 = last ? nA : cA + (size_t)(t + 2) * kstep; const char* b2 = last ? nB : cB + (size_t)(t + 2) * kstep;
;             const char* a3 = a2 + kstep; const char* b3 = b2 + kstep;
;             if (last && has_next) S.a_ready(nxt);
;             if constexpr (SP2) {
;             PG8_LDB(B0, 0, 0); PG8_LDB(B1, 0, 1); PG8_SCHED; PG8_LDA(At, 0, 0); PG8_STAGE(PG8_SA(1, 1), a1 + hstep, voffA);
;             PG8_WAIT_V(8); PG8_WAIT_L(0); PG8_BAR; PG8_MMA(0, 0, At, B0); PG8_MMA(0, 1, At, B1); PG8_BAR; PG8_SCHED;
;             PG8_LDA(At, 0, 1); PG8_STAGE(PG8_SB(0, 0), b2, voffB); PG8_STAGE(PG8_SB(0, 1), b2 + hstep, voffB); PG8_STAGE(PG8_SA(0, 0), a2, voffA);
;             PG8_WAIT_V(8); PG8_WAIT_L(0); PG8_BAR; PG8_MMA(1, 0, At, B0); PG8_MMA(1, 1, At, B1); PG8_BAR; PG8_SCHED;
.LBB0_856:
	ds_read_b128 v[146:149], v167
	ds_read_b128 v[150:153], v167 offset:1024
	ds_read_b128 v[178:181], v167 offset:2048
	ds_read_b128 v[182:185], v167 offset:3072
	ds_read_b128 v[186:189], v171
	ds_read_b128 v[190:193], v171 offset:1024
	ds_read_b128 v[194:197], v171 offset:2048
	ds_read_b128 v[200:203], v171 offset:3072
	s_add_u32 s22, s20, 0xfffc0080
	s_addc_u32 s23, s21, -1
	s_cmp_eq_u32 s55, 12
	s_cselect_b32 s25, s13, s23
	s_cselect_b32 s24, s51, s22
	s_cselect_b32 s23, s11, s54
	s_cselect_b32 s22, s52, s53
	v_lshl_add_u64 v[156:157], s[20:21], 0, v[138:139]
	s_add_i32 m0, s19, 0xc000
	ds_read_b128 v[204:207], v174
	ds_read_b128 v[208:211], v174 offset:1024
	ds_read_b128 v[212:215], v174 offset:2048
	ds_read_b128 v[216:219], v174 offset:3072
	ds_read_b128 v[220:223], v174 offset:4096
	ds_read_b128 v[224:227], v174 offset:5120
	ds_read_b128 v[228:231], v174 offset:6144
	ds_read_b128 v[232:235], v174 offset:7168
	global_load_lds_dwordx4 v[156:157], off
	v_lshl_add_u64 v[156:157], s[20:21], 0, v[140:141]
	s_add_i32 m0, s19, 0xe000
	s_nop 0
	global_load_lds_dwordx4 v[156:157], off
	s_sleep 1
	s_waitcnt vmcnt(8)
	s_waitcnt lgkmcnt(0)
	s_barrier
	s_setprio 1
	s_waitcnt lgkmcnt(0)
	v_mfma_f32_16x16x32_bf16 v[124:127], v[146:149], v[204:207], v[124:127]
	v_mfma_f32_16x16x32_bf16 v[120:123], v[178:181], v[204:207], v[120:123]
	v_mfma_f32_16x16x32_bf16 v[108:111], v[146:149], v[212:215], v[108:111]
	v_mfma_f32_16x16x32_bf16 v[104:107], v[178:181], v[212:215], v[104:107]
	v_mfma_f32_16x16x32_bf16 v[92:95], v[146:149], v[220:223], v[92:95]
	v_mfma_f32_16x16x32_bf16 v[88:91], v[178:181], v[220:223], v[88:91]
	v_mfma_f32_16x16x32_bf16 v[76:79], v[146:149], v[228:231], v[76:79]
	v_mfma_f32_16x16x32_bf16 v[72:75], v[178:181], v[228:231], v[72:75]
	v_mfma_f32_16x16x32_bf16 v[124:127], v[150:153], v[208:211], v[124:127]
	v_mfma_f32_16x16x32_bf16 v[120:123], v[182:185], v[208:211], v[120:123]
	v_mfma_f32_16x16x32_bf16 v[108:111], v[150:153], v[216:219], v[108:111]
	v_mfma_f32_16x16x32_bf16 v[104:107], v[182:185], v[216:219], v[104:107]
	v_mfma_f32_16x16x32_bf16 v[92:95], v[150:153], v[224:227], v[92:95]
	v_mfma_f32_16x16x32_bf16 v[88:91], v[182:185], v[224:227], v[88:91]
	v_mfma_f32_16x16x32_bf16 v[76:79], v[150:153], v[232:235], v[76:79]
	v_mfma_f32_16x16x32_bf16 v[72:75], v[182:185], v[232:235], v[72:75]
	s_setprio 0
	s_setprio 1
	v_mfma_f32_16x16x32_bf16 v[116:119], v[186:189], v[204:207], v[116:119]
	v_mfma_f32_16x16x32_bf16 v[112:115], v[194:197], v[204:207], v[112:115]
	v_mfma_f32_16x16x32_bf16 v[100:103], v[186:189], v[212:215], v[100:103]
	v_mfma_f32_16x16x32_bf16 v[96:99], v[194:197], v[212:215], v[96:99]
	v_mfma_f32_16x16x32_bf16 v[84:87], v[186:189], v[220:223], v[84:87]
	v_mfma_f32_16x16x32_bf16 v[80:83], v[194:197], v[220:223], v[80:83]
	v_mfma_f32_16x16x32_bf16 v[68:71], v[186:189], v[228:231], v[68:71]
	v_mfma_f32_16x16x32_bf16 v[64:67], v[194:197], v[228:231], v[64:67]
	v_mfma_f32_16x16x32_bf16 v[116:119], v[190:193], v[208:211], v[116:119]
	v_mfma_f32_16x16x32_bf16 v[112:115], v[200:203], v[208:211], v[112:115]
	v_mfma_f32_16x16x32_bf16 v[100:103], v[190:193], v[216:219], v[100:103]
	v_mfma_f32_16x16x32_bf16 v[96:99], v[200:203], v[216:219], v[96:99]
	v_mfma_f32_16x16x32_bf16 v[84:87], v[190:193], v[224:227], v[84:87]
	v_mfma_f32_16x16x32_bf16 v[80:83], v[200:203], v[224:227], v[80:83]
	v_mfma_f32_16x16x32_bf16 v[68:71], v[190:193], v[232:235], v[68:71]
	v_mfma_f32_16x16x32_bf16 v[64:67], v[200:203], v[232:235], v[64:67]
	s_setprio 0
	s_barrier
	s_add_i32 s56, s41, s28
	v_lshl_add_u64 v[156:157], s[22:23], 0, v[132:133]
	s_mov_b32 m0, s56
	ds_read_b128 v[204:207], v174 offset:16384
	ds_read_b128 v[208:211], v174 offset:17408
	ds_read_b128 v[212:215], v174 offset:18432
	ds_read_b128 v[216:219], v174 offset:19456
	ds_read_b128 v[220:223], v174 offset:20480
	ds_read_b128 v[224:227], v174 offset:21504
	ds_read_b128 v[228:231], v174 offset:22528
	ds_read_b128 v[232:235], v174 offset:23552
	global_load_lds_dwordx4 v[156:157], off
	s_add_i32 m0, s56, 0x2000
	s_add_u32 s56, s22, 0x40000
	v_lshl_add_u64 v[160:161], s[22:23], 0, v[128:129]
	s_addc_u32 s57, s23, 0
	s_add_i32 s58, s42, s28
	global_load_lds_dwordx4 v[160:161], off
	v_lshl_add_u64 v[164:165], s[56:57], 0, v[132:133]
	s_mov_b32 m0, s58
	v_lshl_add_u64 v[168:169], s[24:25], 0, v[130:131]
	global_load_lds_dwordx4 v[164:165], off
	v_lshl_add_u64 v[164:165], s[56:57], 0, v[128:129]
	s_add_i32 m0, s58, 0x2000
	s_nop 0
	global_load_lds_dwordx4 v[164:165], off
	v_lshl_add_u64 v[164:165], s[24:25], 0, v[134:135]
	s_mov_b32 m0, s19
	s_nop 0
	global_load_lds_dwordx4 v[164:165], off
	s_mov_b32 m0, s31
	s_nop 0
	global_load_lds_dwordx4 v[168:169], off
	s_sleep 1
	s_waitcnt vmcnt(8)
	s_waitcnt lgkmcnt(0)
	s_barrier
; #define PG8_STAGE(bufoff, gbase, voff) do { _Pragma("unroll") for (int _i = 0; _i < 2; ++_i) \
;         __builtin_amdgcn_global_load_lds((const unsigned*)((const char*)(gbase) + (voff)[_i]), (PG8_LAS unsigned*)(lds + (bufoff) + ldsw + _i * 8192), 16, 0, 0); } while (0)
; #define PG8_LDA(dst, b, h) do { _Pragma("unroll") for (int m = 0; m < 4; ++m) _Pragma("unroll") for (int k = 0; k < 2; ++k) dst[m][k] = *(const PG8_LAS bf16x8*)(lds + PG8_SA(b, h) + aoff + m * 2048 + k * 1024); } while (0)
; #define PG8_LDB(dst, b, h) do { _Pragma("unroll") for (int n = 0; n < 2; ++n) _Pragma("unroll") for (int k = 0; k < 2; ++k) dst[n][k] = *(const PG8_LAS bf16x8*)(lds + PG8_SB(b, h) + boff + n * 2048 + k * 1024); } while (0)
; #define PG8_MMA(ai, bj, At, Bt) do { __builtin_amdgcn_s_setprio(1); _Pragma("unroll") for (int m = 0; m < 4; ++m) _Pragma("unroll") for (int n = 0; n < 2; ++n) _Pragma("unroll") for (int k = 0; k < 2; ++k) \
;         acc[ai][bj][m][n] = __builtin_amdgcn_mfma_f32_16x16x32_bf16(Bt[n][k], At[m][k], acc[ai][bj][m][n], 0, 0, 0); __builtin_amdgcn_s_setprio(0); } while (0)
; #define PG8_WAIT_V(n) asm volatile("s_waitcnt vmcnt(" #n ")" ::: "memory")
; #define PG8_WAIT_L(n) asm volatile("s_waitcnt lgkmcnt(" #n ")" ::: "memory")
; #define PG8_BAR __builtin_amdgcn_s_barrier()
; #define PG8_SCHED __builtin_amdgcn_sched_barrier(0)
; template <class Epi, class Sched, bool ALIGN_EPI = false, bool SP2 = false>
; __device__ __forceinline__ void gemm_phase(PG8_LAS unsigned char* lds, const Gemm g, const Sched& S, const Epi& E) {
;     ...
;             PG8_WAIT_V(8); PG8_WAIT_L(0); PG8_BAR; PG8_MMA(1, 0, At, B0); PG8_MMA(1, 1, At, B1); PG8_BAR; PG8_SCHED;
;             PG8_LDB(B0, 1, 0); PG8_LDB(B1, 1, 1); PG8_SCHED; PG8_LDA(At, 1, 0); PG8_STAGE(PG8_SA(0, 1), a2 + hstep, voffA);
;             PG8_WAIT_V(8); PG8_WAIT_L(0); PG8_BAR; PG8_MMA(0, 0, At, B0); PG8_MMA(0, 1, At, B1); PG8_BAR; PG8_SCHED;
	s_setprio 1
	s_waitcnt lgkmcnt(0)
	v_mfma_f32_16x16x32_bf16 v[60:63], v[146:149], v[204:207], v[60:63]
	v_mfma_f32_16x16x32_bf16 v[56:59], v[178:181], v[204:207], v[56:59]
	v_mfma_f32_16x16x32_bf16 v[44:47], v[146:149], v[212:215], v[44:47]
	v_mfma_f32_16x16x32_bf16 v[40:43], v[178:181], v[212:215], v[40:43]
	v_mfma_f32_16x16x32_bf16 v[28:31], v[146:149], v[220:223], v[28:31]
	v_mfma_f32_16x16x32_bf16 v[24:27], v[178:181], v[220:223], v[24:27]
	v_mfma_f32_16x16x32_bf16 v[12:15], v[146:149], v[228:231], v[12:15]
	v_mfma_f32_16x16x32_bf16 v[8:11], v[178:181], v[228:231], v[8:11]
	v_mfma_f32_16x16x32_bf16 v[60:63], v[150:153], v[208:211], v[60:63]
	v_mfma_f32_16x16x32_bf16 v[56:59], v[182:185], v[208:211], v[56:59]
	v_mfma_f32_16x16x32_bf16 v[44:47], v[150:153], v[216:219], v[44:47]
	v_mfma_f32_16x16x32_bf16 v[40:43], v[182:185], v[216:219], v[40:43]
	v_mfma_f32_16x16x32_bf16 v[28:31], v[150:153], v[224:227], v[28:31]
	v_mfma_f32_16x16x32_bf16 v[24:27], v[182:185], v[224:227], v[24:27]
	v_mfma_f32_16x16x32_bf16 v[12:15], v[150:153], v[232:235], v[12:15]
	v_mfma_f32_16x16x32_bf16 v[8:11], v[182:185], v[232:235], v[8:11]
	s_setprio 0
	s_setprio 1
	v_mfma_f32_16x16x32_bf16 v[52:55], v[186:189], v[204:207], v[52:55]
	v_mfma_f32_16x16x32_bf16 v[48:51], v[194:197], v[204:207], v[48:51]
	v_mfma_f32_16x16x32_bf16 v[36:39], v[186:189], v[212:215], v[36:39]
	v_mfma_f32_16x16x32_bf16 v[32:35], v[194:197], v[212:215], v[32:35]
	v_mfma_f32_16x16x32_bf16 v[20:23], v[186:189], v[220:223], v[20:23]
	v_mfma_f32_16x16x32_bf16 v[16:19], v[194:197], v[220:223], v[16:19]
	v_mfma_f32_16x16x32_bf16 v[4:7], v[186:189], v[228:231], v[4:7]
	v_mfma_f32_16x16x32_bf16 v[0:3], v[194:197], v[228:231], v[0:3]
	v_mfma_f32_16x16x32_bf16 v[52:55], v[190:193], v[208:211], v[52:55]
	v_mfma_f32_16x16x32_bf16 v[48:51], v[200:203], v[208:211], v[48:51]
	v_mfma_f32_16x16x32_bf16 v[36:39], v[190:193], v[216:219], v[36:39]
	v_mfma_f32_16x16x32_bf16 v[32:35], v[200:203], v[216:219], v[32:35]
	v_mfma_f32_16x16x32_bf16 v[20:23], v[190:193], v[224:227], v[20:23]
	v_mfma_f32_16x16x32_bf16 v[16:19], v[200:203], v[224:227], v[16:19]
	v_mfma_f32_16x16x32_bf16 v[4:7], v[190:193], v[232:235], v[4:7]
	v_mfma_f32_16x16x32_bf16 v[0:3], v[200:203], v[232:235], v[0:3]
	s_setprio 0
	s_barrier
	s_add_i32 s56, 0, 0x18000
	v_add_u32_e32 v154, s56, v159
	s_add_i32 s57, 0, 0x1c000
	ds_read_b128 v[146:149], v154
	ds_read_b128 v[150:153], v154 offset:1024
	ds_read_b128 v[178:181], v154 offset:2048
	ds_read_b128 v[182:185], v154 offset:3072
	v_add_u32_e32 v154, s57, v159
	ds_read_b128 v[186:189], v154
	ds_read_b128 v[190:193], v154 offset:1024
	ds_read_b128 v[194:197], v154 offset:2048
	ds_read_b128 v[200:203], v154 offset:3072
	s_add_u32 s24, s24, 0x40000
	s_addc_u32 s25, s25, 0
	s_mov_b32 m0, s34
	v_lshl_add_u64 v[172:173], s[24:25], 0, v[134:135]
	ds_read_b128 v[204:207], v174 offset:32768
	ds_read_b128 v[208:211], v174 offset:33792
	ds_read_b128 v[212:215], v174 offset:34816
	ds_read_b128 v[216:219], v174 offset:35840
	ds_read_b128 v[220:223], v174 offset:36864
	ds_read_b128 v[224:227], v174 offset:37888
	ds_read_b128 v[228:231], v174 offset:38912
	ds_read_b128 v[232:235], v174 offset:39936
	global_load_lds_dwordx4 v[172:173], off
	v_lshl_add_u64 v[172:173], s[24:25], 0, v[130:131]
	s_mov_b32 m0, s35
	s_nop 0
	global_load_lds_dwordx4 v[172:173], off
	s_sleep 1
	s_waitcnt vmcnt(8)
	s_waitcnt lgkmcnt(0)
	s_barrier
	s_setprio 1
	s_waitcnt lgkmcnt(0)
	v_mfma_f32_16x16x32_bf16 v[124:127], v[146:149], v[204:207], v[124:127]
	v_mfma_f32_16x16x32_bf16 v[120:123], v[178:181], v[204:207], v[120:123]
	v_mfma_f32_16x16x32_bf16 v[108:111], v[146:149], v[212:215], v[108:111]
	v_mfma_f32_16x16x32_bf16 v[104:107], v[178:181], v[212:215], v[104:107]
	v_mfma_f32_16x16x32_bf16 v[92:95], v[146:149], v[220:223], v[92:95]
	v_mfma_f32_16x16x32_bf16 v[88:91], v[178:181], v[220:223], v[88:91]
	v_mfma_f32_16x16x32_bf16 v[76:79], v[146:149], v[228:231], v[76:79]
	v_mfma_f32_16x16x32_bf16 v[72:75], v[178:181], v[228:231], v[72:75]
	v_mfma_f32_16x16x32_bf16 v[124:127], v[150:153], v[208:211], v[124:127]
	v_mfma_f32_16x16x32_bf16 v[120:123], v[182:185], v[208:211], v[120:123]
	v_mfma_f32_16x16x32_bf16 v[108:111], v[150:153], v[216:219], v[108:111]
	v_mfma_f32_16x16x32_bf16 v[104:107], v[182:185], v[216:219], v[104:107]
	v_mfma_f32_16x16x32_bf16 v[92:95], v[150:153], v[224:227], v[92:95]
	v_mfma_f32_16x16x32_bf16 v[88:91], v[182:185], v[224:227], v[88:91]
	v_mfma_f32_16x16x32_bf16 v[76:79], v[150:153], v[232:235], v[76:79]
	v_mfma_f32_16x16x32_bf16 v[72:75], v[182:185], v[232:235], v[72:75]
	s_setprio 0
	s_setprio 1
	v_mfma_f32_16x16x32_bf16 v[116:119], v[186:189], v[204:207], v[116:119]
	v_mfma_f32_16x16x32_bf16 v[112:115], v[194:197], v[204:207], v[112:115]
	v_mfma_f32_16x16x32_bf16 v[100:103], v[186:189], v[212:215], v[100:103]
	v_mfma_f32_16x16x32_bf16 v[96:99], v[194:197], v[212:215], v[96:99]
	v_mfma_f32_16x16x32_bf16 v[84:87], v[186:189], v[220:223], v[84:87]
	v_mfma_f32_16x16x32_bf16 v[80:83], v[194:197], v[220:223], v[80:83]
	v_mfma_f32_16x16x32_bf16 v[68:71], v[186:189], v[228:231], v[68:71]
	v_mfma_f32_16x16x32_bf16 v[64:67], v[194:197], v[228:231], v[64:67]
	v_mfma_f32_16x16x32_bf16 v[116:119], v[190:193], v[208:211], v[116:119]
	v_mfma_f32_16x16x32_bf16 v[112:115], v[200:203], v[208:211], v[112:115]
	v_mfma_f32_16x16x32_bf16 v[100:103], v[190:193], v[216:219], v[100:103]
	v_mfma_f32_16x16x32_bf16 v[96:99], v[200:203], v[216:219], v[96:99]
	v_mfma_f32_16x16x32_bf16 v[84:87], v[190:193], v[224:227], v[84:87]
	v_mfma_f32_16x16x32_bf16 v[80:83], v[200:203], v[224:227], v[80:83]
	v_mfma_f32_16x16x32_bf16 v[68:71], v[190:193], v[232:235], v[68:71]
	v_mfma_f32_16x16x32_bf16 v[64:67], v[200:203], v[232:235], v[64:67]
	s_setprio 0
	s_barrier
; #define PG8_STAGE(bufoff, gbase, voff) do { _Pragma("unroll") for (int _i = 0; _i < 2; ++_i) \
;         __builtin_amdgcn_global_load_lds((const unsigned*)((const char*)(gbase) + (voff)[_i]), (PG8_LAS unsigned*)(lds + (bufoff) + ldsw + _i * 8192), 16, 0, 0); } while (0)
; #define PG8_LDA(dst, b, h) do { _Pragma("unroll") for (int m = 0; m < 4; ++m) _Pragma("unroll") for (int k = 0; k < 2; ++k) dst[m][k] = *(const PG8_LAS bf16x8*)(lds + PG8_SA(b, h) + aoff + m * 2048 + k * 1024); } while (0)
; #define PG8_MMA(ai, bj, At, Bt) do { __builtin_amdgcn_s_setprio(1); _Pragma("unroll") for (int m = 0; m < 4; ++m) _Pragma("unroll") for (int n = 0; n < 2; ++n) _Pragma("unroll") for (int k = 0; k < 2; ++k) \
;         acc[ai][bj][m][n] = __builtin_amdgcn_mfma_f32_16x16x32_bf16(Bt[n][k], At[m][k], acc[ai][bj][m][n], 0, 0, 0); __builtin_amdgcn_s_setprio(0); } while (0)
; #define PG8_WAIT_V(n) asm volatile("s_waitcnt vmcnt(" #n ")" ::: "memory")
; #define PG8_WAIT_L(n) asm volatile("s_waitcnt lgkmcnt(" #n ")" ::: "memory")
; #define PG8_BAR __builtin_amdgcn_s_barrier()
; #define PG8_SCHED __builtin_amdgcn_sched_barrier(0)
; template <class Epi, class Sched, bool ALIGN_EPI = false, bool SP2 = false>
; __device__ __forceinline__ void gemm_phase(PG8_LAS unsigned char* lds, const Gemm g, const Sched& S, const Epi& E) {
;     ...
;         for (int t = 0; t < nt; t += 2) {
;     ...
;             PG8_LDA(At, 1, 1); PG8_STAGE(PG8_SB(1, 0), b3, voffB); PG8_STAGE(PG8_SB(1, 1), b3 + hstep, voffB); PG8_STAGE(PG8_SA(1, 0), a3, voffA);
;             PG8_WAIT_V(8); PG8_WAIT_L(0); PG8_BAR; PG8_MMA(1, 0, At, B0); PG8_MMA(1, 1, At, B1); PG8_BAR; PG8_SCHED;
;     ...
;         if constexpr (ALIGN_EPI) { if (wr == 0) PG8_BAR; }
	s_add_i32 s24, s56, s28
	v_lshl_add_u64 v[156:157], v[156:157], 0, s[6:7]
	s_mov_b32 m0, s24
	ds_read_b128 v[204:207], v174 offset:49152
	ds_read_b128 v[208:211], v174 offset:50176
	ds_read_b128 v[212:215], v174 offset:51200
	ds_read_b128 v[216:219], v174 offset:52224
	ds_read_b128 v[220:223], v174 offset:53248
	ds_read_b128 v[224:227], v174 offset:54272
	ds_read_b128 v[228:231], v174 offset:55296
	ds_read_b128 v[232:235], v174 offset:56320
	global_load_lds_dwordx4 v[156:157], off
	s_add_i32 m0, s24, 0x2000
	s_add_u32 s22, s22, 0x40080
	v_lshl_add_u64 v[156:157], v[160:161], 0, s[6:7]
	s_addc_u32 s23, s23, 0
	s_add_i32 s24, s57, s28
	global_load_lds_dwordx4 v[156:157], off
	v_lshl_add_u64 v[156:157], s[22:23], 0, v[132:133]
	s_mov_b32 m0, s24
	s_nop 0
	global_load_lds_dwordx4 v[156:157], off
	v_lshl_add_u64 v[156:157], s[22:23], 0, v[128:129]
	s_add_i32 m0, s24, 0x2000
	s_nop 0
	global_load_lds_dwordx4 v[156:157], off
	v_lshl_add_u64 v[156:157], v[164:165], 0, s[6:7]
	s_mov_b32 m0, s37
	s_nop 0
	global_load_lds_dwordx4 v[156:157], off
	v_lshl_add_u64 v[156:157], v[168:169], 0, s[6:7]
	s_mov_b32 m0, s38
	s_nop 0
	global_load_lds_dwordx4 v[156:157], off
	s_sleep 1
	s_waitcnt vmcnt(8)
	s_waitcnt lgkmcnt(0)
	s_barrier
	s_setprio 1
	s_waitcnt lgkmcnt(0)
	v_mfma_f32_16x16x32_bf16 v[60:63], v[146:149], v[204:207], v[60:63]
	v_mfma_f32_16x16x32_bf16 v[56:59], v[178:181], v[204:207], v[56:59]
	v_mfma_f32_16x16x32_bf16 v[44:47], v[146:149], v[212:215], v[44:47]
	v_mfma_f32_16x16x32_bf16 v[40:43], v[178:181], v[212:215], v[40:43]
	v_mfma_f32_16x16x32_bf16 v[28:31], v[146:149], v[220:223], v[28:31]
	v_mfma_f32_16x16x32_bf16 v[24:27], v[178:181], v[220:223], v[24:27]
	v_mfma_f32_16x16x32_bf16 v[12:15], v[146:149], v[228:231], v[12:15]
	v_mfma_f32_16x16x32_bf16 v[8:11], v[178:181], v[228:231], v[8:11]
	v_mfma_f32_16x16x32_bf16 v[60:63], v[150:153], v[208:211], v[60:63]
	v_mfma_f32_16x16x32_bf16 v[56:59], v[182:185], v[208:211], v[56:59]
	v_mfma_f32_16x16x32_bf16 v[44:47], v[150:153], v[216:219], v[44:47]
	v_mfma_f32_16x16x32_bf16 v[40:43], v[182:185], v[216:219], v[40:43]
	v_mfma_f32_16x16x32_bf16 v[28:31], v[150:153], v[224:227], v[28:31]
	v_mfma_f32_16x16x32_bf16 v[24:27], v[182:185], v[224:227], v[24:27]
	v_mfma_f32_16x16x32_bf16 v[12:15], v[150:153], v[232:235], v[12:15]
	v_mfma_f32_16x16x32_bf16 v[8:11], v[182:185], v[232:235], v[8:11]
	s_setprio 0
	s_setprio 1
	v_mfma_f32_16x16x32_bf16 v[52:55], v[186:189], v[204:207], v[52:55]
	v_mfma_f32_16x16x32_bf16 v[48:51], v[194:197], v[204:207], v[48:51]
	v_mfma_f32_16x16x32_bf16 v[36:39], v[186:189], v[212:215], v[36:39]
	v_mfma_f32_16x16x32_bf16 v[32:35], v[194:197], v[212:215], v[32:35]
	v_mfma_f32_16x16x32_bf16 v[20:23], v[186:189], v[220:223], v[20:23]
	v_mfma_f32_16x16x32_bf16 v[16:19], v[194:197], v[220:223], v[16:19]
	v_mfma_f32_16x16x32_bf16 v[4:7], v[186:189], v[228:231], v[4:7]
	v_mfma_f32_16x16x32_bf16 v[0:3], v[194:197], v[228:231], v[0:3]
	v_mfma_f32_16x16x32_bf16 v[52:55], v[190:193], v[208:211], v[52:55]
	v_mfma_f32_16x16x32_bf16 v[48:51], v[200:203], v[208:211], v[48:51]
	v_mfma_f32_16x16x32_bf16 v[36:39], v[190:193], v[216:219], v[36:39]
	v_mfma_f32_16x16x32_bf16 v[32:35], v[200:203], v[216:219], v[32:35]
	v_mfma_f32_16x16x32_bf16 v[20:23], v[190:193], v[224:227], v[20:23]
	v_mfma_f32_16x16x32_bf16 v[16:19], v[200:203], v[224:227], v[16:19]
	v_mfma_f32_16x16x32_bf16 v[4:7], v[190:193], v[232:235], v[4:7]
	v_mfma_f32_16x16x32_bf16 v[0:3], v[200:203], v[232:235], v[0:3]
	s_setprio 0
	s_barrier
	s_add_i32 s55, s55, 2
	s_add_u32 s20, s20, 0x100
	s_addc_u32 s21, s21, 0
	s_add_u32 s53, s53, 0x100
	s_addc_u32 s54, s54, 0
	s_cmp_gt_u32 s55, 13
	s_cbranch_scc0 .LBB0_856
	s_and_b64 vcc, exec, s[8:9]
	s_cbranch_vccz .LBB0_859
	s_barrier

; #define PG8_STAGE(bufoff, gbase, voff) do { _Pragma("unroll") for (int _i = 0; _i < 2; ++_i) \
;         __builtin_amdgcn_global_load_lds((const unsigned*)((const char*)(gbase) + (voff)[_i]), (PG8_LAS unsigned*)(lds + (bufoff) + ldsw + _i * 8192), 16, 0, 0); } while (0)
; #define PG8_LDA(dst, b, h) do { _Pragma("unroll") for (int m = 0; m < 4; ++m) _Pragma("unroll") for (int k = 0; k < 2; ++k) dst[m][k] = *(const PG8_LAS bf16x8*)(lds + PG8_SA(b, h) + aoff + m * 2048 + k * 1024); } while (0)
; #define PG8_LDB(dst, b, h) do { _Pragma("unroll") for (int n = 0; n < 2; ++n) _Pragma("unroll") for (int k = 0; k < 2; ++k) dst[n][k] = *(const PG8_LAS bf16x8*)(lds + PG8_SB(b, h) + boff + n * 2048 + k * 1024); } while (0)
; #define PG8_MMA(ai, bj, At, Bt) do { __builtin_amdgcn_s_setprio(1); _Pragma("unroll") for (int m = 0; m < 4; ++m) _Pragma("unroll") for (int n = 0; n < 2; ++n) _Pragma("unroll") for (int k = 0; k < 2; ++k) \
;         acc[ai][bj][m][n] = __builtin_amdgcn_mfma_f32_16x16x32_bf16(Bt[n][k], At[m][k], acc[ai][bj][m][n], 0, 0, 0); __builtin_amdgcn_s_setprio(0); } while (0)
; #define PG8_WAIT_V(n) asm volatile("s_waitcnt vmcnt(" #n ")" ::: "memory")
; #define PG8_BAR __builtin_amdgcn_s_barrier()
; template <class Epi, class Sched, bool ALIGN_EPI = false, bool SP2 = false>
; __device__ __forceinline__ void gemm_phase(PG8_LAS unsigned char* lds, const Gemm g, const Sched& S, const Epi& E) {
;     ...
;         for (int t = 0; t < nt; t += 2) {
;             const bool last = (t == nt - 2);
;             const char* a1 = cA + (size_t)(t + 1) * kstep;
;             const char* a2 = last ? nA : cA + (size_t)(t + 2) * kstep; const char* b2 = last ? nB : cB + (size_t)(t + 2) * kstep;
;             const char* a3 = a2 + kstep; const char* b3 = b2 + kstep;
;             if (last && has_next) S.a_ready(nxt);
;             if constexpr (SP2) {
;             PG8_LDB(B0, 0, 0); PG8_LDB(B1, 0, 1); PG8_SCHED; PG8_LDA(At, 0, 0); PG8_STAGE(PG8_SA(1, 1), a1 + hstep, voffA);
;             PG8_WAIT_V(8); PG8_WAIT_L(0); PG8_BAR; PG8_MMA(0, 0, At, B0); PG8_MMA(0, 1, At, B1); PG8_BAR; PG8_SCHED;
;             PG8_LDA(At, 0, 1); PG8_STAGE(PG8_SB(0, 0), b2, voffB); PG8_STAGE(PG8_SB(0, 1), b2 + hstep, voffB); PG8_STAGE(PG8_SA(0, 0), a2, voffA);
;             PG8_WAIT_V(8); PG8_WAIT_L(0); PG8_BAR; PG8_MMA(1, 0, At, B0); PG8_MMA(1, 1, At, B1); PG8_BAR; PG8_SCHED;
.LBB0_932:
	ds_read_b128 v[144:147], v153
	ds_read_b128 v[156:159], v153 offset:1024
	ds_read_b128 v[160:163], v153 offset:2048
	ds_read_b128 v[164:167], v153 offset:3072
	ds_read_b128 v[168:171], v154
	ds_read_b128 v[172:175], v154 offset:1024
	ds_read_b128 v[176:179], v154 offset:2048
	ds_read_b128 v[180:183], v154 offset:3072
	s_add_u32 s26, s24, 0xfff50080
	s_addc_u32 s27, s25, -1
	s_cmp_eq_u32 s60, 40
	s_cselect_b32 s29, s3, s27
	s_cselect_b32 s28, s2, s26
	s_cselect_b32 s27, s23, s59
	s_cselect_b32 s26, s22, s58
	v_lshl_add_u64 v[148:149], s[24:25], 0, v[136:137]
	s_add_i32 m0, s35, 0xc000
	ds_read_b128 v[184:187], v155
	ds_read_b128 v[188:191], v155 offset:1024
	ds_read_b128 v[192:195], v155 offset:2048
	ds_read_b128 v[200:203], v155 offset:3072
	ds_read_b128 v[204:207], v155 offset:4096
	ds_read_b128 v[208:211], v155 offset:5120
	ds_read_b128 v[212:215], v155 offset:6144
	ds_read_b128 v[216:219], v155 offset:7168
	global_load_lds_dwordx4 v[148:149], off
	v_lshl_add_u64 v[148:149], s[24:25], 0, v[138:139]
	s_add_i32 m0, s35, 0xe000
	s_nop 0
	global_load_lds_dwordx4 v[148:149], off
	s_sleep 1
	s_waitcnt vmcnt(8)
	s_waitcnt lgkmcnt(0)
	s_barrier
	s_setprio 1
	s_waitcnt lgkmcnt(0)
	v_mfma_f32_16x16x32_bf16 v[124:127], v[144:147], v[184:187], v[124:127]
	v_mfma_f32_16x16x32_bf16 v[120:123], v[160:163], v[184:187], v[120:123]
	v_mfma_f32_16x16x32_bf16 v[116:119], v[144:147], v[192:195], v[116:119]
	v_mfma_f32_16x16x32_bf16 v[112:115], v[160:163], v[192:195], v[112:115]
	v_mfma_f32_16x16x32_bf16 v[92:95], v[144:147], v[204:207], v[92:95]
	v_mfma_f32_16x16x32_bf16 v[88:91], v[160:163], v[204:207], v[88:91]
	v_mfma_f32_16x16x32_bf16 v[84:87], v[144:147], v[212:215], v[84:87]
	v_mfma_f32_16x16x32_bf16 v[80:83], v[160:163], v[212:215], v[80:83]
	v_mfma_f32_16x16x32_bf16 v[124:127], v[156:159], v[188:191], v[124:127]
	v_mfma_f32_16x16x32_bf16 v[120:123], v[164:167], v[188:191], v[120:123]
	v_mfma_f32_16x16x32_bf16 v[116:119], v[156:159], v[200:203], v[116:119]
	v_mfma_f32_16x16x32_bf16 v[112:115], v[164:167], v[200:203], v[112:115]
	v_mfma_f32_16x16x32_bf16 v[92:95], v[156:159], v[208:211], v[92:95]
	v_mfma_f32_16x16x32_bf16 v[88:91], v[164:167], v[208:211], v[88:91]
	v_mfma_f32_16x16x32_bf16 v[84:87], v[156:159], v[216:219], v[84:87]
	v_mfma_f32_16x16x32_bf16 v[80:83], v[164:167], v[216:219], v[80:83]
	s_setprio 0
	s_setprio 1
	v_mfma_f32_16x16x32_bf16 v[108:111], v[168:171], v[184:187], v[108:111]
	v_mfma_f32_16x16x32_bf16 v[104:107], v[176:179], v[184:187], v[104:107]
	v_mfma_f32_16x16x32_bf16 v[100:103], v[168:171], v[192:195], v[100:103]
	v_mfma_f32_16x16x32_bf16 v[96:99], v[176:179], v[192:195], v[96:99]
	v_mfma_f32_16x16x32_bf16 v[76:79], v[168:171], v[204:207], v[76:79]
	v_mfma_f32_16x16x32_bf16 v[72:75], v[176:179], v[204:207], v[72:75]
	v_mfma_f32_16x16x32_bf16 v[68:71], v[168:171], v[212:215], v[68:71]
	v_mfma_f32_16x16x32_bf16 v[64:67], v[176:179], v[212:215], v[64:67]
	v_mfma_f32_16x16x32_bf16 v[108:111], v[172:175], v[188:191], v[108:111]
	v_mfma_f32_16x16x32_bf16 v[104:107], v[180:183], v[188:191], v[104:107]
	v_mfma_f32_16x16x32_bf16 v[100:103], v[172:175], v[200:203], v[100:103]
	v_mfma_f32_16x16x32_bf16 v[96:99], v[180:183], v[200:203], v[96:99]
	v_mfma_f32_16x16x32_bf16 v[76:79], v[172:175], v[208:211], v[76:79]
	v_mfma_f32_16x16x32_bf16 v[72:75], v[180:183], v[208:211], v[72:75]
	v_mfma_f32_16x16x32_bf16 v[68:71], v[172:175], v[216:219], v[68:71]
	v_mfma_f32_16x16x32_bf16 v[64:67], v[180:183], v[216:219], v[64:67]
	s_setprio 0
	s_barrier
	s_add_i32 s61, s52, s30
	v_lshl_add_u64 v[148:149], s[26:27], 0, v[132:133]
	s_mov_b32 m0, s61
	ds_read_b128 v[184:187], v155 offset:16384
	ds_read_b128 v[188:191], v155 offset:17408
	ds_read_b128 v[192:195], v155 offset:18432
	ds_read_b128 v[200:203], v155 offset:19456
	ds_read_b128 v[204:207], v155 offset:20480
	ds_read_b128 v[208:211], v155 offset:21504
	ds_read_b128 v[212:215], v155 offset:22528
	ds_read_b128 v[216:219], v155 offset:23552
	global_load_lds_dwordx4 v[148:149], off
	s_add_i32 m0, s61, 0x2000
	s_add_u32 s62, s26, 0xb0000
	v_lshl_add_u64 v[196:197], s[26:27], 0, v[128:129]
	s_addc_u32 s63, s27, 0
	s_add_i32 s61, s53, s30
	global_load_lds_dwordx4 v[196:197], off
	v_lshl_add_u64 v[220:221], s[62:63], 0, v[132:133]
	s_mov_b32 m0, s61
	v_lshl_add_u64 v[222:223], s[28:29], 0, v[130:131]
	global_load_lds_dwordx4 v[220:221], off
	v_lshl_add_u64 v[220:221], s[62:63], 0, v[128:129]
	s_add_i32 m0, s61, 0x2000
	s_nop 0
	global_load_lds_dwordx4 v[220:221], off
	v_lshl_add_u64 v[220:221], s[28:29], 0, v[134:135]
	s_mov_b32 m0, s35
	s_nop 0
	global_load_lds_dwordx4 v[220:221], off
	s_mov_b32 m0, s36
	s_nop 0
	global_load_lds_dwordx4 v[222:223], off
	s_sleep 1
	s_waitcnt vmcnt(8)
	s_waitcnt lgkmcnt(0)
	s_barrier
; #define PG8_STAGE(bufoff, gbase, voff) do { _Pragma("unroll") for (int _i = 0; _i < 2; ++_i) \
;         __builtin_amdgcn_global_load_lds((const unsigned*)((const char*)(gbase) + (voff)[_i]), (PG8_LAS unsigned*)(lds + (bufoff) + ldsw + _i * 8192), 16, 0, 0); } while (0)
; #define PG8_LDA(dst, b, h) do { _Pragma("unroll") for (int m = 0; m < 4; ++m) _Pragma("unroll") for (int k = 0; k < 2; ++k) dst[m][k] = *(const PG8_LAS bf16x8*)(lds + PG8_SA(b, h) + aoff + m * 2048 + k * 1024); } while (0)
; #define PG8_LDB(dst, b, h) do { _Pragma("unroll") for (int n = 0; n < 2; ++n) _Pragma("unroll") for (int k = 0; k < 2; ++k) dst[n][k] = *(const PG8_LAS bf16x8*)(lds + PG8_SB(b, h) + boff + n * 2048 + k * 1024); } while (0)
; #define PG8_MMA(ai, bj, At, Bt) do { __builtin_amdgcn_s_setprio(1); _Pragma("unroll") for (int m = 0; m < 4; ++m) _Pragma("unroll") for (int n = 0; n < 2; ++n) _Pragma("unroll") for (int k = 0; k < 2; ++k) \
;         acc[ai][bj][m][n] = __builtin_amdgcn_mfma_f32_16x16x32_bf16(Bt[n][k], At[m][k], acc[ai][bj][m][n], 0, 0, 0); __builtin_amdgcn_s_setprio(0); } while (0)
; #define PG8_WAIT_V(n) asm volatile("s_waitcnt vmcnt(" #n ")" ::: "memory")
; #define PG8_WAIT_L(n) asm volatile("s_waitcnt lgkmcnt(" #n ")" ::: "memory")
; #define PG8_BAR __builtin_amdgcn_s_barrier()
; #define PG8_SCHED __builtin_amdgcn_sched_barrier(0)
; template <class Epi, class Sched, bool ALIGN_EPI = false, bool SP2 = false>
; __device__ __forceinline__ void gemm_phase(PG8_LAS unsigned char* lds, const Gemm g, const Sched& S, const Epi& E) {
;     ...
;             PG8_WAIT_V(8); PG8_WAIT_L(0); PG8_BAR; PG8_MMA(1, 0, At, B0); PG8_MMA(1, 1, At, B1); PG8_BAR; PG8_SCHED;
;             PG8_LDB(B0, 1, 0); PG8_LDB(B1, 1, 1); PG8_SCHED; PG8_LDA(At, 1, 0); PG8_STAGE(PG8_SA(0, 1), a2 + hstep, voffA);
;             PG8_WAIT_V(8); PG8_WAIT_L(0); PG8_BAR; PG8_MMA(0, 0, At, B0); PG8_MMA(0, 1, At, B1); PG8_BAR; PG8_SCHED;
	s_setprio 1
	s_waitcnt lgkmcnt(0)
	v_mfma_f32_16x16x32_bf16 v[60:63], v[144:147], v[184:187], v[60:63]
	v_mfma_f32_16x16x32_bf16 v[56:59], v[160:163], v[184:187], v[56:59]
	v_mfma_f32_16x16x32_bf16 v[52:55], v[144:147], v[192:195], v[52:55]
	v_mfma_f32_16x16x32_bf16 v[48:51], v[160:163], v[192:195], v[48:51]
	v_mfma_f32_16x16x32_bf16 v[28:31], v[144:147], v[204:207], v[28:31]
	v_mfma_f32_16x16x32_bf16 v[24:27], v[160:163], v[204:207], v[24:27]
	v_mfma_f32_16x16x32_bf16 v[20:23], v[144:147], v[212:215], v[20:23]
	v_mfma_f32_16x16x32_bf16 v[16:19], v[160:163], v[212:215], v[16:19]
	v_mfma_f32_16x16x32_bf16 v[60:63], v[156:159], v[188:191], v[60:63]
	v_mfma_f32_16x16x32_bf16 v[56:59], v[164:167], v[188:191], v[56:59]
	v_mfma_f32_16x16x32_bf16 v[52:55], v[156:159], v[200:203], v[52:55]
	v_mfma_f32_16x16x32_bf16 v[48:51], v[164:167], v[200:203], v[48:51]
	v_mfma_f32_16x16x32_bf16 v[28:31], v[156:159], v[208:211], v[28:31]
	v_mfma_f32_16x16x32_bf16 v[24:27], v[164:167], v[208:211], v[24:27]
	v_mfma_f32_16x16x32_bf16 v[20:23], v[156:159], v[216:219], v[20:23]
	v_mfma_f32_16x16x32_bf16 v[16:19], v[164:167], v[216:219], v[16:19]
	s_setprio 0
	s_setprio 1
	v_mfma_f32_16x16x32_bf16 v[44:47], v[168:171], v[184:187], v[44:47]
	v_mfma_f32_16x16x32_bf16 v[40:43], v[176:179], v[184:187], v[40:43]
	v_mfma_f32_16x16x32_bf16 v[36:39], v[168:171], v[192:195], v[36:39]
	v_mfma_f32_16x16x32_bf16 v[32:35], v[176:179], v[192:195], v[32:35]
	v_mfma_f32_16x16x32_bf16 v[12:15], v[168:171], v[204:207], v[12:15]
	v_mfma_f32_16x16x32_bf16 v[8:11], v[176:179], v[204:207], v[8:11]
	v_mfma_f32_16x16x32_bf16 v[4:7], v[168:171], v[212:215], v[4:7]
	v_mfma_f32_16x16x32_bf16 v[0:3], v[176:179], v[212:215], v[0:3]
	v_mfma_f32_16x16x32_bf16 v[44:47], v[172:175], v[188:191], v[44:47]
	v_mfma_f32_16x16x32_bf16 v[40:43], v[180:183], v[188:191], v[40:43]
	v_mfma_f32_16x16x32_bf16 v[36:39], v[172:175], v[200:203], v[36:39]
	v_mfma_f32_16x16x32_bf16 v[32:35], v[180:183], v[200:203], v[32:35]
	v_mfma_f32_16x16x32_bf16 v[12:15], v[172:175], v[208:211], v[12:15]
	v_mfma_f32_16x16x32_bf16 v[8:11], v[180:183], v[208:211], v[8:11]
	v_mfma_f32_16x16x32_bf16 v[4:7], v[172:175], v[216:219], v[4:7]
	v_mfma_f32_16x16x32_bf16 v[0:3], v[180:183], v[216:219], v[0:3]
	s_setprio 0
	s_barrier
	s_add_i32 s61, 0, 0x18000
	s_add_i32 s62, 0, 0x1c000
	v_add_u32_e32 v164, s61, v151
	v_add_u32_e32 v180, s62, v151
	ds_read_b128 v[144:147], v164
	ds_read_b128 v[156:159], v164 offset:1024
	ds_read_b128 v[160:163], v164 offset:2048
	ds_read_b128 v[164:167], v164 offset:3072
	ds_read_b128 v[168:171], v180
	ds_read_b128 v[172:175], v180 offset:1024
	ds_read_b128 v[176:179], v180 offset:2048
	ds_read_b128 v[180:183], v180 offset:3072
	s_add_u32 s28, s28, 0xb0000
	s_addc_u32 s29, s29, 0
	s_mov_b32 m0, s37
	v_lshl_add_u64 v[224:225], s[28:29], 0, v[134:135]
	ds_read_b128 v[184:187], v155 offset:32768
	ds_read_b128 v[188:191], v155 offset:33792
	ds_read_b128 v[192:195], v155 offset:34816
	ds_read_b128 v[200:203], v155 offset:35840
	ds_read_b128 v[204:207], v155 offset:36864
	ds_read_b128 v[208:211], v155 offset:37888
	ds_read_b128 v[212:215], v155 offset:38912
	ds_read_b128 v[216:219], v155 offset:39936
	global_load_lds_dwordx4 v[224:225], off
	v_lshl_add_u64 v[224:225], s[28:29], 0, v[130:131]
	s_mov_b32 m0, s40
	s_nop 0
	global_load_lds_dwordx4 v[224:225], off
	s_sleep 1
	s_waitcnt vmcnt(8)
	s_waitcnt lgkmcnt(0)
	s_barrier
	s_setprio 1
	s_waitcnt lgkmcnt(0)
	v_mfma_f32_16x16x32_bf16 v[124:127], v[144:147], v[184:187], v[124:127]
	v_mfma_f32_16x16x32_bf16 v[120:123], v[160:163], v[184:187], v[120:123]
	v_mfma_f32_16x16x32_bf16 v[116:119], v[144:147], v[192:195], v[116:119]
	v_mfma_f32_16x16x32_bf16 v[112:115], v[160:163], v[192:195], v[112:115]
	v_mfma_f32_16x16x32_bf16 v[92:95], v[144:147], v[204:207], v[92:95]
	v_mfma_f32_16x16x32_bf16 v[88:91], v[160:163], v[204:207], v[88:91]
	v_mfma_f32_16x16x32_bf16 v[84:87], v[144:147], v[212:215], v[84:87]
	v_mfma_f32_16x16x32_bf16 v[80:83], v[160:163], v[212:215], v[80:83]
	v_mfma_f32_16x16x32_bf16 v[124:127], v[156:159], v[188:191], v[124:127]
	v_mfma_f32_16x16x32_bf16 v[120:123], v[164:167], v[188:191], v[120:123]
	v_mfma_f32_16x16x32_bf16 v[116:119], v[156:159], v[200:203], v[116:119]
	v_mfma_f32_16x16x32_bf16 v[112:115], v[164:167], v[200:203], v[112:115]
	v_mfma_f32_16x16x32_bf16 v[92:95], v[156:159], v[208:211], v[92:95]
	v_mfma_f32_16x16x32_bf16 v[88:91], v[164:167], v[208:211], v[88:91]
	v_mfma_f32_16x16x32_bf16 v[84:87], v[156:159], v[216:219], v[84:87]
	v_mfma_f32_16x16x32_bf16 v[80:83], v[164:167], v[216:219], v[80:83]
	s_setprio 0
	s_setprio 1
	v_mfma_f32_16x16x32_bf16 v[108:111], v[168:171], v[184:187], v[108:111]
	v_mfma_f32_16x16x32_bf16 v[104:107], v[176:179], v[184:187], v[104:107]
	v_mfma_f32_16x16x32_bf16 v[100:103], v[168:171], v[192:195], v[100:103]
	v_mfma_f32_16x16x32_bf16 v[96:99], v[176:179], v[192:195], v[96:99]
	v_mfma_f32_16x16x32_bf16 v[76:79], v[168:171], v[204:207], v[76:79]
	v_mfma_f32_16x16x32_bf16 v[72:75], v[176:179], v[204:207], v[72:75]
	v_mfma_f32_16x16x32_bf16 v[68:71], v[168:171], v[212:215], v[68:71]
	v_mfma_f32_16x16x32_bf16 v[64:67], v[176:179], v[212:215], v[64:67]
	v_mfma_f32_16x16x32_bf16 v[108:111], v[172:175], v[188:191], v[108:111]
	v_mfma_f32_16x16x32_bf16 v[104:107], v[180:183], v[188:191], v[104:107]
	v_mfma_f32_16x16x32_bf16 v[100:103], v[172:175], v[200:203], v[100:103]
	v_mfma_f32_16x16x32_bf16 v[96:99], v[180:183], v[200:203], v[96:99]
	v_mfma_f32_16x16x32_bf16 v[76:79], v[172:175], v[208:211], v[76:79]
	v_mfma_f32_16x16x32_bf16 v[72:75], v[180:183], v[208:211], v[72:75]
	v_mfma_f32_16x16x32_bf16 v[68:71], v[172:175], v[216:219], v[68:71]
	v_mfma_f32_16x16x32_bf16 v[64:67], v[180:183], v[216:219], v[64:67]
	s_setprio 0
	s_barrier
; #define PG8_STAGE(bufoff, gbase, voff) do { _Pragma("unroll") for (int _i = 0; _i < 2; ++_i) \
;         __builtin_amdgcn_global_load_lds((const unsigned*)((const char*)(gbase) + (voff)[_i]), (PG8_LAS unsigned*)(lds + (bufoff) + ldsw + _i * 8192), 16, 0, 0); } while (0)
; #define PG8_LDA(dst, b, h) do { _Pragma("unroll") for (int m = 0; m < 4; ++m) _Pragma("unroll") for (int k = 0; k < 2; ++k) dst[m][k] = *(const PG8_LAS bf16x8*)(lds + PG8_SA(b, h) + aoff + m * 2048 + k * 1024); } while (0)
; #define PG8_MMA(ai, bj, At, Bt) do { __builtin_amdgcn_s_setprio(1); _Pragma("unroll") for (int m = 0; m < 4; ++m) _Pragma("unroll") for (int n = 0; n < 2; ++n) _Pragma("unroll") for (int k = 0; k < 2; ++k) \
;         acc[ai][bj][m][n] = __builtin_amdgcn_mfma_f32_16x16x32_bf16(Bt[n][k], At[m][k], acc[ai][bj][m][n], 0, 0, 0); __builtin_amdgcn_s_setprio(0); } while (0)
; #define PG8_WAIT_V(n) asm volatile("s_waitcnt vmcnt(" #n ")" ::: "memory")
; #define PG8_WAIT_L(n) asm volatile("s_waitcnt lgkmcnt(" #n ")" ::: "memory")
; #define PG8_BAR __builtin_amdgcn_s_barrier()
; #define PG8_SCHED __builtin_amdgcn_sched_barrier(0)
; template <class Epi, class Sched, bool ALIGN_EPI = false, bool SP2 = false>
; __device__ __forceinline__ void gemm_phase(PG8_LAS unsigned char* lds, const Gemm g, const Sched& S, const Epi& E) {
;     ...
;         for (int t = 0; t < nt; t += 2) {
;     ...
;             PG8_LDA(At, 1, 1); PG8_STAGE(PG8_SB(1, 0), b3, voffB); PG8_STAGE(PG8_SB(1, 1), b3 + hstep, voffB); PG8_STAGE(PG8_SA(1, 0), a3, voffA);
;             PG8_WAIT_V(8); PG8_WAIT_L(0); PG8_BAR; PG8_MMA(1, 0, At, B0); PG8_MMA(1, 1, At, B1); PG8_BAR; PG8_SCHED;
;     ...
;         if constexpr (ALIGN_EPI) { if (wr == 0) PG8_BAR; }
	s_add_i32 s28, s61, s30
	v_lshl_add_u64 v[148:149], v[148:149], 0, s[6:7]
	s_mov_b32 m0, s28
	ds_read_b128 v[184:187], v155 offset:49152
	ds_read_b128 v[188:191], v155 offset:50176
	ds_read_b128 v[192:195], v155 offset:51200
	ds_read_b128 v[200:203], v155 offset:52224
	ds_read_b128 v[204:207], v155 offset:53248
	ds_read_b128 v[208:211], v155 offset:54272
	ds_read_b128 v[212:215], v155 offset:55296
	ds_read_b128 v[216:219], v155 offset:56320
	global_load_lds_dwordx4 v[148:149], off
	s_add_i32 m0, s28, 0x2000
	s_add_u32 s26, s26, 0xb0080
	v_lshl_add_u64 v[148:149], v[196:197], 0, s[6:7]
	s_addc_u32 s27, s27, 0
	s_add_i32 s28, s62, s30
	global_load_lds_dwordx4 v[148:149], off
	v_lshl_add_u64 v[148:149], s[26:27], 0, v[132:133]
	s_mov_b32 m0, s28
	s_nop 0
	global_load_lds_dwordx4 v[148:149], off
	v_lshl_add_u64 v[148:149], s[26:27], 0, v[128:129]
	s_add_i32 m0, s28, 0x2000
	s_nop 0
	global_load_lds_dwordx4 v[148:149], off
	v_lshl_add_u64 v[148:149], v[220:221], 0, s[6:7]
	s_mov_b32 m0, s42
	s_nop 0
	global_load_lds_dwordx4 v[148:149], off
	v_lshl_add_u64 v[148:149], v[222:223], 0, s[6:7]
	s_mov_b32 m0, s43
	s_nop 0
	global_load_lds_dwordx4 v[148:149], off
	s_sleep 1
	s_waitcnt vmcnt(8)
	s_waitcnt lgkmcnt(0)
	s_barrier
	s_setprio 1
	s_waitcnt lgkmcnt(0)
	v_mfma_f32_16x16x32_bf16 v[60:63], v[144:147], v[184:187], v[60:63]
	v_mfma_f32_16x16x32_bf16 v[56:59], v[160:163], v[184:187], v[56:59]
	v_mfma_f32_16x16x32_bf16 v[52:55], v[144:147], v[192:195], v[52:55]
	v_mfma_f32_16x16x32_bf16 v[48:51], v[160:163], v[192:195], v[48:51]
	v_mfma_f32_16x16x32_bf16 v[28:31], v[144:147], v[204:207], v[28:31]
	v_mfma_f32_16x16x32_bf16 v[24:27], v[160:163], v[204:207], v[24:27]
	v_mfma_f32_16x16x32_bf16 v[20:23], v[144:147], v[212:215], v[20:23]
	v_mfma_f32_16x16x32_bf16 v[16:19], v[160:163], v[212:215], v[16:19]
	v_mfma_f32_16x16x32_bf16 v[60:63], v[156:159], v[188:191], v[60:63]
	v_mfma_f32_16x16x32_bf16 v[56:59], v[164:167], v[188:191], v[56:59]
	v_mfma_f32_16x16x32_bf16 v[52:55], v[156:159], v[200:203], v[52:55]
	v_mfma_f32_16x16x32_bf16 v[48:51], v[164:167], v[200:203], v[48:51]
	v_mfma_f32_16x16x32_bf16 v[28:31], v[156:159], v[208:211], v[28:31]
	v_mfma_f32_16x16x32_bf16 v[24:27], v[164:167], v[208:211], v[24:27]
	v_mfma_f32_16x16x32_bf16 v[20:23], v[156:159], v[216:219], v[20:23]
	v_mfma_f32_16x16x32_bf16 v[16:19], v[164:167], v[216:219], v[16:19]
	s_setprio 0
	s_setprio 1
	v_mfma_f32_16x16x32_bf16 v[44:47], v[168:171], v[184:187], v[44:47]
	v_mfma_f32_16x16x32_bf16 v[40:43], v[176:179], v[184:187], v[40:43]
	v_mfma_f32_16x16x32_bf16 v[36:39], v[168:171], v[192:195], v[36:39]
	v_mfma_f32_16x16x32_bf16 v[32:35], v[176:179], v[192:195], v[32:35]
	v_mfma_f32_16x16x32_bf16 v[12:15], v[168:171], v[204:207], v[12:15]
	v_mfma_f32_16x16x32_bf16 v[8:11], v[176:179], v[204:207], v[8:11]
	v_mfma_f32_16x16x32_bf16 v[4:7], v[168:171], v[212:215], v[4:7]
	v_mfma_f32_16x16x32_bf16 v[0:3], v[176:179], v[212:215], v[0:3]
	v_mfma_f32_16x16x32_bf16 v[44:47], v[172:175], v[188:191], v[44:47]
	v_mfma_f32_16x16x32_bf16 v[40:43], v[180:183], v[188:191], v[40:43]
	v_mfma_f32_16x16x32_bf16 v[36:39], v[172:175], v[200:203], v[36:39]
	v_mfma_f32_16x16x32_bf16 v[32:35], v[180:183], v[200:203], v[32:35]
	v_mfma_f32_16x16x32_bf16 v[12:15], v[172:175], v[208:211], v[12:15]
	v_mfma_f32_16x16x32_bf16 v[8:11], v[180:183], v[208:211], v[8:11]
	v_mfma_f32_16x16x32_bf16 v[4:7], v[172:175], v[216:219], v[4:7]
	v_mfma_f32_16x16x32_bf16 v[0:3], v[180:183], v[216:219], v[0:3]
	s_setprio 0
	s_barrier
	s_add_i32 s60, s60, 2
	s_add_u32 s24, s24, 0x100
	s_addc_u32 s25, s25, 0
	s_add_u32 s58, s58, 0x100
	s_addc_u32 s59, s59, 0
	s_cmp_gt_u32 s60, 41
	s_cbranch_scc0 .LBB0_932
	s_and_b64 vcc, exec, s[20:21]
	s_cbranch_vccz .LBB0_935
	s_barrier

; #define PG8_STAGE(bufoff, gbase, voff) do { _Pragma("unroll") for (int _i = 0; _i < 2; ++_i) \
;         __builtin_amdgcn_global_load_lds((const unsigned*)((const char*)(gbase) + (voff)[_i]), (PG8_LAS unsigned*)(lds + (bufoff) + ldsw + _i * 8192), 16, 0, 0); } while (0)
; #define PG8_LDA(dst, b, h) do { _Pragma("unroll") for (int m = 0; m < 4; ++m) _Pragma("unroll") for (int k = 0; k < 2; ++k) dst[m][k] = *(const PG8_LAS bf16x8*)(lds + PG8_SA(b, h) + aoff + m * 2048 + k * 1024); } while (0)
; #define PG8_LDB(dst, b, h) do { _Pragma("unroll") for (int n = 0; n < 2; ++n) _Pragma("unroll") for (int k = 0; k < 2; ++k) dst[n][k] = *(const PG8_LAS bf16x8*)(lds + PG8_SB(b, h) + boff + n * 2048 + k * 1024); } while (0)
; #define PG8_MMA(ai, bj, At, Bt) do { __builtin_amdgcn_s_setprio(1); _Pragma("unroll") for (int m = 0; m < 4; ++m) _Pragma("unroll") for (int n = 0; n < 2; ++n) _Pragma("unroll") for (int k = 0; k < 2; ++k) \
;         acc[ai][bj][m][n] = __builtin_amdgcn_mfma_f32_16x16x32_bf16(Bt[n][k], At[m][k], acc[ai][bj][m][n], 0, 0, 0); __builtin_amdgcn_s_setprio(0); } while (0)
; #define PG8_WAIT_V(n) asm volatile("s_waitcnt vmcnt(" #n ")" ::: "memory")
; #define PG8_BAR __builtin_amdgcn_s_barrier()
; template <class Epi, class Sched, bool ALIGN_EPI = false, bool SP2 = false>
; __device__ __forceinline__ void gemm_phase(PG8_LAS unsigned char* lds, const Gemm g, const Sched& S, const Epi& E) {
;     ...
;         for (int t = 0; t < nt; t += 2) {
;             const bool last = (t == nt - 2);
;             const char* a1 = cA + (size_t)(t + 1) * kstep;
;             const char* a2 = last ? nA : cA + (size_t)(t + 2) * kstep; const char* b2 = last ? nB : cB + (size_t)(t + 2) * kstep;
;             const char* a3 = a2 + kstep; const char* b3 = b2 + kstep;
;             if (last && has_next) S.a_ready(nxt);
;             if constexpr (SP2) {
;             PG8_LDB(B0, 0, 0); PG8_LDB(B1, 0, 1); PG8_SCHED; PG8_LDA(At, 0, 0); PG8_STAGE(PG8_SA(1, 1), a1 + hstep, voffA);
;             PG8_WAIT_V(8); PG8_WAIT_L(0); PG8_BAR; PG8_MMA(0, 0, At, B0); PG8_MMA(0, 1, At, B1); PG8_BAR; PG8_SCHED;
;             PG8_LDA(At, 0, 1); PG8_STAGE(PG8_SB(0, 0), b2, voffB); PG8_STAGE(PG8_SB(0, 1), b2 + hstep, voffB); PG8_STAGE(PG8_SA(0, 0), a2, voffA);
;             PG8_WAIT_V(8); PG8_WAIT_L(0); PG8_BAR; PG8_MMA(1, 0, At, B0); PG8_MMA(1, 1, At, B1); PG8_BAR; PG8_SCHED;
.LBB0_956:
	ds_read_b128 v[146:149], v200
	ds_read_b128 v[150:153], v200 offset:1024
	ds_read_b128 v[154:157], v200 offset:2048
	ds_read_b128 v[158:161], v200 offset:3072
	ds_read_b128 v[162:165], v201
	ds_read_b128 v[166:169], v201 offset:1024
	ds_read_b128 v[170:173], v201 offset:2048
	ds_read_b128 v[174:177], v201 offset:3072
	s_add_u32 s34, s30, 0xfff50080
	s_addc_u32 s35, s31, -1
	s_cmp_eq_u32 s66, 40
	s_cselect_b32 s37, s7, s35
	s_cselect_b32 s36, s6, s34
	s_cselect_b32 s35, s29, s65
	s_cselect_b32 s34, s28, s64
	v_lshl_add_u64 v[194:195], s[30:31], 0, v[138:139]
	s_add_i32 m0, s41, 0xc000
	ds_read_b128 v[178:181], v202
	ds_read_b128 v[182:185], v202 offset:1024
	ds_read_b128 v[186:189], v202 offset:2048
	ds_read_b128 v[190:193], v202 offset:3072
	ds_read_b128 v[206:209], v202 offset:4096
	ds_read_b128 v[210:213], v202 offset:5120
	ds_read_b128 v[214:217], v202 offset:6144
	ds_read_b128 v[218:221], v202 offset:7168
	global_load_lds_dwordx4 v[194:195], off
	v_lshl_add_u64 v[194:195], s[30:31], 0, v[140:141]
	s_add_i32 m0, s41, 0xe000
	s_nop 0
	global_load_lds_dwordx4 v[194:195], off
	s_sleep 1
	s_waitcnt vmcnt(8)
	s_waitcnt lgkmcnt(0)
	s_barrier
	s_setprio 1
	s_waitcnt lgkmcnt(0)
	v_mfma_f32_16x16x32_bf16 v[124:127], v[146:149], v[178:181], v[124:127]
	v_mfma_f32_16x16x32_bf16 v[120:123], v[154:157], v[178:181], v[120:123]
	v_mfma_f32_16x16x32_bf16 v[108:111], v[146:149], v[186:189], v[108:111]
	v_mfma_f32_16x16x32_bf16 v[104:107], v[154:157], v[186:189], v[104:107]
	v_mfma_f32_16x16x32_bf16 v[92:95], v[146:149], v[206:209], v[92:95]
	v_mfma_f32_16x16x32_bf16 v[88:91], v[154:157], v[206:209], v[88:91]
	v_mfma_f32_16x16x32_bf16 v[76:79], v[146:149], v[214:217], v[76:79]
	v_mfma_f32_16x16x32_bf16 v[72:75], v[154:157], v[214:217], v[72:75]
	v_mfma_f32_16x16x32_bf16 v[124:127], v[150:153], v[182:185], v[124:127]
	v_mfma_f32_16x16x32_bf16 v[120:123], v[158:161], v[182:185], v[120:123]
	v_mfma_f32_16x16x32_bf16 v[108:111], v[150:153], v[190:193], v[108:111]
	v_mfma_f32_16x16x32_bf16 v[104:107], v[158:161], v[190:193], v[104:107]
	v_mfma_f32_16x16x32_bf16 v[92:95], v[150:153], v[210:213], v[92:95]
	v_mfma_f32_16x16x32_bf16 v[88:91], v[158:161], v[210:213], v[88:91]
	v_mfma_f32_16x16x32_bf16 v[76:79], v[150:153], v[218:221], v[76:79]
	v_mfma_f32_16x16x32_bf16 v[72:75], v[158:161], v[218:221], v[72:75]
	s_setprio 0
	s_setprio 1
	v_mfma_f32_16x16x32_bf16 v[116:119], v[162:165], v[178:181], v[116:119]
	v_mfma_f32_16x16x32_bf16 v[112:115], v[170:173], v[178:181], v[112:115]
	v_mfma_f32_16x16x32_bf16 v[100:103], v[162:165], v[186:189], v[100:103]
	v_mfma_f32_16x16x32_bf16 v[96:99], v[170:173], v[186:189], v[96:99]
	v_mfma_f32_16x16x32_bf16 v[84:87], v[162:165], v[206:209], v[84:87]
	v_mfma_f32_16x16x32_bf16 v[80:83], v[170:173], v[206:209], v[80:83]
	v_mfma_f32_16x16x32_bf16 v[68:71], v[162:165], v[214:217], v[68:71]
	v_mfma_f32_16x16x32_bf16 v[64:67], v[170:173], v[214:217], v[64:67]
	v_mfma_f32_16x16x32_bf16 v[116:119], v[166:169], v[182:185], v[116:119]
	v_mfma_f32_16x16x32_bf16 v[112:115], v[174:177], v[182:185], v[112:115]
	v_mfma_f32_16x16x32_bf16 v[100:103], v[166:169], v[190:193], v[100:103]
	v_mfma_f32_16x16x32_bf16 v[96:99], v[174:177], v[190:193], v[96:99]
	v_mfma_f32_16x16x32_bf16 v[84:87], v[166:169], v[210:213], v[84:87]
	v_mfma_f32_16x16x32_bf16 v[80:83], v[174:177], v[210:213], v[80:83]
	v_mfma_f32_16x16x32_bf16 v[68:71], v[166:169], v[218:221], v[68:71]
	v_mfma_f32_16x16x32_bf16 v[64:67], v[174:177], v[218:221], v[64:67]
	s_setprio 0
	s_barrier
	s_add_i32 s67, s58, s40
	v_lshl_add_u64 v[194:195], s[34:35], 0, v[130:131]
	s_mov_b32 m0, s67
	ds_read_b128 v[178:181], v202 offset:16384
	ds_read_b128 v[182:185], v202 offset:17408
	ds_read_b128 v[186:189], v202 offset:18432
	ds_read_b128 v[190:193], v202 offset:19456
	ds_read_b128 v[206:209], v202 offset:20480
	ds_read_b128 v[210:213], v202 offset:21504
	ds_read_b128 v[214:217], v202 offset:22528
	ds_read_b128 v[218:221], v202 offset:23552
	global_load_lds_dwordx4 v[194:195], off
	s_add_i32 m0, s67, 0x2000
	s_add_u32 s68, s34, 0xb0000
	v_lshl_add_u64 v[222:223], s[34:35], 0, v[134:135]
	s_addc_u32 s69, s35, 0
	s_add_i32 s67, s59, s40
	global_load_lds_dwordx4 v[222:223], off
	v_lshl_add_u64 v[224:225], s[68:69], 0, v[130:131]
	s_mov_b32 m0, s67
	v_lshl_add_u64 v[226:227], s[36:37], 0, v[132:133]
	global_load_lds_dwordx4 v[224:225], off
	v_lshl_add_u64 v[224:225], s[68:69], 0, v[134:135]
	s_add_i32 m0, s67, 0x2000
	s_nop 0
	global_load_lds_dwordx4 v[224:225], off
	v_lshl_add_u64 v[224:225], s[36:37], 0, v[128:129]
	s_mov_b32 m0, s41
	s_nop 0
	global_load_lds_dwordx4 v[224:225], off
	s_mov_b32 m0, s42
	s_nop 0
	global_load_lds_dwordx4 v[226:227], off
	s_sleep 1
	s_waitcnt vmcnt(8)
	s_waitcnt lgkmcnt(0)
	s_barrier
; #define PG8_STAGE(bufoff, gbase, voff) do { _Pragma("unroll") for (int _i = 0; _i < 2; ++_i) \
;         __builtin_amdgcn_global_load_lds((const unsigned*)((const char*)(gbase) + (voff)[_i]), (PG8_LAS unsigned*)(lds + (bufoff) + ldsw + _i * 8192), 16, 0, 0); } while (0)
; #define PG8_LDA(dst, b, h) do { _Pragma("unroll") for (int m = 0; m < 4; ++m) _Pragma("unroll") for (int k = 0; k < 2; ++k) dst[m][k] = *(const PG8_LAS bf16x8*)(lds + PG8_SA(b, h) + aoff + m * 2048 + k * 1024); } while (0)
; #define PG8_LDB(dst, b, h) do { _Pragma("unroll") for (int n = 0; n < 2; ++n) _Pragma("unroll") for (int k = 0; k < 2; ++k) dst[n][k] = *(const PG8_LAS bf16x8*)(lds + PG8_SB(b, h) + boff + n * 2048 + k * 1024); } while (0)
; #define PG8_MMA(ai, bj, At, Bt) do { __builtin_amdgcn_s_setprio(1); _Pragma("unroll") for (int m = 0; m < 4; ++m) _Pragma("unroll") for (int n = 0; n < 2; ++n) _Pragma("unroll") for (int k = 0; k < 2; ++k) \
;         acc[ai][bj][m][n] = __builtin_amdgcn_mfma_f32_16x16x32_bf16(Bt[n][k], At[m][k], acc[ai][bj][m][n], 0, 0, 0); __builtin_amdgcn_s_setprio(0); } while (0)
; #define PG8_WAIT_V(n) asm volatile("s_waitcnt vmcnt(" #n ")" ::: "memory")
; #define PG8_WAIT_L(n) asm volatile("s_waitcnt lgkmcnt(" #n ")" ::: "memory")
; #define PG8_BAR __builtin_amdgcn_s_barrier()
; #define PG8_SCHED __builtin_amdgcn_sched_barrier(0)
; template <class Epi, class Sched, bool ALIGN_EPI = false, bool SP2 = false>
; __device__ __forceinline__ void gemm_phase(PG8_LAS unsigned char* lds, const Gemm g, const Sched& S, const Epi& E) {
;     ...
;             PG8_WAIT_V(8); PG8_WAIT_L(0); PG8_BAR; PG8_MMA(1, 0, At, B0); PG8_MMA(1, 1, At, B1); PG8_BAR; PG8_SCHED;
;             PG8_LDB(B0, 1, 0); PG8_LDB(B1, 1, 1); PG8_SCHED; PG8_LDA(At, 1, 0); PG8_STAGE(PG8_SA(0, 1), a2 + hstep, voffA);
;             PG8_WAIT_V(8); PG8_WAIT_L(0); PG8_BAR; PG8_MMA(0, 0, At, B0); PG8_MMA(0, 1, At, B1); PG8_BAR; PG8_SCHED;
	s_setprio 1
	s_waitcnt lgkmcnt(0)
	v_mfma_f32_16x16x32_bf16 v[60:63], v[146:149], v[178:181], v[60:63]
	v_mfma_f32_16x16x32_bf16 v[56:59], v[154:157], v[178:181], v[56:59]
	v_mfma_f32_16x16x32_bf16 v[44:47], v[146:149], v[186:189], v[44:47]
	v_mfma_f32_16x16x32_bf16 v[40:43], v[154:157], v[186:189], v[40:43]
	v_mfma_f32_16x16x32_bf16 v[28:31], v[146:149], v[206:209], v[28:31]
	v_mfma_f32_16x16x32_bf16 v[24:27], v[154:157], v[206:209], v[24:27]
	v_mfma_f32_16x16x32_bf16 v[12:15], v[146:149], v[214:217], v[12:15]
	v_mfma_f32_16x16x32_bf16 v[8:11], v[154:157], v[214:217], v[8:11]
	v_mfma_f32_16x16x32_bf16 v[60:63], v[150:153], v[182:185], v[60:63]
	v_mfma_f32_16x16x32_bf16 v[56:59], v[158:161], v[182:185], v[56:59]
	v_mfma_f32_16x16x32_bf16 v[44:47], v[150:153], v[190:193], v[44:47]
	v_mfma_f32_16x16x32_bf16 v[40:43], v[158:161], v[190:193], v[40:43]
	v_mfma_f32_16x16x32_bf16 v[28:31], v[150:153], v[210:213], v[28:31]
	v_mfma_f32_16x16x32_bf16 v[24:27], v[158:161], v[210:213], v[24:27]
	v_mfma_f32_16x16x32_bf16 v[12:15], v[150:153], v[218:221], v[12:15]
	v_mfma_f32_16x16x32_bf16 v[8:11], v[158:161], v[218:221], v[8:11]
	s_setprio 0
	s_setprio 1
	v_mfma_f32_16x16x32_bf16 v[52:55], v[162:165], v[178:181], v[52:55]
	v_mfma_f32_16x16x32_bf16 v[48:51], v[170:173], v[178:181], v[48:51]
	v_mfma_f32_16x16x32_bf16 v[36:39], v[162:165], v[186:189], v[36:39]
	v_mfma_f32_16x16x32_bf16 v[32:35], v[170:173], v[186:189], v[32:35]
	v_mfma_f32_16x16x32_bf16 v[20:23], v[162:165], v[206:209], v[20:23]
	v_mfma_f32_16x16x32_bf16 v[16:19], v[170:173], v[206:209], v[16:19]
	v_mfma_f32_16x16x32_bf16 v[4:7], v[162:165], v[214:217], v[4:7]
	v_mfma_f32_16x16x32_bf16 v[0:3], v[170:173], v[214:217], v[0:3]
	v_mfma_f32_16x16x32_bf16 v[52:55], v[166:169], v[182:185], v[52:55]
	v_mfma_f32_16x16x32_bf16 v[48:51], v[174:177], v[182:185], v[48:51]
	v_mfma_f32_16x16x32_bf16 v[36:39], v[166:169], v[190:193], v[36:39]
	v_mfma_f32_16x16x32_bf16 v[32:35], v[174:177], v[190:193], v[32:35]
	v_mfma_f32_16x16x32_bf16 v[20:23], v[166:169], v[210:213], v[20:23]
	v_mfma_f32_16x16x32_bf16 v[16:19], v[174:177], v[210:213], v[16:19]
	v_mfma_f32_16x16x32_bf16 v[4:7], v[166:169], v[218:221], v[4:7]
	v_mfma_f32_16x16x32_bf16 v[0:3], v[174:177], v[218:221], v[0:3]
	s_setprio 0
	s_barrier
	s_add_i32 s67, 0, 0x18000
	s_add_i32 s68, 0, 0x1c000
	v_add_u32_e32 v158, s67, v197
	v_add_u32_e32 v174, s68, v197
	ds_read_b128 v[146:149], v158
	ds_read_b128 v[150:153], v158 offset:1024
	ds_read_b128 v[154:157], v158 offset:2048
	ds_read_b128 v[158:161], v158 offset:3072
	ds_read_b128 v[162:165], v174
	ds_read_b128 v[166:169], v174 offset:1024
	ds_read_b128 v[170:173], v174 offset:2048
	ds_read_b128 v[174:177], v174 offset:3072
	s_add_u32 s36, s36, 0xb0000
	s_addc_u32 s37, s37, 0
	s_mov_b32 m0, s43
	v_lshl_add_u64 v[228:229], s[36:37], 0, v[128:129]
	ds_read_b128 v[178:181], v202 offset:32768
	ds_read_b128 v[182:185], v202 offset:33792
	ds_read_b128 v[186:189], v202 offset:34816
	ds_read_b128 v[190:193], v202 offset:35840
	ds_read_b128 v[206:209], v202 offset:36864
	ds_read_b128 v[210:213], v202 offset:37888
	ds_read_b128 v[214:217], v202 offset:38912
	ds_read_b128 v[218:221], v202 offset:39936
	global_load_lds_dwordx4 v[228:229], off
	v_lshl_add_u64 v[228:229], s[36:37], 0, v[132:133]
	s_mov_b32 m0, s50
	s_nop 0
	global_load_lds_dwordx4 v[228:229], off
	s_sleep 1
	s_waitcnt vmcnt(8)
	s_waitcnt lgkmcnt(0)
	s_barrier
	s_setprio 1
	s_waitcnt lgkmcnt(0)
	v_mfma_f32_16x16x32_bf16 v[124:127], v[146:149], v[178:181], v[124:127]
	v_mfma_f32_16x16x32_bf16 v[120:123], v[154:157], v[178:181], v[120:123]
	v_mfma_f32_16x16x32_bf16 v[108:111], v[146:149], v[186:189], v[108:111]
	v_mfma_f32_16x16x32_bf16 v[104:107], v[154:157], v[186:189], v[104:107]
	v_mfma_f32_16x16x32_bf16 v[92:95], v[146:149], v[206:209], v[92:95]
	v_mfma_f32_16x16x32_bf16 v[88:91], v[154:157], v[206:209], v[88:91]
	v_mfma_f32_16x16x32_bf16 v[76:79], v[146:149], v[214:217], v[76:79]
	v_mfma_f32_16x16x32_bf16 v[72:75], v[154:157], v[214:217], v[72:75]
	v_mfma_f32_16x16x32_bf16 v[124:127], v[150:153], v[182:185], v[124:127]
	v_mfma_f32_16x16x32_bf16 v[120:123], v[158:161], v[182:185], v[120:123]
	v_mfma_f32_16x16x32_bf16 v[108:111], v[150:153], v[190:193], v[108:111]
	v_mfma_f32_16x16x32_bf16 v[104:107], v[158:161], v[190:193], v[104:107]
	v_mfma_f32_16x16x32_bf16 v[92:95], v[150:153], v[210:213], v[92:95]
	v_mfma_f32_16x16x32_bf16 v[88:91], v[158:161], v[210:213], v[88:91]
	v_mfma_f32_16x16x32_bf16 v[76:79], v[150:153], v[218:221], v[76:79]
	v_mfma_f32_16x16x32_bf16 v[72:75], v[158:161], v[218:221], v[72:75]
	s_setprio 0
	s_setprio 1
	v_mfma_f32_16x16x32_bf16 v[116:119], v[162:165], v[178:181], v[116:119]
	v_mfma_f32_16x16x32_bf16 v[112:115], v[170:173], v[178:181], v[112:115]
	v_mfma_f32_16x16x32_bf16 v[100:103], v[162:165], v[186:189], v[100:103]
	v_mfma_f32_16x16x32_bf16 v[96:99], v[170:173], v[186:189], v[96:99]
	v_mfma_f32_16x16x32_bf16 v[84:87], v[162:165], v[206:209], v[84:87]
	v_mfma_f32_16x16x32_bf16 v[80:83], v[170:173], v[206:209], v[80:83]
	v_mfma_f32_16x16x32_bf16 v[68:71], v[162:165], v[214:217], v[68:71]
	v_mfma_f32_16x16x32_bf16 v[64:67], v[170:173], v[214:217], v[64:67]
	v_mfma_f32_16x16x32_bf16 v[116:119], v[166:169], v[182:185], v[116:119]
	v_mfma_f32_16x16x32_bf16 v[112:115], v[174:177], v[182:185], v[112:115]
	v_mfma_f32_16x16x32_bf16 v[100:103], v[166:169], v[190:193], v[100:103]
	v_mfma_f32_16x16x32_bf16 v[96:99], v[174:177], v[190:193], v[96:99]
	v_mfma_f32_16x16x32_bf16 v[84:87], v[166:169], v[210:213], v[84:87]
	v_mfma_f32_16x16x32_bf16 v[80:83], v[174:177], v[210:213], v[80:83]
	v_mfma_f32_16x16x32_bf16 v[68:71], v[166:169], v[218:221], v[68:71]
	v_mfma_f32_16x16x32_bf16 v[64:67], v[174:177], v[218:221], v[64:67]
	s_setprio 0
	s_barrier
; #define PG8_STAGE(bufoff, gbase, voff) do { _Pragma("unroll") for (int _i = 0; _i < 2; ++_i) \
;         __builtin_amdgcn_global_load_lds((const unsigned*)((const char*)(gbase) + (voff)[_i]), (PG8_LAS unsigned*)(lds + (bufoff) + ldsw + _i * 8192), 16, 0, 0); } while (0)
; #define PG8_LDA(dst, b, h) do { _Pragma("unroll") for (int m = 0; m < 4; ++m) _Pragma("unroll") for (int k = 0; k < 2; ++k) dst[m][k] = *(const PG8_LAS bf16x8*)(lds + PG8_SA(b, h) + aoff + m * 2048 + k * 1024); } while (0)
; #define PG8_MMA(ai, bj, At, Bt) do { __builtin_amdgcn_s_setprio(1); _Pragma("unroll") for (int m = 0; m < 4; ++m) _Pragma("unroll") for (int n = 0; n < 2; ++n) _Pragma("unroll") for (int k = 0; k < 2; ++k) \
;         acc[ai][bj][m][n] = __builtin_amdgcn_mfma_f32_16x16x32_bf16(Bt[n][k], At[m][k], acc[ai][bj][m][n], 0, 0, 0); __builtin_amdgcn_s_setprio(0); } while (0)
; #define PG8_WAIT_V(n) asm volatile("s_waitcnt vmcnt(" #n ")" ::: "memory")
; #define PG8_WAIT_L(n) asm volatile("s_waitcnt lgkmcnt(" #n ")" ::: "memory")
; #define PG8_BAR __builtin_amdgcn_s_barrier()
; #define PG8_SCHED __builtin_amdgcn_sched_barrier(0)
; template <class Epi, class Sched, bool ALIGN_EPI = false, bool SP2 = false>
; __device__ __forceinline__ void gemm_phase(PG8_LAS unsigned char* lds, const Gemm g, const Sched& S, const Epi& E) {
;     ...
;         for (int t = 0; t < nt; t += 2) {
;     ...
;             PG8_LDA(At, 1, 1); PG8_STAGE(PG8_SB(1, 0), b3, voffB); PG8_STAGE(PG8_SB(1, 1), b3 + hstep, voffB); PG8_STAGE(PG8_SA(1, 0), a3, voffA);
;             PG8_WAIT_V(8); PG8_WAIT_L(0); PG8_BAR; PG8_MMA(1, 0, At, B0); PG8_MMA(1, 1, At, B1); PG8_BAR; PG8_SCHED;
;     ...
;         if constexpr (ALIGN_EPI) { if (wr == 0) PG8_BAR; }
	s_add_i32 s36, s67, s40
	v_lshl_add_u64 v[194:195], v[194:195], 0, s[10:11]
	s_mov_b32 m0, s36
	ds_read_b128 v[178:181], v202 offset:49152
	ds_read_b128 v[182:185], v202 offset:50176
	ds_read_b128 v[186:189], v202 offset:51200
	ds_read_b128 v[190:193], v202 offset:52224
	ds_read_b128 v[206:209], v202 offset:53248
	ds_read_b128 v[210:213], v202 offset:54272
	ds_read_b128 v[214:217], v202 offset:55296
	ds_read_b128 v[218:221], v202 offset:56320
	global_load_lds_dwordx4 v[194:195], off
	s_add_i32 m0, s36, 0x2000
	s_add_u32 s34, s34, 0xb0080
	v_lshl_add_u64 v[194:195], v[222:223], 0, s[10:11]
	s_addc_u32 s35, s35, 0
	s_add_i32 s36, s68, s40
	global_load_lds_dwordx4 v[194:195], off
	v_lshl_add_u64 v[194:195], s[34:35], 0, v[130:131]
	s_mov_b32 m0, s36
	s_nop 0
	global_load_lds_dwordx4 v[194:195], off
	v_lshl_add_u64 v[194:195], s[34:35], 0, v[134:135]
	s_add_i32 m0, s36, 0x2000
	s_nop 0
	global_load_lds_dwordx4 v[194:195], off
	v_lshl_add_u64 v[194:195], v[224:225], 0, s[10:11]
	s_mov_b32 m0, s54
	s_nop 0
	global_load_lds_dwordx4 v[194:195], off
	v_lshl_add_u64 v[194:195], v[226:227], 0, s[10:11]
	s_mov_b32 m0, s55
	s_nop 0
	global_load_lds_dwordx4 v[194:195], off
	s_sleep 1
	s_waitcnt vmcnt(8)
	s_waitcnt lgkmcnt(0)
	s_barrier
	s_setprio 1
	s_waitcnt lgkmcnt(0)
	v_mfma_f32_16x16x32_bf16 v[60:63], v[146:149], v[178:181], v[60:63]
	v_mfma_f32_16x16x32_bf16 v[56:59], v[154:157], v[178:181], v[56:59]
	v_mfma_f32_16x16x32_bf16 v[44:47], v[146:149], v[186:189], v[44:47]
	v_mfma_f32_16x16x32_bf16 v[40:43], v[154:157], v[186:189], v[40:43]
	v_mfma_f32_16x16x32_bf16 v[28:31], v[146:149], v[206:209], v[28:31]
	v_mfma_f32_16x16x32_bf16 v[24:27], v[154:157], v[206:209], v[24:27]
	v_mfma_f32_16x16x32_bf16 v[12:15], v[146:149], v[214:217], v[12:15]
	v_mfma_f32_16x16x32_bf16 v[8:11], v[154:157], v[214:217], v[8:11]
	v_mfma_f32_16x16x32_bf16 v[60:63], v[150:153], v[182:185], v[60:63]
	v_mfma_f32_16x16x32_bf16 v[56:59], v[158:161], v[182:185], v[56:59]
	v_mfma_f32_16x16x32_bf16 v[44:47], v[150:153], v[190:193], v[44:47]
	v_mfma_f32_16x16x32_bf16 v[40:43], v[158:161], v[190:193], v[40:43]
	v_mfma_f32_16x16x32_bf16 v[28:31], v[150:153], v[210:213], v[28:31]
	v_mfma_f32_16x16x32_bf16 v[24:27], v[158:161], v[210:213], v[24:27]
	v_mfma_f32_16x16x32_bf16 v[12:15], v[150:153], v[218:221], v[12:15]
	v_mfma_f32_16x16x32_bf16 v[8:11], v[158:161], v[218:221], v[8:11]
	s_setprio 0
	s_setprio 1
	v_mfma_f32_16x16x32_bf16 v[52:55], v[162:165], v[178:181], v[52:55]
	v_mfma_f32_16x16x32_bf16 v[48:51], v[170:173], v[178:181], v[48:51]
	v_mfma_f32_16x16x32_bf16 v[36:39], v[162:165], v[186:189], v[36:39]
	v_mfma_f32_16x16x32_bf16 v[32:35], v[170:173], v[186:189], v[32:35]
	v_mfma_f32_16x16x32_bf16 v[20:23], v[162:165], v[206:209], v[20:23]
	v_mfma_f32_16x16x32_bf16 v[16:19], v[170:173], v[206:209], v[16:19]
	v_mfma_f32_16x16x32_bf16 v[4:7], v[162:165], v[214:217], v[4:7]
	v_mfma_f32_16x16x32_bf16 v[0:3], v[170:173], v[214:217], v[0:3]
	v_mfma_f32_16x16x32_bf16 v[52:55], v[166:169], v[182:185], v[52:55]
	v_mfma_f32_16x16x32_bf16 v[48:51], v[174:177], v[182:185], v[48:51]
	v_mfma_f32_16x16x32_bf16 v[36:39], v[166:169], v[190:193], v[36:39]
	v_mfma_f32_16x16x32_bf16 v[32:35], v[174:177], v[190:193], v[32:35]
	v_mfma_f32_16x16x32_bf16 v[20:23], v[166:169], v[210:213], v[20:23]
	v_mfma_f32_16x16x32_bf16 v[16:19], v[174:177], v[210:213], v[16:19]
	v_mfma_f32_16x16x32_bf16 v[4:7], v[166:169], v[218:221], v[4:7]
	v_mfma_f32_16x16x32_bf16 v[0:3], v[174:177], v[218:221], v[0:3]
	s_setprio 0
	s_barrier
	s_add_i32 s66, s66, 2
	s_add_u32 s30, s30, 0x100
	s_addc_u32 s31, s31, 0
	s_add_u32 s64, s64, 0x100
	s_addc_u32 s65, s65, 0
	s_cmp_gt_u32 s66, 41
	s_cbranch_scc0 .LBB0_956
	s_and_b64 vcc, exec, s[26:27]
	s_cbranch_vccz .LBB0_959
	s_barrier
